# pipelined LDS fragment reads in all four 192x128 GEMM K-loops and the ffn_in K-loop, on top of v11
# baseline (speedup 1.0000x reference)
.LBB0_267:
	s_add_i32 s4, s1, 2
	s_cmp_lt_u32 s1, 14
	s_cselect_b64 s[6:7], -1, 0
	s_and_b64 vcc, s[6:7], exec
	s_cselect_b32 s2, s0, 0x3c0
	s_lshl_b64 s[6:7], s[2:3], 1
	ds_read_b128 v[138:141], v134
	ds_read_b128 v[146:149], v135 offset:18432
	ds_read_b128 v[142:145], v134 offset:4608
	ds_read_b128 v[150:153], v135 offset:23040
	ds_read_b128 v[154:157], v134 offset:32
	ds_read_b128 v[162:165], v135 offset:18464
	ds_read_b128 v[158:161], v134 offset:4640
	ds_read_b128 v[166:169], v135 offset:23072
	v_lshl_add_u64 v[170:171], v[130:131], 0, s[6:7]
	v_lshl_add_u64 v[172:173], v[132:133], 0, s[6:7]
	global_load_dwordx4 v[98:101], v[170:171], off
	global_load_dwordx4 v[102:105], v[172:173], off
	v_lshl_add_u64 v[174:175], v[170:171], 0, s[40:41]
	global_load_dwordx4 v[106:109], v[174:175], off
	v_lshl_add_u64 v[174:175], v[172:173], 0, s[40:41]
	global_load_dwordx4 v[110:113], v[174:175], off
	v_lshl_add_u64 v[174:175], v[170:171], 0, s[18:19]
	global_load_dwordx4 v[114:117], v[174:175], off
	v_lshl_add_u64 v[174:175], v[172:173], 0, s[18:19]
	global_load_dwordx4 v[118:121], v[174:175], off
	v_lshl_add_u64 v[174:175], v[170:171], 0, s[92:93]
	global_load_dwordx4 v[122:125], v[174:175], off
	v_lshl_add_u64 v[174:175], v[172:173], 0, s[92:93]
	global_load_dwordx4 v[126:129], v[174:175], off
	s_waitcnt lgkmcnt(4)
	v_mfma_f32_32x32x16_bf16 v[48:63], v[138:141], v[146:149], v[48:63]
	v_mfma_f32_32x32x16_bf16 v[32:47], v[138:141], v[150:153], v[32:47]
	v_mfma_f32_32x32x16_bf16 v[16:31], v[142:145], v[146:149], v[16:31]
	v_mfma_f32_32x32x16_bf16 v[0:15], v[142:145], v[150:153], v[0:15]
	ds_read_b128 v[138:141], v134 offset:64
	ds_read_b128 v[146:149], v135 offset:18496
	ds_read_b128 v[142:145], v134 offset:4672
	ds_read_b128 v[150:153], v135 offset:23104
	s_waitcnt lgkmcnt(4)
	v_mfma_f32_32x32x16_bf16 v[48:63], v[154:157], v[162:165], v[48:63]
	v_mfma_f32_32x32x16_bf16 v[32:47], v[154:157], v[166:169], v[32:47]
	v_mfma_f32_32x32x16_bf16 v[16:31], v[158:161], v[162:165], v[16:31]
	v_mfma_f32_32x32x16_bf16 v[0:15], v[158:161], v[166:169], v[0:15]
	ds_read_b128 v[154:157], v134 offset:96
	ds_read_b128 v[162:165], v135 offset:18528
	ds_read_b128 v[158:161], v134 offset:4704
	ds_read_b128 v[166:169], v135 offset:23136
	s_waitcnt lgkmcnt(4)
	v_mfma_f32_32x32x16_bf16 v[48:63], v[138:141], v[146:149], v[48:63]
	s_waitcnt vmcnt(8)
	ds_write_b128 v97, v[64:67] offset:36864
	ds_write_b128 v97, v[68:71] offset:55296
	v_mfma_f32_32x32x16_bf16 v[32:47], v[138:141], v[150:153], v[32:47]
	ds_write_b128 v97, v[72:75] offset:41472
	ds_write_b128 v97, v[76:79] offset:59904
	v_mfma_f32_32x32x16_bf16 v[16:31], v[142:145], v[146:149], v[16:31]
	ds_write_b128 v97, v[80:83] offset:46080
	ds_write_b128 v97, v[84:87] offset:64512
	v_mfma_f32_32x32x16_bf16 v[0:15], v[142:145], v[150:153], v[0:15]
	ds_write_b128 v97, v[88:91] offset:50688
	ds_write_b128 v136, v[92:95] offset:55296
	s_waitcnt lgkmcnt(8)
	v_mfma_f32_32x32x16_bf16 v[48:63], v[154:157], v[162:165], v[48:63]
	v_mfma_f32_32x32x16_bf16 v[32:47], v[154:157], v[166:169], v[32:47]
	v_mfma_f32_32x32x16_bf16 v[16:31], v[158:161], v[162:165], v[16:31]
	v_mfma_f32_32x32x16_bf16 v[0:15], v[158:161], v[166:169], v[0:15]
	s_waitcnt lgkmcnt(0)
	s_barrier
	s_min_u32 s2, s1, 12
	s_lshl_b32 s2, s2, 7
	s_addk_i32 s0, 0x80
	s_mov_b32 s1, s4
	ds_read_b128 v[138:141], v134 offset:36864
	ds_read_b128 v[146:149], v135 offset:55296
	ds_read_b128 v[142:145], v134 offset:41472
	ds_read_b128 v[150:153], v135 offset:59904
	ds_read_b128 v[154:157], v134 offset:36896
	ds_read_b128 v[162:165], v135 offset:55328
	ds_read_b128 v[158:161], v134 offset:41504
	ds_read_b128 v[166:169], v135 offset:59936
	v_lshl_add_u64 v[170:171], v[130:131], 0, s[2:3]
	v_lshl_add_u64 v[172:173], v[132:133], 0, s[2:3]
	v_lshl_add_u64 v[174:175], v[170:171], 0, s[22:23]
	global_load_dwordx4 v[64:67], v[174:175], off
	v_lshl_add_u64 v[174:175], v[172:173], 0, s[22:23]
	global_load_dwordx4 v[68:71], v[174:175], off
	v_lshl_add_u64 v[174:175], v[170:171], 0, s[76:77]
	global_load_dwordx4 v[72:75], v[174:175], off
	v_lshl_add_u64 v[174:175], v[172:173], 0, s[76:77]
	global_load_dwordx4 v[76:79], v[174:175], off
	v_lshl_add_u64 v[174:175], v[170:171], 0, s[26:27]
	global_load_dwordx4 v[80:83], v[174:175], off
	v_lshl_add_u64 v[174:175], v[172:173], 0, s[26:27]
	global_load_dwordx4 v[84:87], v[174:175], off
	v_lshl_add_u64 v[174:175], v[170:171], 0, s[70:71]
	global_load_dwordx4 v[88:91], v[174:175], off
	v_lshl_add_u64 v[174:175], v[172:173], 0, s[70:71]
	global_load_dwordx4 v[92:95], v[174:175], off
	s_waitcnt lgkmcnt(4)
	v_mfma_f32_32x32x16_bf16 v[48:63], v[138:141], v[146:149], v[48:63]
	v_mfma_f32_32x32x16_bf16 v[32:47], v[138:141], v[150:153], v[32:47]
	v_mfma_f32_32x32x16_bf16 v[16:31], v[142:145], v[146:149], v[16:31]
	v_mfma_f32_32x32x16_bf16 v[0:15], v[142:145], v[150:153], v[0:15]
	ds_read_b128 v[138:141], v134 offset:36928
	ds_read_b128 v[146:149], v135 offset:55360
	ds_read_b128 v[142:145], v134 offset:41536
	ds_read_b128 v[150:153], v135 offset:59968
	s_waitcnt lgkmcnt(4)
	v_mfma_f32_32x32x16_bf16 v[48:63], v[154:157], v[162:165], v[48:63]
	v_mfma_f32_32x32x16_bf16 v[32:47], v[154:157], v[166:169], v[32:47]
	v_mfma_f32_32x32x16_bf16 v[16:31], v[158:161], v[162:165], v[16:31]
	v_mfma_f32_32x32x16_bf16 v[0:15], v[158:161], v[166:169], v[0:15]
	ds_read_b128 v[154:157], v134 offset:36960
	ds_read_b128 v[162:165], v135 offset:55392
	ds_read_b128 v[158:161], v134 offset:41568
	ds_read_b128 v[166:169], v135 offset:60000
	s_waitcnt lgkmcnt(4)
	v_mfma_f32_32x32x16_bf16 v[48:63], v[138:141], v[146:149], v[48:63]
	s_waitcnt vmcnt(8)
	ds_write_b128 v97, v[98:101]
	ds_write_b128 v97, v[102:105] offset:18432
	v_mfma_f32_32x32x16_bf16 v[32:47], v[138:141], v[150:153], v[32:47]
	ds_write_b128 v97, v[106:109] offset:4608
	ds_write_b128 v97, v[110:113] offset:23040
	v_mfma_f32_32x32x16_bf16 v[16:31], v[142:145], v[146:149], v[16:31]
	ds_write_b128 v97, v[114:117] offset:9216
	ds_write_b128 v97, v[118:121] offset:27648
	v_mfma_f32_32x32x16_bf16 v[0:15], v[142:145], v[150:153], v[0:15]
	ds_write_b128 v97, v[122:125] offset:13824
	ds_write_b128 v97, v[126:129] offset:32256
	s_waitcnt lgkmcnt(8)
	v_mfma_f32_32x32x16_bf16 v[48:63], v[154:157], v[162:165], v[48:63]
	v_mfma_f32_32x32x16_bf16 v[32:47], v[154:157], v[166:169], v[32:47]
	v_mfma_f32_32x32x16_bf16 v[16:31], v[158:161], v[162:165], v[16:31]
	v_mfma_f32_32x32x16_bf16 v[0:15], v[158:161], v[166:169], v[0:15]
	s_waitcnt lgkmcnt(0)
	s_barrier
	s_cbranch_vccnz .LBB0_267
	s_cmp_gt_i32 s59, 7
	s_cselect_b64 s[50:51], -1, 0
	s_cmp_lt_i32 s59, 8
	s_cselect_b64 s[0:1], -1, 0
	s_sub_i32 s2, s59, 32
	s_cmp_lt_u32 s2, 40
	s_waitcnt vmcnt(0)
	s_cselect_b64 s[4:5], -1, 0
	s_or_b64 s[0:1], s[0:1], s[4:5]
	v_mov_b32_e32 v64, v244
	s_andn2_b64 vcc, exec, s[0:1]
	s_mov_b64 s[0:1], -1
	s_cbranch_vccz .LBB0_383
	v_ashrrev_i32_e32 v107, 7, v64
	v_bfe_u32 v108, v64, 6, 1
	v_and_b32_e32 v106, 31, v64
	v_bfe_u32 v97, v64, 5, 1
	s_cmp_gt_u32 s59, 15
	s_cbranch_scc0 .LBB0_373
	s_cmp_gt_u32 s59, 31
	s_cbranch_scc0 .LBB0_338
	v_cmp_eq_u32_e32 vcc, 0, v108
	v_cmp_gt_u32_e64 s[0:1], 16, v106
	s_and_b64 s[0:1], vcc, s[0:1]
	s_and_saveexec_b64 s[4:5], s[0:1]
	s_cbranch_execz .LBB0_337
	v_or_b32_e32 v66, s58, v106
	v_mov_b32_e32 v67, v96
	v_lshl_add_u64 v[66:67], v[66:67], 2, s[8:9]
	global_load_dword v68, v[66:67], off
	v_and_b32_e32 v64, 4, v64
	v_cmp_ne_u32_e32 vcc, 0, v64
	s_waitcnt vmcnt(0)
	v_add_f32_e32 v69, v48, v68
	s_and_saveexec_b64 s[6:7], vcc
	s_cbranch_execz .LBB0_274
	v_mul_f32_e64 v64, |v69|, s69
	v_exp_f32_e32 v80, v64
	v_max_f32_e32 v64, v69, v69
	v_min_f32_e32 v69, 0, v64
	s_mov_b32 s0, 0x3f2aaaab
	v_add_f32_e32 v66, 1.0, v80
	v_add_f32_e32 v64, -1.0, v66
	v_sub_f32_e32 v65, v64, v66
	v_sub_f32_e32 v64, v80, v64
	v_add_f32_e32 v65, 1.0, v65
	v_add_f32_e32 v67, v64, v65
	v_frexp_mant_f32_e32 v70, v66
	v_cvt_f64_f32_e32 v[64:65], v66
	v_frexp_exp_i32_f64_e32 v64, v[64:65]
	v_cmp_gt_f32_e64 s[0:1], s0, v70
	s_nop 1
	v_subbrev_co_u32_e64 v74, s[0:1], 0, v64, s[0:1]
	v_sub_u32_e32 v64, 0, v74
	v_ldexp_f32 v65, v66, v64
	v_add_f32_e32 v66, -1.0, v65
	v_add_f32_e32 v70, 1.0, v65
	v_ldexp_f32 v64, v67, v64
	v_add_f32_e32 v67, 1.0, v66
	v_add_f32_e32 v71, -1.0, v70
	v_sub_f32_e32 v67, v65, v67
	v_sub_f32_e32 v65, v65, v71
	v_add_f32_e32 v67, v64, v67
	v_add_f32_e32 v64, v64, v65
	v_add_f32_e32 v75, v70, v64
	v_rcp_f32_e32 v77, v75
	v_sub_f32_e32 v65, v75, v70
	v_sub_f32_e32 v76, v64, v65
	v_add_f32_e32 v65, v66, v67
	v_mul_f32_e32 v79, v65, v77
	v_sub_f32_e32 v64, v65, v66
	v_mul_f32_e32 v66, v75, v79
	v_fma_f32 v70, v79, v75, -v66
	v_fmac_f32_e32 v70, v79, v76
	v_sub_f32_e32 v78, v67, v64
	v_add_f32_e32 v64, v66, v70
	v_sub_f32_e32 v67, v65, v64
	v_pk_add_f32 v[72:73], v[64:65], v[66:67] neg_lo:[0,1] neg_hi:[0,1]
	v_mov_b32_e32 v71, v64
	v_pk_add_f32 v[64:65], v[72:73], v[70:71] neg_lo:[0,1] neg_hi:[0,1]
	s_mov_b32 s0, 0x3f317218
	v_add_f32_e32 v65, v78, v65
	v_add_f32_e32 v64, v64, v65
	v_add_f32_e32 v65, v67, v64
	v_mul_f32_e32 v78, v77, v65
	v_mul_f32_e32 v66, v75, v78
	v_fma_f32 v70, v78, v75, -v66
	v_fmac_f32_e32 v70, v78, v76
	v_sub_f32_e32 v67, v67, v65
	v_add_f32_e32 v75, v64, v67
	v_add_f32_e32 v64, v66, v70
	v_sub_f32_e32 v67, v65, v64
	v_pk_add_f32 v[72:73], v[64:65], v[66:67] neg_lo:[0,1] neg_hi:[0,1]
	v_mov_b32_e32 v71, v64
	v_pk_add_f32 v[64:65], v[72:73], v[70:71] neg_lo:[0,1] neg_hi:[0,1]
	s_nop 0
	v_add_f32_e32 v65, v75, v65
	v_add_f32_e32 v64, v64, v65
	v_add_f32_e32 v65, v79, v78
	v_add_f32_e32 v64, v67, v64
	v_sub_f32_e32 v66, v65, v79
	v_mul_f32_e32 v64, v77, v64
	v_sub_f32_e32 v66, v78, v66
	v_add_f32_e32 v66, v66, v64
	v_add_f32_e32 v70, v65, v66
	v_mul_f32_e32 v71, v70, v70
	v_fmamk_f32 v64, v71, 0x3e9b6dac, v253
	v_fmaak_f32 v179, v71, v64, 0x3f2aaada
	v_cvt_f32_i32_e32 v64, v74
	v_sub_f32_e32 v65, v70, v65
	v_sub_f32_e32 v65, v66, v65
	v_ldexp_f32 v72, v65, 1
	v_mul_f32_e32 v65, v70, v71
	v_ldexp_f32 v67, v70, 1
	v_pk_mul_f32 v[70:71], v[64:65], v[178:179]
	s_nop 0
	v_fma_f32 v66, v64, s0, -v70
	v_fmac_f32_e32 v66, 0xb102e308, v64
	v_pk_add_f32 v[64:65], v[70:71], v[66:67]
	s_mov_b32 s0, 0x7f800000
	v_sub_f32_e32 v67, v65, v67
	v_sub_f32_e32 v67, v71, v67
	v_add_f32_e32 v73, v72, v67
	v_mov_b32_e32 v72, v70
	v_pk_add_f32 v[70:71], v[64:65], v[70:71] neg_lo:[0,1] neg_hi:[0,1]
	v_pk_add_f32 v[74:75], v[64:65], v[72:73]
	v_mov_b32_e32 v67, v64
	v_mov_b32_e32 v71, v75
	v_pk_add_f32 v[76:77], v[66:67], v[70:71] neg_lo:[0,1] neg_hi:[0,1]
	v_pk_add_f32 v[66:67], v[66:67], v[70:71]
	v_mov_b32_e32 v72, v73
	v_pk_add_f32 v[70:71], v[66:67], v[64:65] op_sel:[1,0] op_sel_hi:[0,1] neg_lo:[0,1] neg_hi:[0,1]
	v_pk_add_f32 v[78:79], v[74:75], v[70:71] op_sel_hi:[1,0] neg_lo:[0,1] neg_hi:[0,1]
	v_mov_b32_e32 v74, v75
	v_mov_b32_e32 v75, v67
	v_pk_mov_b32 v[70:71], v[64:65], v[70:71] op_sel:[1,0]
	v_mov_b32_e32 v73, v64
	v_pk_add_f32 v[70:71], v[74:75], v[70:71] neg_lo:[0,1] neg_hi:[0,1]
	v_mov_b32_e32 v78, v76
	v_pk_add_f32 v[64:65], v[72:73], v[70:71] neg_lo:[0,1] neg_hi:[0,1]
	v_mov_b32_e32 v77, v67
	v_pk_add_f32 v[70:71], v[78:79], v[64:65]
	v_cmp_neq_f32_e64 s[0:1], s0, v80
	v_pk_add_f32 v[72:73], v[70:71], v[70:71] op_sel:[0,1] op_sel_hi:[1,0]
	s_nop 0
	v_pk_add_f32 v[66:67], v[66:67], v[72:73] op_sel:[1,0] op_sel_hi:[0,1]
	v_mov_b32_e32 v71, v66
	v_pk_add_f32 v[74:75], v[70:71], v[76:77] neg_lo:[0,1] neg_hi:[0,1]
	v_mov_b32_e32 v65, v72
	v_sub_f32_e32 v67, v70, v74
	v_pk_add_f32 v[64:65], v[64:65], v[74:75] neg_lo:[0,1] neg_hi:[0,1]
	v_sub_f32_e32 v67, v76, v67
	v_add_f32_e32 v64, v64, v67
	v_add_f32_e32 v64, v64, v65
	v_add_f32_e32 v64, v66, v64
	v_cndmask_b32_e64 v64, v243, v64, s[0:1]
	v_cmp_ngt_f32_e64 s[0:1], -1.0, v80
	s_nop 1
	v_cndmask_b32_e64 v64, v245, v64, s[0:1]
	v_cmp_neq_f32_e64 s[0:1], -1.0, v80
	s_nop 1
	v_cndmask_b32_e64 v64, v246, v64, s[0:1]
	s_mov_b32 s0, 0x33800000
	v_cmp_lt_f32_e64 s[0:1], |v80|, s0
	s_nop 1
	v_cndmask_b32_e64 v64, v64, v80, s[0:1]
	v_sub_f32_e32 v69, v69, v64

.LBB0_778:
	s_add_i32 s5, s6, 2
	s_cmp_lt_u32 s6, 30
	s_cselect_b64 s[10:11], -1, 0
	s_and_b64 vcc, s[10:11], exec
	s_cselect_b32 s2, s4, 0x7c0
	s_lshl_b64 s[10:11], s[2:3], 1
	v_lshl_add_u64 v[158:159], v[180:181], 0, s[10:11]
	global_load_dwordx4 v[138:141], v[158:159], off
	v_lshl_add_u64 v[146:147], v[158:159], 0, s[18:19]
	global_load_dwordx4 v[142:145], v[146:147], off
	v_lshl_add_u64 v[150:151], v[158:159], 0, s[62:63]
	global_load_dwordx4 v[146:149], v[150:151], off
	v_lshl_add_u64 v[154:155], v[158:159], 0, s[72:73]
	global_load_dwordx4 v[150:153], v[154:155], off
	v_lshl_add_u64 v[160:161], v[158:159], 0, s[52:53]
	global_load_dwordx4 v[154:157], v[160:161], off
	v_lshl_add_u64 v[162:163], v[158:159], 0, s[50:51]
	global_load_dwordx4 v[158:161], v[162:163], off
	v_lshl_add_u64 v[174:175], v[182:183], 0, s[10:11]
	global_load_dwordx4 v[162:165], v[174:175], off
	v_lshl_add_u64 v[170:171], v[174:175], 0, s[18:19]
	global_load_dwordx4 v[166:169], v[170:171], off
	v_lshl_add_u64 v[176:177], v[174:175], 0, s[62:63]
	global_load_dwordx4 v[170:173], v[176:177], off
	v_lshl_add_u64 v[186:187], v[174:175], 0, s[72:73]
	global_load_dwordx4 v[174:177], v[186:187], off
	s_min_u32 s2, s6, 28
	s_lshl_b32 s2, s2, 7
	s_mov_b64 s[6:7], 0x80180
	s_addk_i32 s4, 0x80
	ds_read_b128 v[186:189], v179
	ds_read_b128 v[190:193], v184 offset:27648
	ds_read_b128 v[194:197], v179 offset:4608
	ds_read_b128 v[198:201], v184 offset:32256
	ds_read_b128 v[202:205], v179 offset:9216
	ds_read_b128 v[206:209], v179 offset:32
	ds_read_b128 v[210:213], v184 offset:27680
	ds_read_b128 v[214:217], v179 offset:4640
	ds_read_b128 v[218:221], v184 offset:32288
	ds_read_b128 v[222:225], v179 offset:9248
	s_waitcnt lgkmcnt(5)
	v_mfma_f32_32x32x16_bf16 v[80:95], v[186:189], v[190:193], v[80:95]
	v_mfma_f32_32x32x16_bf16 v[64:79], v[186:189], v[198:201], v[64:79]
	v_mfma_f32_32x32x16_bf16 v[48:63], v[194:197], v[190:193], v[48:63]
	v_mfma_f32_32x32x16_bf16 v[32:47], v[194:197], v[198:201], v[32:47]
	v_mfma_f32_32x32x16_bf16 v[16:31], v[202:205], v[190:193], v[16:31]
	v_mfma_f32_32x32x16_bf16 v[0:15], v[202:205], v[198:201], v[0:15]
	ds_read_b128 v[186:189], v179 offset:64
	ds_read_b128 v[190:193], v184 offset:27712
	ds_read_b128 v[194:197], v179 offset:4672
	ds_read_b128 v[198:201], v184 offset:32320
	ds_read_b128 v[202:205], v179 offset:9280
	s_waitcnt lgkmcnt(5)
	v_mfma_f32_32x32x16_bf16 v[80:95], v[206:209], v[210:213], v[80:95]
	v_mfma_f32_32x32x16_bf16 v[64:79], v[206:209], v[218:221], v[64:79]
	v_mfma_f32_32x32x16_bf16 v[48:63], v[214:217], v[210:213], v[48:63]
	v_mfma_f32_32x32x16_bf16 v[32:47], v[214:217], v[218:221], v[32:47]
	v_mfma_f32_32x32x16_bf16 v[16:31], v[222:225], v[210:213], v[16:31]
	v_mfma_f32_32x32x16_bf16 v[0:15], v[222:225], v[218:221], v[0:15]
	ds_read_b128 v[206:209], v179 offset:96
	ds_read_b128 v[210:213], v184 offset:27744
	ds_read_b128 v[214:217], v179 offset:4704
	ds_read_b128 v[218:221], v184 offset:32352
	ds_read_b128 v[222:225], v179 offset:9312
	s_waitcnt lgkmcnt(0)
	s_waitcnt vmcnt(10)
	s_barrier
	v_mfma_f32_32x32x16_bf16 v[80:95], v[186:189], v[190:193], v[80:95]
	ds_write_b128 v97, v[98:101]
	ds_write_b128 v97, v[102:105] offset:4608
	v_mfma_f32_32x32x16_bf16 v[64:79], v[186:189], v[198:201], v[64:79]
	ds_write_b128 v97, v[106:109] offset:9216
	ds_write_b128 v97, v[110:113] offset:13824
	v_mfma_f32_32x32x16_bf16 v[48:63], v[194:197], v[190:193], v[48:63]
	ds_write_b128 v97, v[114:117] offset:18432
	ds_write_b128 v97, v[118:121] offset:23040
	v_mfma_f32_32x32x16_bf16 v[32:47], v[194:197], v[198:201], v[32:47]
	ds_write_b128 v97, v[122:125] offset:27648
	ds_write_b128 v97, v[126:129] offset:32256
	v_mfma_f32_32x32x16_bf16 v[16:31], v[202:205], v[190:193], v[16:31]
	ds_write_b128 v97, v[130:133] offset:36864
	ds_write_b128 v97, v[134:137] offset:41472
	v_mfma_f32_32x32x16_bf16 v[0:15], v[202:205], v[198:201], v[0:15]
	v_lshl_add_u64 v[118:119], v[180:181], 0, s[2:3]
	v_mfma_f32_32x32x16_bf16 v[80:95], v[206:209], v[210:213], v[80:95]
	v_mfma_f32_32x32x16_bf16 v[64:79], v[206:209], v[218:221], v[64:79]
	v_mfma_f32_32x32x16_bf16 v[48:63], v[214:217], v[210:213], v[48:63]
	v_mfma_f32_32x32x16_bf16 v[32:47], v[214:217], v[218:221], v[32:47]
	v_mfma_f32_32x32x16_bf16 v[16:31], v[222:225], v[210:213], v[16:31]
	v_mfma_f32_32x32x16_bf16 v[0:15], v[222:225], v[218:221], v[0:15]
	s_waitcnt lgkmcnt(0)
	s_barrier
	v_lshl_add_u64 v[102:103], v[118:119], 0, s[22:23]
	global_load_dwordx4 v[98:101], v[102:103], off
	v_lshl_add_u64 v[106:107], v[118:119], 0, s[26:27]
	global_load_dwordx4 v[102:105], v[106:107], off
	v_lshl_add_u64 v[110:111], v[118:119], 0, s[48:49]
	global_load_dwordx4 v[106:109], v[110:111], off
	v_lshl_add_u64 v[114:115], v[118:119], 0, s[12:13]
	global_load_dwordx4 v[110:113], v[114:115], off
	v_lshl_add_u64 v[120:121], v[118:119], 0, s[6:7]
	global_load_dwordx4 v[114:117], v[120:121], off
	s_mov_b64 s[6:7], 0xa0180
	v_lshl_add_u64 v[122:123], v[118:119], 0, s[6:7]
	global_load_dwordx4 v[118:121], v[122:123], off
	v_lshl_add_u64 v[134:135], v[182:183], 0, s[2:3]
	v_lshl_add_u64 v[126:127], v[134:135], 0, s[22:23]
	global_load_dwordx4 v[122:125], v[126:127], off
	v_lshl_add_u64 v[130:131], v[134:135], 0, s[26:27]
	global_load_dwordx4 v[126:129], v[130:131], off
	v_lshl_add_u64 v[136:137], v[134:135], 0, s[48:49]
	global_load_dwordx4 v[130:133], v[136:137], off
	s_mov_b32 s6, s5
	v_lshl_add_u64 v[186:187], v[134:135], 0, s[12:13]
	global_load_dwordx4 v[134:137], v[186:187], off
	ds_read_b128 v[186:189], v179
	ds_read_b128 v[190:193], v184 offset:27648
	ds_read_b128 v[194:197], v179 offset:4608
	ds_read_b128 v[198:201], v184 offset:32256
	ds_read_b128 v[202:205], v179 offset:9216
	ds_read_b128 v[206:209], v179 offset:32
	ds_read_b128 v[210:213], v184 offset:27680
	ds_read_b128 v[214:217], v179 offset:4640
	ds_read_b128 v[218:221], v184 offset:32288
	ds_read_b128 v[222:225], v179 offset:9248
	s_waitcnt lgkmcnt(5)
	v_mfma_f32_32x32x16_bf16 v[80:95], v[186:189], v[190:193], v[80:95]
	v_mfma_f32_32x32x16_bf16 v[64:79], v[186:189], v[198:201], v[64:79]
	v_mfma_f32_32x32x16_bf16 v[48:63], v[194:197], v[190:193], v[48:63]
	v_mfma_f32_32x32x16_bf16 v[32:47], v[194:197], v[198:201], v[32:47]
	v_mfma_f32_32x32x16_bf16 v[16:31], v[202:205], v[190:193], v[16:31]
	v_mfma_f32_32x32x16_bf16 v[0:15], v[202:205], v[198:201], v[0:15]
	ds_read_b128 v[186:189], v179 offset:64
	ds_read_b128 v[190:193], v184 offset:27712
	ds_read_b128 v[194:197], v179 offset:4672
	ds_read_b128 v[198:201], v184 offset:32320
	ds_read_b128 v[202:205], v179 offset:9280
	s_waitcnt lgkmcnt(5)
	v_mfma_f32_32x32x16_bf16 v[80:95], v[206:209], v[210:213], v[80:95]
	v_mfma_f32_32x32x16_bf16 v[64:79], v[206:209], v[218:221], v[64:79]
	v_mfma_f32_32x32x16_bf16 v[48:63], v[214:217], v[210:213], v[48:63]
	v_mfma_f32_32x32x16_bf16 v[32:47], v[214:217], v[218:221], v[32:47]
	v_mfma_f32_32x32x16_bf16 v[16:31], v[222:225], v[210:213], v[16:31]
	v_mfma_f32_32x32x16_bf16 v[0:15], v[222:225], v[218:221], v[0:15]
	ds_read_b128 v[206:209], v179 offset:96
	ds_read_b128 v[210:213], v184 offset:27744
	ds_read_b128 v[214:217], v179 offset:4704
	ds_read_b128 v[218:221], v184 offset:32352
	ds_read_b128 v[222:225], v179 offset:9312
	s_waitcnt lgkmcnt(0)
	s_waitcnt vmcnt(10)
	s_barrier
	v_mfma_f32_32x32x16_bf16 v[80:95], v[186:189], v[190:193], v[80:95]
	ds_write_b128 v97, v[138:141]
	ds_write_b128 v97, v[142:145] offset:4608
	v_mfma_f32_32x32x16_bf16 v[64:79], v[186:189], v[198:201], v[64:79]
	ds_write_b128 v97, v[146:149] offset:9216
	ds_write_b128 v97, v[150:153] offset:13824
	v_mfma_f32_32x32x16_bf16 v[48:63], v[194:197], v[190:193], v[48:63]
	ds_write_b128 v97, v[154:157] offset:18432
	ds_write_b128 v97, v[158:161] offset:23040
	v_mfma_f32_32x32x16_bf16 v[32:47], v[194:197], v[198:201], v[32:47]
	ds_write_b128 v97, v[162:165] offset:27648
	ds_write_b128 v97, v[166:169] offset:32256
	v_mfma_f32_32x32x16_bf16 v[16:31], v[202:205], v[190:193], v[16:31]
	ds_write_b128 v97, v[170:173] offset:36864
	ds_write_b128 v97, v[174:177] offset:41472
	v_mfma_f32_32x32x16_bf16 v[0:15], v[202:205], v[198:201], v[0:15]
	v_mfma_f32_32x32x16_bf16 v[80:95], v[206:209], v[210:213], v[80:95]
	v_mfma_f32_32x32x16_bf16 v[64:79], v[206:209], v[218:221], v[64:79]
	v_mfma_f32_32x32x16_bf16 v[48:63], v[214:217], v[210:213], v[48:63]
	v_mfma_f32_32x32x16_bf16 v[32:47], v[214:217], v[218:221], v[32:47]
	v_mfma_f32_32x32x16_bf16 v[16:31], v[222:225], v[210:213], v[16:31]
	v_mfma_f32_32x32x16_bf16 v[0:15], v[222:225], v[218:221], v[0:15]
	s_waitcnt lgkmcnt(0)
	s_barrier
	s_cbranch_vccnz .LBB0_778
	s_waitcnt vmcnt(0)
	s_lshl_b64 s[4:5], s[0:1], 10
	s_lshl_b64 s[10:11], s[0:1], 11
	s_lshl_b64 s[6:7], s[8:9], 1
	s_add_u32 s12, s37, s10
	s_addc_u32 s13, s38, s11
	s_add_u32 s12, s12, s6
	s_addc_u32 s13, s13, s7
	s_add_u32 s0, s43, s10
	s_addc_u32 s1, s44, s11
	s_add_u32 s0, s0, s6
	s_addc_u32 s1, s1, s7
	s_add_u32 s10, s17, s10
	s_addc_u32 s11, s20, s11
	s_lshl_b64 s[8:9], s[8:9], 11
	s_add_u32 s8, s35, s8
	s_addc_u32 s9, s36, s9
	v_and_b32_e32 v97, 0x5f, v244
	v_lshrrev_b32_e32 v98, 7, v244
	v_mul_u32_u24_e32 v98, 0x60, v98
	v_lshrrev_b32_e32 v99, 3, v244
	v_and_or_b32 v98, v99, 4, v98
	v_lshl_or_b32 v99, v98, 10, v97
	v_lshlrev_b32_e32 v99, 1, v99
	s_mov_b64 s[52:53], s[12:13]
	s_mov_b64 s[12:13], s[52:53]
	global_load_ushort v100, v99, s[12:13]
	s_add_u32 s12, s12, 0x800
	s_addc_u32 s13, s13, 0
	global_load_ushort v101, v99, s[12:13]
	s_add_u32 s12, s12, 0x800
	s_addc_u32 s13, s13, 0
	global_load_ushort v102, v99, s[12:13]
	s_add_u32 s12, s12, 0x800
	s_addc_u32 s13, s13, 0
	global_load_ushort v103, v99, s[12:13]
	s_add_u32 s12, s12, 0x2800
	s_addc_u32 s13, s13, 0
	global_load_ushort v104, v99, s[12:13]
	s_add_u32 s12, s12, 0x800
	s_addc_u32 s13, s13, 0
	global_load_ushort v105, v99, s[12:13]
	s_add_u32 s12, s12, 0x800
	s_addc_u32 s13, s13, 0
	global_load_ushort v106, v99, s[12:13]
	s_add_u32 s12, s12, 0x800
	s_addc_u32 s13, s13, 0
	global_load_ushort v107, v99, s[12:13]
	s_add_u32 s12, s12, 0x2800
	s_addc_u32 s13, s13, 0
	global_load_ushort v108, v99, s[12:13]
	s_add_u32 s12, s12, 0x800
	s_addc_u32 s13, s13, 0
	global_load_ushort v109, v99, s[12:13]
	s_add_u32 s12, s12, 0x800
	s_addc_u32 s13, s13, 0
	global_load_ushort v110, v99, s[12:13]
	s_add_u32 s12, s12, 0x800
	s_addc_u32 s13, s13, 0
	global_load_ushort v111, v99, s[12:13]
	s_add_u32 s12, s12, 0x2800
	s_addc_u32 s13, s13, 0
	global_load_ushort v112, v99, s[12:13]
	s_add_u32 s12, s12, 0x800
	s_addc_u32 s13, s13, 0
	global_load_ushort v113, v99, s[12:13]
	s_add_u32 s12, s12, 0x800
	s_addc_u32 s13, s13, 0
	global_load_ushort v114, v99, s[12:13]
	s_add_u32 s12, s12, 0x800
	s_addc_u32 s13, s13, 0
	global_load_ushort v115, v99, s[12:13]
	s_add_u32 s12, s12, 0x2800
	s_addc_u32 s13, s13, 0
	global_load_ushort v116, v99, s[12:13]
	s_add_u32 s12, s12, 0x800
	s_addc_u32 s13, s13, 0
	global_load_ushort v117, v99, s[12:13]
	s_add_u32 s12, s12, 0x800
	s_addc_u32 s13, s13, 0
	global_load_ushort v118, v99, s[12:13]
	s_add_u32 s12, s12, 0x800
	s_addc_u32 s13, s13, 0
	global_load_ushort v119, v99, s[12:13]
	s_add_u32 s12, s12, 0x2800
	s_addc_u32 s13, s13, 0
	global_load_ushort v120, v99, s[12:13]
	s_add_u32 s12, s12, 0x800
	s_addc_u32 s13, s13, 0
	global_load_ushort v121, v99, s[12:13]
	s_add_u32 s12, s12, 0x800
	s_addc_u32 s13, s13, 0
	global_load_ushort v122, v99, s[12:13]
	s_add_u32 s12, s12, 0x800
	s_addc_u32 s13, s13, 0
	global_load_ushort v123, v99, s[12:13]
	s_add_u32 s12, s12, 0x2800
	s_addc_u32 s13, s13, 0
	global_load_ushort v124, v99, s[12:13]
	s_add_u32 s12, s12, 0x800
	s_addc_u32 s13, s13, 0
	global_load_ushort v125, v99, s[12:13]
	s_add_u32 s12, s12, 0x800
	s_addc_u32 s13, s13, 0
	global_load_ushort v126, v99, s[12:13]
	s_add_u32 s12, s12, 0x800
	s_addc_u32 s13, s13, 0
	global_load_ushort v127, v99, s[12:13]
	s_add_u32 s12, s12, 0x2800
	s_addc_u32 s13, s13, 0
	global_load_ushort v128, v99, s[12:13]
	s_add_u32 s12, s12, 0x800
	s_addc_u32 s13, s13, 0
	global_load_ushort v129, v99, s[12:13]
	s_add_u32 s12, s12, 0x800
	s_addc_u32 s13, s13, 0
	global_load_ushort v130, v99, s[12:13]
	s_add_u32 s12, s12, 0x800
	s_addc_u32 s13, s13, 0
	global_load_ushort v131, v99, s[12:13]
	s_add_u32 s12, s12, 0x2800
	s_addc_u32 s13, s13, 0
	global_load_ushort v132, v99, s[12:13]
	s_add_u32 s12, s12, 0x800
	s_addc_u32 s13, s13, 0
	global_load_ushort v133, v99, s[12:13]
	s_add_u32 s12, s12, 0x800
	s_addc_u32 s13, s13, 0
	global_load_ushort v134, v99, s[12:13]
	s_add_u32 s12, s12, 0x800
	s_addc_u32 s13, s13, 0
	global_load_ushort v135, v99, s[12:13]
	s_add_u32 s12, s12, 0x2800
	s_addc_u32 s13, s13, 0
	global_load_ushort v136, v99, s[12:13]
	s_add_u32 s12, s12, 0x800
	s_addc_u32 s13, s13, 0
	global_load_ushort v137, v99, s[12:13]
	s_add_u32 s12, s12, 0x800
	s_addc_u32 s13, s13, 0
	global_load_ushort v138, v99, s[12:13]
	s_add_u32 s12, s12, 0x800
	s_addc_u32 s13, s13, 0
	global_load_ushort v139, v99, s[12:13]
	s_add_u32 s12, s12, 0x2800
	s_addc_u32 s13, s13, 0
	global_load_ushort v140, v99, s[12:13]
	s_add_u32 s12, s12, 0x800
	s_addc_u32 s13, s13, 0
	global_load_ushort v141, v99, s[12:13]
	s_add_u32 s12, s12, 0x800
	s_addc_u32 s13, s13, 0
	global_load_ushort v142, v99, s[12:13]
	s_add_u32 s12, s12, 0x800
	s_addc_u32 s13, s13, 0
	global_load_ushort v143, v99, s[12:13]
	s_add_u32 s12, s12, 0x2800
	s_addc_u32 s13, s13, 0
	global_load_ushort v144, v99, s[12:13]
	s_add_u32 s12, s12, 0x800
	s_addc_u32 s13, s13, 0
	global_load_ushort v145, v99, s[12:13]
	s_add_u32 s12, s12, 0x800
	s_addc_u32 s13, s13, 0
	global_load_ushort v146, v99, s[12:13]
	s_add_u32 s12, s12, 0x800
	s_addc_u32 s13, s13, 0
	global_load_ushort v147, v99, s[12:13]
	s_waitcnt vmcnt(0)
	v_lshlrev_b32_e32 v100, 16, v100
	v_mul_f32_e32 v100, v80, v100
	v_cvt_pk_bf16_f32 v100, v100, v100
	v_lshlrev_b32_e32 v101, 16, v101
	v_mul_f32_e32 v101, v81, v101
	v_cvt_pk_bf16_f32 v101, v101, v101
	v_lshlrev_b32_e32 v102, 16, v102
	v_mul_f32_e32 v102, v82, v102
	v_cvt_pk_bf16_f32 v102, v102, v102
	v_lshlrev_b32_e32 v103, 16, v103
	v_mul_f32_e32 v103, v83, v103
	v_cvt_pk_bf16_f32 v103, v103, v103
	v_lshlrev_b32_e32 v104, 16, v104
	v_mul_f32_e32 v104, v84, v104
	v_cvt_pk_bf16_f32 v104, v104, v104
	v_lshlrev_b32_e32 v105, 16, v105
	v_mul_f32_e32 v105, v85, v105
	v_cvt_pk_bf16_f32 v105, v105, v105
	v_lshlrev_b32_e32 v106, 16, v106
	v_mul_f32_e32 v106, v86, v106
	v_cvt_pk_bf16_f32 v106, v106, v106
	v_lshlrev_b32_e32 v107, 16, v107
	v_mul_f32_e32 v107, v87, v107
	v_cvt_pk_bf16_f32 v107, v107, v107
	v_lshlrev_b32_e32 v108, 16, v108
	v_mul_f32_e32 v108, v88, v108
	v_cvt_pk_bf16_f32 v108, v108, v108
	v_lshlrev_b32_e32 v109, 16, v109
	v_mul_f32_e32 v109, v89, v109
	v_cvt_pk_bf16_f32 v109, v109, v109
	v_lshlrev_b32_e32 v110, 16, v110
	v_mul_f32_e32 v110, v90, v110
	v_cvt_pk_bf16_f32 v110, v110, v110
	v_lshlrev_b32_e32 v111, 16, v111
	v_mul_f32_e32 v111, v91, v111
	v_cvt_pk_bf16_f32 v111, v111, v111
	v_lshlrev_b32_e32 v112, 16, v112
	v_mul_f32_e32 v112, v92, v112
	v_cvt_pk_bf16_f32 v112, v112, v112
	v_lshlrev_b32_e32 v113, 16, v113
	v_mul_f32_e32 v113, v93, v113
	v_cvt_pk_bf16_f32 v113, v113, v113
	v_lshlrev_b32_e32 v114, 16, v114
	v_mul_f32_e32 v114, v94, v114
	v_cvt_pk_bf16_f32 v114, v114, v114
	v_lshlrev_b32_e32 v115, 16, v115
	v_mul_f32_e32 v115, v95, v115
	v_cvt_pk_bf16_f32 v115, v115, v115
	v_lshlrev_b32_e32 v116, 16, v116
	v_mul_f32_e32 v116, v48, v116
	v_cvt_pk_bf16_f32 v116, v116, v116
	v_lshlrev_b32_e32 v117, 16, v117
	v_mul_f32_e32 v117, v49, v117
	v_cvt_pk_bf16_f32 v117, v117, v117
	v_lshlrev_b32_e32 v118, 16, v118
	v_mul_f32_e32 v118, v50, v118
	v_cvt_pk_bf16_f32 v118, v118, v118
	v_lshlrev_b32_e32 v119, 16, v119
	v_mul_f32_e32 v119, v51, v119
	v_cvt_pk_bf16_f32 v119, v119, v119
	v_lshlrev_b32_e32 v120, 16, v120
	v_mul_f32_e32 v120, v52, v120
	v_cvt_pk_bf16_f32 v120, v120, v120
	v_lshlrev_b32_e32 v121, 16, v121
	v_mul_f32_e32 v121, v53, v121
	v_cvt_pk_bf16_f32 v121, v121, v121
	v_lshlrev_b32_e32 v122, 16, v122
	v_mul_f32_e32 v122, v54, v122
	v_cvt_pk_bf16_f32 v122, v122, v122
	v_lshlrev_b32_e32 v123, 16, v123
	v_mul_f32_e32 v123, v55, v123
	v_cvt_pk_bf16_f32 v123, v123, v123
	v_lshlrev_b32_e32 v124, 16, v124
	v_mul_f32_e32 v124, v56, v124
	v_cvt_pk_bf16_f32 v124, v124, v124
	v_lshlrev_b32_e32 v125, 16, v125
	v_mul_f32_e32 v125, v57, v125
	v_cvt_pk_bf16_f32 v125, v125, v125
	v_lshlrev_b32_e32 v126, 16, v126
	v_mul_f32_e32 v126, v58, v126
	v_cvt_pk_bf16_f32 v126, v126, v126
	v_lshlrev_b32_e32 v127, 16, v127
	v_mul_f32_e32 v127, v59, v127
	v_cvt_pk_bf16_f32 v127, v127, v127
	v_lshlrev_b32_e32 v128, 16, v128
	v_mul_f32_e32 v128, v60, v128
	v_cvt_pk_bf16_f32 v128, v128, v128
	v_lshlrev_b32_e32 v129, 16, v129
	v_mul_f32_e32 v129, v61, v129
	v_cvt_pk_bf16_f32 v129, v129, v129
	v_lshlrev_b32_e32 v130, 16, v130
	v_mul_f32_e32 v130, v62, v130
	v_cvt_pk_bf16_f32 v130, v130, v130
	v_lshlrev_b32_e32 v131, 16, v131
	v_mul_f32_e32 v131, v63, v131
	v_cvt_pk_bf16_f32 v131, v131, v131
	v_lshlrev_b32_e32 v132, 16, v132
	v_mul_f32_e32 v132, v16, v132
	v_cvt_pk_bf16_f32 v132, v132, v132
	v_lshlrev_b32_e32 v133, 16, v133
	v_mul_f32_e32 v133, v17, v133
	v_cvt_pk_bf16_f32 v133, v133, v133
	v_lshlrev_b32_e32 v134, 16, v134
	v_mul_f32_e32 v134, v18, v134
	v_cvt_pk_bf16_f32 v134, v134, v134
	v_lshlrev_b32_e32 v135, 16, v135
	v_mul_f32_e32 v135, v19, v135
	v_cvt_pk_bf16_f32 v135, v135, v135
	v_lshlrev_b32_e32 v136, 16, v136
	v_mul_f32_e32 v136, v20, v136
	v_cvt_pk_bf16_f32 v136, v136, v136
	v_lshlrev_b32_e32 v137, 16, v137
	v_mul_f32_e32 v137, v21, v137
	v_cvt_pk_bf16_f32 v137, v137, v137
	v_lshlrev_b32_e32 v138, 16, v138
	v_mul_f32_e32 v138, v22, v138
	v_cvt_pk_bf16_f32 v138, v138, v138
	v_lshlrev_b32_e32 v139, 16, v139
	v_mul_f32_e32 v139, v23, v139
	v_cvt_pk_bf16_f32 v139, v139, v139
	v_lshlrev_b32_e32 v140, 16, v140
	v_mul_f32_e32 v140, v24, v140
	v_cvt_pk_bf16_f32 v140, v140, v140
	v_lshlrev_b32_e32 v141, 16, v141
	v_mul_f32_e32 v141, v25, v141
	v_cvt_pk_bf16_f32 v141, v141, v141
	v_lshlrev_b32_e32 v142, 16, v142
	v_mul_f32_e32 v142, v26, v142
	v_cvt_pk_bf16_f32 v142, v142, v142
	v_lshlrev_b32_e32 v143, 16, v143
	v_mul_f32_e32 v143, v27, v143
	v_cvt_pk_bf16_f32 v143, v143, v143
	v_lshlrev_b32_e32 v144, 16, v144
	v_mul_f32_e32 v144, v28, v144
	v_cvt_pk_bf16_f32 v144, v144, v144
	v_lshlrev_b32_e32 v145, 16, v145
	v_mul_f32_e32 v145, v29, v145
	v_cvt_pk_bf16_f32 v145, v145, v145
	v_lshlrev_b32_e32 v146, 16, v146
	v_mul_f32_e32 v146, v30, v146
	v_cvt_pk_bf16_f32 v146, v146, v146
	v_lshlrev_b32_e32 v147, 16, v147
	v_mul_f32_e32 v147, v31, v147
	v_cvt_pk_bf16_f32 v147, v147, v147
	s_mov_b64 s[50:51], s[0:1]
	global_store_short v99, v100, s[50:51]
	s_add_u32 s50, s50, 0x800
	s_addc_u32 s51, s51, 0
	global_store_short v99, v101, s[50:51]
	s_add_u32 s50, s50, 0x800
	s_addc_u32 s51, s51, 0
	global_store_short v99, v102, s[50:51]
	s_add_u32 s50, s50, 0x800
	s_addc_u32 s51, s51, 0
	global_store_short v99, v103, s[50:51]
	s_add_u32 s50, s50, 0x2800
	s_addc_u32 s51, s51, 0
	global_store_short v99, v104, s[50:51]
	s_add_u32 s50, s50, 0x800
	s_addc_u32 s51, s51, 0
	global_store_short v99, v105, s[50:51]
	s_add_u32 s50, s50, 0x800
	s_addc_u32 s51, s51, 0
	global_store_short v99, v106, s[50:51]
	s_add_u32 s50, s50, 0x800
	s_addc_u32 s51, s51, 0
	global_store_short v99, v107, s[50:51]
	s_add_u32 s50, s50, 0x2800
	s_addc_u32 s51, s51, 0
	global_store_short v99, v108, s[50:51]
	s_add_u32 s50, s50, 0x800
	s_addc_u32 s51, s51, 0
	global_store_short v99, v109, s[50:51]
	s_add_u32 s50, s50, 0x800
	s_addc_u32 s51, s51, 0
	global_store_short v99, v110, s[50:51]
	s_add_u32 s50, s50, 0x800
	s_addc_u32 s51, s51, 0
	global_store_short v99, v111, s[50:51]
	s_add_u32 s50, s50, 0x2800
	s_addc_u32 s51, s51, 0
	global_store_short v99, v112, s[50:51]
	s_add_u32 s50, s50, 0x800
	s_addc_u32 s51, s51, 0
	global_store_short v99, v113, s[50:51]
	s_add_u32 s50, s50, 0x800
	s_addc_u32 s51, s51, 0
	global_store_short v99, v114, s[50:51]
	s_add_u32 s50, s50, 0x800
	s_addc_u32 s51, s51, 0
	global_store_short v99, v115, s[50:51]
	s_add_u32 s50, s50, 0x2800
	s_addc_u32 s51, s51, 0
	global_store_short v99, v116, s[50:51]
	s_add_u32 s50, s50, 0x800
	s_addc_u32 s51, s51, 0
	global_store_short v99, v117, s[50:51]
	s_add_u32 s50, s50, 0x800
	s_addc_u32 s51, s51, 0
	global_store_short v99, v118, s[50:51]
	s_add_u32 s50, s50, 0x800
	s_addc_u32 s51, s51, 0
	global_store_short v99, v119, s[50:51]
	s_add_u32 s50, s50, 0x2800
	s_addc_u32 s51, s51, 0
	global_store_short v99, v120, s[50:51]
	s_add_u32 s50, s50, 0x800
	s_addc_u32 s51, s51, 0
	global_store_short v99, v121, s[50:51]
	s_add_u32 s50, s50, 0x800
	s_addc_u32 s51, s51, 0
	global_store_short v99, v122, s[50:51]
	s_add_u32 s50, s50, 0x800
	s_addc_u32 s51, s51, 0
	global_store_short v99, v123, s[50:51]
	s_add_u32 s50, s50, 0x2800
	s_addc_u32 s51, s51, 0
	global_store_short v99, v124, s[50:51]
	s_add_u32 s50, s50, 0x800
	s_addc_u32 s51, s51, 0
	global_store_short v99, v125, s[50:51]
	s_add_u32 s50, s50, 0x800
	s_addc_u32 s51, s51, 0
	global_store_short v99, v126, s[50:51]
	s_add_u32 s50, s50, 0x800
	s_addc_u32 s51, s51, 0
	global_store_short v99, v127, s[50:51]
	s_add_u32 s50, s50, 0x2800
	s_addc_u32 s51, s51, 0
	global_store_short v99, v128, s[50:51]
	s_add_u32 s50, s50, 0x800
	s_addc_u32 s51, s51, 0
	global_store_short v99, v129, s[50:51]
	s_add_u32 s50, s50, 0x800
	s_addc_u32 s51, s51, 0
	global_store_short v99, v130, s[50:51]
	s_add_u32 s50, s50, 0x800
	s_addc_u32 s51, s51, 0
	global_store_short v99, v131, s[50:51]
	s_add_u32 s50, s50, 0x2800
	s_addc_u32 s51, s51, 0
	global_store_short v99, v132, s[50:51]
	s_add_u32 s50, s50, 0x800
	s_addc_u32 s51, s51, 0
	global_store_short v99, v133, s[50:51]
	s_add_u32 s50, s50, 0x800
	s_addc_u32 s51, s51, 0
	global_store_short v99, v134, s[50:51]
	s_add_u32 s50, s50, 0x800
	s_addc_u32 s51, s51, 0
	global_store_short v99, v135, s[50:51]
	s_add_u32 s50, s50, 0x2800
	s_addc_u32 s51, s51, 0
	global_store_short v99, v136, s[50:51]
	s_add_u32 s50, s50, 0x800
	s_addc_u32 s51, s51, 0
	global_store_short v99, v137, s[50:51]
	s_add_u32 s50, s50, 0x800
	s_addc_u32 s51, s51, 0
	global_store_short v99, v138, s[50:51]
	s_add_u32 s50, s50, 0x800
	s_addc_u32 s51, s51, 0
	global_store_short v99, v139, s[50:51]
	s_add_u32 s50, s50, 0x2800
	s_addc_u32 s51, s51, 0
	global_store_short v99, v140, s[50:51]
	s_add_u32 s50, s50, 0x800
	s_addc_u32 s51, s51, 0
	global_store_short v99, v141, s[50:51]
	s_add_u32 s50, s50, 0x800
	s_addc_u32 s51, s51, 0
	global_store_short v99, v142, s[50:51]
	s_add_u32 s50, s50, 0x800
	s_addc_u32 s51, s51, 0
	global_store_short v99, v143, s[50:51]
	s_add_u32 s50, s50, 0x2800
	s_addc_u32 s51, s51, 0
	global_store_short v99, v144, s[50:51]
	s_add_u32 s50, s50, 0x800
	s_addc_u32 s51, s51, 0
	global_store_short v99, v145, s[50:51]
	s_add_u32 s50, s50, 0x800
	s_addc_u32 s51, s51, 0
	global_store_short v99, v146, s[50:51]
	s_add_u32 s50, s50, 0x800
	s_addc_u32 s51, s51, 0
	global_store_short v99, v147, s[50:51]
	s_mov_b64 s[12:13], s[52:53]
	global_load_ushort v100, v99, s[12:13] offset:64
	s_add_u32 s12, s12, 0x800
	s_addc_u32 s13, s13, 0
	global_load_ushort v101, v99, s[12:13] offset:64
	s_add_u32 s12, s12, 0x800
	s_addc_u32 s13, s13, 0
	global_load_ushort v102, v99, s[12:13] offset:64
	s_add_u32 s12, s12, 0x800
	s_addc_u32 s13, s13, 0
	global_load_ushort v103, v99, s[12:13] offset:64
	s_add_u32 s12, s12, 0x2800
	s_addc_u32 s13, s13, 0
	global_load_ushort v104, v99, s[12:13] offset:64
	s_add_u32 s12, s12, 0x800
	s_addc_u32 s13, s13, 0
	global_load_ushort v105, v99, s[12:13] offset:64
	s_add_u32 s12, s12, 0x800
	s_addc_u32 s13, s13, 0
	global_load_ushort v106, v99, s[12:13] offset:64
	s_add_u32 s12, s12, 0x800
	s_addc_u32 s13, s13, 0
	global_load_ushort v107, v99, s[12:13] offset:64
	s_add_u32 s12, s12, 0x2800
	s_addc_u32 s13, s13, 0
	global_load_ushort v108, v99, s[12:13] offset:64
	s_add_u32 s12, s12, 0x800
	s_addc_u32 s13, s13, 0
	global_load_ushort v109, v99, s[12:13] offset:64
	s_add_u32 s12, s12, 0x800
	s_addc_u32 s13, s13, 0
	global_load_ushort v110, v99, s[12:13] offset:64
	s_add_u32 s12, s12, 0x800
	s_addc_u32 s13, s13, 0
	global_load_ushort v111, v99, s[12:13] offset:64
	s_add_u32 s12, s12, 0x2800
	s_addc_u32 s13, s13, 0
	global_load_ushort v112, v99, s[12:13] offset:64
	s_add_u32 s12, s12, 0x800
	s_addc_u32 s13, s13, 0
	global_load_ushort v113, v99, s[12:13] offset:64
	s_add_u32 s12, s12, 0x800
	s_addc_u32 s13, s13, 0
	global_load_ushort v114, v99, s[12:13] offset:64
	s_add_u32 s12, s12, 0x800
	s_addc_u32 s13, s13, 0
	global_load_ushort v115, v99, s[12:13] offset:64
	s_add_u32 s12, s12, 0x2800
	s_addc_u32 s13, s13, 0
	global_load_ushort v116, v99, s[12:13] offset:64
	s_add_u32 s12, s12, 0x800
	s_addc_u32 s13, s13, 0
	global_load_ushort v117, v99, s[12:13] offset:64
	s_add_u32 s12, s12, 0x800
	s_addc_u32 s13, s13, 0
	global_load_ushort v118, v99, s[12:13] offset:64
	s_add_u32 s12, s12, 0x800
	s_addc_u32 s13, s13, 0
	global_load_ushort v119, v99, s[12:13] offset:64
	s_add_u32 s12, s12, 0x2800
	s_addc_u32 s13, s13, 0
	global_load_ushort v120, v99, s[12:13] offset:64
	s_add_u32 s12, s12, 0x800
	s_addc_u32 s13, s13, 0
	global_load_ushort v121, v99, s[12:13] offset:64
	s_add_u32 s12, s12, 0x800
	s_addc_u32 s13, s13, 0
	global_load_ushort v122, v99, s[12:13] offset:64
	s_add_u32 s12, s12, 0x800
	s_addc_u32 s13, s13, 0
	global_load_ushort v123, v99, s[12:13] offset:64
	s_add_u32 s12, s12, 0x2800
	s_addc_u32 s13, s13, 0
	global_load_ushort v124, v99, s[12:13] offset:64
	s_add_u32 s12, s12, 0x800
	s_addc_u32 s13, s13, 0
	global_load_ushort v125, v99, s[12:13] offset:64
	s_add_u32 s12, s12, 0x800
	s_addc_u32 s13, s13, 0
	global_load_ushort v126, v99, s[12:13] offset:64
	s_add_u32 s12, s12, 0x800
	s_addc_u32 s13, s13, 0
	global_load_ushort v127, v99, s[12:13] offset:64
	s_add_u32 s12, s12, 0x2800
	s_addc_u32 s13, s13, 0
	global_load_ushort v128, v99, s[12:13] offset:64
	s_add_u32 s12, s12, 0x800
	s_addc_u32 s13, s13, 0
	global_load_ushort v129, v99, s[12:13] offset:64
	s_add_u32 s12, s12, 0x800
	s_addc_u32 s13, s13, 0
	global_load_ushort v130, v99, s[12:13] offset:64
	s_add_u32 s12, s12, 0x800
	s_addc_u32 s13, s13, 0
	global_load_ushort v131, v99, s[12:13] offset:64
	s_add_u32 s12, s12, 0x2800
	s_addc_u32 s13, s13, 0
	global_load_ushort v132, v99, s[12:13] offset:64
	s_add_u32 s12, s12, 0x800
	s_addc_u32 s13, s13, 0
	global_load_ushort v133, v99, s[12:13] offset:64
	s_add_u32 s12, s12, 0x800
	s_addc_u32 s13, s13, 0
	global_load_ushort v134, v99, s[12:13] offset:64
	s_add_u32 s12, s12, 0x800
	s_addc_u32 s13, s13, 0
	global_load_ushort v135, v99, s[12:13] offset:64
	s_add_u32 s12, s12, 0x2800
	s_addc_u32 s13, s13, 0
	global_load_ushort v136, v99, s[12:13] offset:64
	s_add_u32 s12, s12, 0x800
	s_addc_u32 s13, s13, 0
	global_load_ushort v137, v99, s[12:13] offset:64
	s_add_u32 s12, s12, 0x800
	s_addc_u32 s13, s13, 0
	global_load_ushort v138, v99, s[12:13] offset:64
	s_add_u32 s12, s12, 0x800
	s_addc_u32 s13, s13, 0
	global_load_ushort v139, v99, s[12:13] offset:64
	s_add_u32 s12, s12, 0x2800
	s_addc_u32 s13, s13, 0
	global_load_ushort v140, v99, s[12:13] offset:64
	s_add_u32 s12, s12, 0x800
	s_addc_u32 s13, s13, 0
	global_load_ushort v141, v99, s[12:13] offset:64
	s_add_u32 s12, s12, 0x800
	s_addc_u32 s13, s13, 0
	global_load_ushort v142, v99, s[12:13] offset:64
	s_add_u32 s12, s12, 0x800
	s_addc_u32 s13, s13, 0
	global_load_ushort v143, v99, s[12:13] offset:64
	s_add_u32 s12, s12, 0x2800
	s_addc_u32 s13, s13, 0
	global_load_ushort v144, v99, s[12:13] offset:64
	s_add_u32 s12, s12, 0x800
	s_addc_u32 s13, s13, 0
	global_load_ushort v145, v99, s[12:13] offset:64
	s_add_u32 s12, s12, 0x800
	s_addc_u32 s13, s13, 0
	global_load_ushort v146, v99, s[12:13] offset:64
	s_add_u32 s12, s12, 0x800
	s_addc_u32 s13, s13, 0
	global_load_ushort v147, v99, s[12:13] offset:64
	s_waitcnt vmcnt(0)
	v_lshlrev_b32_e32 v100, 16, v100
	v_mul_f32_e32 v100, v64, v100
	v_cvt_pk_bf16_f32 v100, v100, v100
	v_lshlrev_b32_e32 v101, 16, v101
	v_mul_f32_e32 v101, v65, v101
	v_cvt_pk_bf16_f32 v101, v101, v101
	v_lshlrev_b32_e32 v102, 16, v102
	v_mul_f32_e32 v102, v66, v102
	v_cvt_pk_bf16_f32 v102, v102, v102
	v_lshlrev_b32_e32 v103, 16, v103
	v_mul_f32_e32 v103, v67, v103
	v_cvt_pk_bf16_f32 v103, v103, v103
	v_lshlrev_b32_e32 v104, 16, v104
	v_mul_f32_e32 v104, v68, v104
	v_cvt_pk_bf16_f32 v104, v104, v104
	v_lshlrev_b32_e32 v105, 16, v105
	v_mul_f32_e32 v105, v69, v105
	v_cvt_pk_bf16_f32 v105, v105, v105
	v_lshlrev_b32_e32 v106, 16, v106
	v_mul_f32_e32 v106, v70, v106
	v_cvt_pk_bf16_f32 v106, v106, v106
	v_lshlrev_b32_e32 v107, 16, v107
	v_mul_f32_e32 v107, v71, v107
	v_cvt_pk_bf16_f32 v107, v107, v107
	v_lshlrev_b32_e32 v108, 16, v108
	v_mul_f32_e32 v108, v72, v108
	v_cvt_pk_bf16_f32 v108, v108, v108
	v_lshlrev_b32_e32 v109, 16, v109
	v_mul_f32_e32 v109, v73, v109
	v_cvt_pk_bf16_f32 v109, v109, v109
	v_lshlrev_b32_e32 v110, 16, v110
	v_mul_f32_e32 v110, v74, v110
	v_cvt_pk_bf16_f32 v110, v110, v110
	v_lshlrev_b32_e32 v111, 16, v111
	v_mul_f32_e32 v111, v75, v111
	v_cvt_pk_bf16_f32 v111, v111, v111
	v_lshlrev_b32_e32 v112, 16, v112
	v_mul_f32_e32 v112, v76, v112
	v_cvt_pk_bf16_f32 v112, v112, v112
	v_lshlrev_b32_e32 v113, 16, v113
	v_mul_f32_e32 v113, v77, v113
	v_cvt_pk_bf16_f32 v113, v113, v113
	v_lshlrev_b32_e32 v114, 16, v114
	v_mul_f32_e32 v114, v78, v114
	v_cvt_pk_bf16_f32 v114, v114, v114
	v_lshlrev_b32_e32 v115, 16, v115
	v_mul_f32_e32 v115, v79, v115
	v_cvt_pk_bf16_f32 v115, v115, v115
	v_lshlrev_b32_e32 v116, 16, v116
	v_mul_f32_e32 v116, v32, v116
	v_cvt_pk_bf16_f32 v116, v116, v116
	v_lshlrev_b32_e32 v117, 16, v117
	v_mul_f32_e32 v117, v33, v117
	v_cvt_pk_bf16_f32 v117, v117, v117
	v_lshlrev_b32_e32 v118, 16, v118
	v_mul_f32_e32 v118, v34, v118
	v_cvt_pk_bf16_f32 v118, v118, v118
	v_lshlrev_b32_e32 v119, 16, v119
	v_mul_f32_e32 v119, v35, v119
	v_cvt_pk_bf16_f32 v119, v119, v119
	v_lshlrev_b32_e32 v120, 16, v120
	v_mul_f32_e32 v120, v36, v120
	v_cvt_pk_bf16_f32 v120, v120, v120
	v_lshlrev_b32_e32 v121, 16, v121
	v_mul_f32_e32 v121, v37, v121
	v_cvt_pk_bf16_f32 v121, v121, v121
	v_lshlrev_b32_e32 v122, 16, v122
	v_mul_f32_e32 v122, v38, v122
	v_cvt_pk_bf16_f32 v122, v122, v122
	v_lshlrev_b32_e32 v123, 16, v123
	v_mul_f32_e32 v123, v39, v123
	v_cvt_pk_bf16_f32 v123, v123, v123
	v_lshlrev_b32_e32 v124, 16, v124
	v_mul_f32_e32 v124, v40, v124
	v_cvt_pk_bf16_f32 v124, v124, v124
	v_lshlrev_b32_e32 v125, 16, v125
	v_mul_f32_e32 v125, v41, v125
	v_cvt_pk_bf16_f32 v125, v125, v125
	v_lshlrev_b32_e32 v126, 16, v126
	v_mul_f32_e32 v126, v42, v126
	v_cvt_pk_bf16_f32 v126, v126, v126
	v_lshlrev_b32_e32 v127, 16, v127
	v_mul_f32_e32 v127, v43, v127
	v_cvt_pk_bf16_f32 v127, v127, v127
	v_lshlrev_b32_e32 v128, 16, v128
	v_mul_f32_e32 v128, v44, v128
	v_cvt_pk_bf16_f32 v128, v128, v128
	v_lshlrev_b32_e32 v129, 16, v129
	v_mul_f32_e32 v129, v45, v129
	v_cvt_pk_bf16_f32 v129, v129, v129
	v_lshlrev_b32_e32 v130, 16, v130
	v_mul_f32_e32 v130, v46, v130
	v_cvt_pk_bf16_f32 v130, v130, v130
	v_lshlrev_b32_e32 v131, 16, v131
	v_mul_f32_e32 v131, v47, v131
	v_cvt_pk_bf16_f32 v131, v131, v131
	v_lshlrev_b32_e32 v132, 16, v132
	v_mul_f32_e32 v132, v0, v132
	v_cvt_pk_bf16_f32 v132, v132, v132
	v_lshlrev_b32_e32 v133, 16, v133
	v_mul_f32_e32 v133, v1, v133
	v_cvt_pk_bf16_f32 v133, v133, v133
	v_lshlrev_b32_e32 v134, 16, v134
	v_mul_f32_e32 v134, v2, v134
	v_cvt_pk_bf16_f32 v134, v134, v134
	v_lshlrev_b32_e32 v135, 16, v135
	v_mul_f32_e32 v135, v3, v135
	v_cvt_pk_bf16_f32 v135, v135, v135
	v_lshlrev_b32_e32 v136, 16, v136
	v_mul_f32_e32 v136, v4, v136
	v_cvt_pk_bf16_f32 v136, v136, v136
	v_lshlrev_b32_e32 v137, 16, v137
	v_mul_f32_e32 v137, v5, v137
	v_cvt_pk_bf16_f32 v137, v137, v137
	v_lshlrev_b32_e32 v138, 16, v138
	v_mul_f32_e32 v138, v6, v138
	v_cvt_pk_bf16_f32 v138, v138, v138
	v_lshlrev_b32_e32 v139, 16, v139
	v_mul_f32_e32 v139, v7, v139
	v_cvt_pk_bf16_f32 v139, v139, v139
	v_lshlrev_b32_e32 v140, 16, v140
	v_mul_f32_e32 v140, v8, v140
	v_cvt_pk_bf16_f32 v140, v140, v140
	v_lshlrev_b32_e32 v141, 16, v141
	v_mul_f32_e32 v141, v9, v141
	v_cvt_pk_bf16_f32 v141, v141, v141
	v_lshlrev_b32_e32 v142, 16, v142
	v_mul_f32_e32 v142, v10, v142
	v_cvt_pk_bf16_f32 v142, v142, v142
	v_lshlrev_b32_e32 v143, 16, v143
	v_mul_f32_e32 v143, v11, v143
	v_cvt_pk_bf16_f32 v143, v143, v143
	v_lshlrev_b32_e32 v144, 16, v144
	v_mul_f32_e32 v144, v12, v144
	v_cvt_pk_bf16_f32 v144, v144, v144
	v_lshlrev_b32_e32 v145, 16, v145
	v_mul_f32_e32 v145, v13, v145
	v_cvt_pk_bf16_f32 v145, v145, v145
	v_lshlrev_b32_e32 v146, 16, v146
	v_mul_f32_e32 v146, v14, v146
	v_cvt_pk_bf16_f32 v146, v146, v146
	v_lshlrev_b32_e32 v147, 16, v147
	v_mul_f32_e32 v147, v15, v147
	v_cvt_pk_bf16_f32 v147, v147, v147
	s_mov_b64 s[50:51], s[0:1]
	global_store_short v99, v100, s[50:51] offset:64
	s_add_u32 s50, s50, 0x800
	s_addc_u32 s51, s51, 0
	global_store_short v99, v101, s[50:51] offset:64
	s_add_u32 s50, s50, 0x800
	s_addc_u32 s51, s51, 0
	global_store_short v99, v102, s[50:51] offset:64
	s_add_u32 s50, s50, 0x800
	s_addc_u32 s51, s51, 0
	global_store_short v99, v103, s[50:51] offset:64
	s_add_u32 s50, s50, 0x2800
	s_addc_u32 s51, s51, 0
	global_store_short v99, v104, s[50:51] offset:64
	s_add_u32 s50, s50, 0x800
	s_addc_u32 s51, s51, 0
	global_store_short v99, v105, s[50:51] offset:64
	s_add_u32 s50, s50, 0x800
	s_addc_u32 s51, s51, 0
	global_store_short v99, v106, s[50:51] offset:64
	s_add_u32 s50, s50, 0x800
	s_addc_u32 s51, s51, 0
	global_store_short v99, v107, s[50:51] offset:64
	s_add_u32 s50, s50, 0x2800
	s_addc_u32 s51, s51, 0
	global_store_short v99, v108, s[50:51] offset:64
	s_add_u32 s50, s50, 0x800
	s_addc_u32 s51, s51, 0
	global_store_short v99, v109, s[50:51] offset:64
	s_add_u32 s50, s50, 0x800
	s_addc_u32 s51, s51, 0
	global_store_short v99, v110, s[50:51] offset:64
	s_add_u32 s50, s50, 0x800
	s_addc_u32 s51, s51, 0
	global_store_short v99, v111, s[50:51] offset:64
	s_add_u32 s50, s50, 0x2800
	s_addc_u32 s51, s51, 0
	global_store_short v99, v112, s[50:51] offset:64
	s_add_u32 s50, s50, 0x800
	s_addc_u32 s51, s51, 0
	global_store_short v99, v113, s[50:51] offset:64
	s_add_u32 s50, s50, 0x800
	s_addc_u32 s51, s51, 0
	global_store_short v99, v114, s[50:51] offset:64
	s_add_u32 s50, s50, 0x800
	s_addc_u32 s51, s51, 0
	global_store_short v99, v115, s[50:51] offset:64
	s_add_u32 s50, s50, 0x2800
	s_addc_u32 s51, s51, 0
	global_store_short v99, v116, s[50:51] offset:64
	s_add_u32 s50, s50, 0x800
	s_addc_u32 s51, s51, 0
	global_store_short v99, v117, s[50:51] offset:64
	s_add_u32 s50, s50, 0x800
	s_addc_u32 s51, s51, 0
	global_store_short v99, v118, s[50:51] offset:64
	s_add_u32 s50, s50, 0x800
	s_addc_u32 s51, s51, 0
	global_store_short v99, v119, s[50:51] offset:64
	s_add_u32 s50, s50, 0x2800
	s_addc_u32 s51, s51, 0
	global_store_short v99, v120, s[50:51] offset:64
	s_add_u32 s50, s50, 0x800
	s_addc_u32 s51, s51, 0
	global_store_short v99, v121, s[50:51] offset:64
	s_add_u32 s50, s50, 0x800
	s_addc_u32 s51, s51, 0
	global_store_short v99, v122, s[50:51] offset:64
	s_add_u32 s50, s50, 0x800
	s_addc_u32 s51, s51, 0
	global_store_short v99, v123, s[50:51] offset:64
	s_add_u32 s50, s50, 0x2800
	s_addc_u32 s51, s51, 0
	global_store_short v99, v124, s[50:51] offset:64
	s_add_u32 s50, s50, 0x800
	s_addc_u32 s51, s51, 0
	global_store_short v99, v125, s[50:51] offset:64
	s_add_u32 s50, s50, 0x800
	s_addc_u32 s51, s51, 0
	global_store_short v99, v126, s[50:51] offset:64
	s_add_u32 s50, s50, 0x800
	s_addc_u32 s51, s51, 0
	global_store_short v99, v127, s[50:51] offset:64
	s_add_u32 s50, s50, 0x2800
	s_addc_u32 s51, s51, 0
	global_store_short v99, v128, s[50:51] offset:64
	s_add_u32 s50, s50, 0x800
	s_addc_u32 s51, s51, 0
	global_store_short v99, v129, s[50:51] offset:64
	s_add_u32 s50, s50, 0x800
	s_addc_u32 s51, s51, 0
	global_store_short v99, v130, s[50:51] offset:64
	s_add_u32 s50, s50, 0x800
	s_addc_u32 s51, s51, 0
	global_store_short v99, v131, s[50:51] offset:64
	s_add_u32 s50, s50, 0x2800
	s_addc_u32 s51, s51, 0
	global_store_short v99, v132, s[50:51] offset:64
	s_add_u32 s50, s50, 0x800
	s_addc_u32 s51, s51, 0
	global_store_short v99, v133, s[50:51] offset:64
	s_add_u32 s50, s50, 0x800
	s_addc_u32 s51, s51, 0
	global_store_short v99, v134, s[50:51] offset:64
	s_add_u32 s50, s50, 0x800
	s_addc_u32 s51, s51, 0
	global_store_short v99, v135, s[50:51] offset:64
	s_add_u32 s50, s50, 0x2800
	s_addc_u32 s51, s51, 0
	global_store_short v99, v136, s[50:51] offset:64
	s_add_u32 s50, s50, 0x800
	s_addc_u32 s51, s51, 0
	global_store_short v99, v137, s[50:51] offset:64
	s_add_u32 s50, s50, 0x800
	s_addc_u32 s51, s51, 0
	global_store_short v99, v138, s[50:51] offset:64
	s_add_u32 s50, s50, 0x800
	s_addc_u32 s51, s51, 0
	global_store_short v99, v139, s[50:51] offset:64
	s_add_u32 s50, s50, 0x2800
	s_addc_u32 s51, s51, 0
	global_store_short v99, v140, s[50:51] offset:64
	s_add_u32 s50, s50, 0x800
	s_addc_u32 s51, s51, 0
	global_store_short v99, v141, s[50:51] offset:64
	s_add_u32 s50, s50, 0x800
	s_addc_u32 s51, s51, 0
	global_store_short v99, v142, s[50:51] offset:64
	s_add_u32 s50, s50, 0x800
	s_addc_u32 s51, s51, 0
	global_store_short v99, v143, s[50:51] offset:64
	s_add_u32 s50, s50, 0x2800
	s_addc_u32 s51, s51, 0
	global_store_short v99, v144, s[50:51] offset:64
	s_add_u32 s50, s50, 0x800
	s_addc_u32 s51, s51, 0
	global_store_short v99, v145, s[50:51] offset:64
	s_add_u32 s50, s50, 0x800
	s_addc_u32 s51, s51, 0
	global_store_short v99, v146, s[50:51] offset:64
	s_add_u32 s50, s50, 0x800
	s_addc_u32 s51, s51, 0
	global_store_short v99, v147, s[50:51] offset:64
	v_mov_b32_e32 v43, v96
	v_mov_b32_e32 v46, v244
	s_mov_b64 s[50:51], 0x50000
	s_mov_b64 s[52:53], 0x50180
	v_ashrrev_i32_e32 v40, 3, v46
	v_ashrrev_i32_e32 v41, 31, v40
	v_lshlrev_b64 v[0:1], 11, v[40:41]
	v_lshlrev_b32_e32 v4, 4, v46
	v_lshl_add_u64 v[2:3], s[10:11], 0, v[0:1]
	v_and_b32_e32 v42, 0x70, v4
	v_lshl_add_u64 v[180:181], v[2:3], 0, v[42:43]
	v_lshl_add_u64 v[24:25], s[8:9], 0, v[0:1]
	global_load_dwordx4 v[0:3], v[180:181], off
	v_lshl_add_u64 v[8:9], v[180:181], 0, s[40:41]
	global_load_dwordx4 v[4:7], v[8:9], off
	v_lshl_add_u64 v[12:13], v[180:181], 0, s[18:19]
	global_load_dwordx4 v[8:11], v[12:13], off
	v_lshl_add_u64 v[16:17], v[180:181], 0, s[92:93]
	global_load_dwordx4 v[12:15], v[16:17], off
	v_lshl_add_u64 v[20:21], v[180:181], 0, s[62:63]
	global_load_dwordx4 v[16:19], v[20:21], off
	v_lshl_add_u64 v[26:27], v[180:181], 0, s[50:51]
	global_load_dwordx4 v[20:23], v[26:27], off
	v_lshl_add_u64 v[182:183], v[24:25], 0, v[42:43]
	global_load_dwordx4 v[24:27], v[182:183], off
	v_lshl_add_u64 v[32:33], v[182:183], 0, s[40:41]
	global_load_dwordx4 v[28:31], v[32:33], off
	v_lshl_add_u64 v[36:37], v[182:183], 0, s[18:19]
	global_load_dwordx4 v[32:35], v[36:37], off
	v_lshl_add_u64 v[44:45], v[182:183], 0, s[92:93]
	global_load_dwordx4 v[36:39], v[44:45], off
	v_lshl_add_u64 v[44:45], v[180:181], 0, s[94:95]
	global_load_dwordx4 v[98:101], v[44:45], off
	v_lshl_add_u64 v[44:45], v[180:181], 0, s[96:97]
	global_load_dwordx4 v[102:105], v[44:45], off
	v_lshl_add_u64 v[44:45], v[180:181], 0, s[64:65]
	global_load_dwordx4 v[106:109], v[44:45], off
	v_lshl_add_u64 v[44:45], v[180:181], 0, s[66:67]
	global_load_dwordx4 v[110:113], v[44:45], off
	v_lshl_add_u64 v[44:45], v[180:181], 0, s[80:81]
	global_load_dwordx4 v[114:117], v[44:45], off
	s_mov_b64 s[8:9], 0x50080
	v_lshl_add_u64 v[44:45], v[180:181], 0, s[8:9]
	global_load_dwordx4 v[118:121], v[44:45], off
	v_lshl_add_u64 v[44:45], v[182:183], 0, s[94:95]
	global_load_dwordx4 v[122:125], v[44:45], off
	v_lshl_add_u64 v[44:45], v[182:183], 0, s[96:97]
	global_load_dwordx4 v[126:129], v[44:45], off
	v_lshl_add_u64 v[44:45], v[182:183], 0, s[64:65]
	global_load_dwordx4 v[130:133], v[44:45], off
	v_lshl_add_u64 v[44:45], v[182:183], 0, s[66:67]
	global_load_dwordx4 v[134:137], v[44:45], off
	s_waitcnt vmcnt(10)
	v_mul_lo_u32 v40, v40, s85
	v_add_u32_e32 v97, v42, v40
	ds_write_b128 v97, v[0:3]
	ds_write_b128 v97, v[4:7] offset:4608
	ds_write_b128 v97, v[8:11] offset:9216
	ds_write_b128 v97, v[12:15] offset:13824
	ds_write_b128 v97, v[16:19] offset:18432
	ds_write_b128 v97, v[20:23] offset:23040
	ds_write_b128 v97, v[24:27] offset:27648
	ds_write_b128 v97, v[28:31] offset:32256
	ds_write_b128 v97, v[32:35] offset:36864
	ds_write_b128 v97, v[36:39] offset:41472
	v_ashrrev_i32_e32 v0, 7, v46
	v_mul_lo_u32 v0, v0, s45
	v_and_or_b32 v0, v46, 31, v0
	v_lshrrev_b32_e32 v1, 1, v46
	v_and_b32_e32 v2, 0x5f, v46
	v_and_b32_e32 v1, 16, v1
	v_mul_lo_u32 v3, v0, s85
	v_mul_u32_u24_e32 v2, 0x90, v2
	v_mov_b32_e32 v0, 0
	s_mov_b32 s9, 0
	s_movk_i32 s8, 0x80
	v_add_u32_e32 v179, v1, v3
	v_add_u32_e32 v184, v1, v2
	v_mov_b32_e32 v1, v0
	v_mov_b32_e32 v2, v0
	v_mov_b32_e32 v3, v0
	v_mov_b32_e32 v4, v0
	v_mov_b32_e32 v5, v0
	v_mov_b32_e32 v6, v0
	v_mov_b32_e32 v7, v0
	v_mov_b32_e32 v8, v0
	v_mov_b32_e32 v9, v0
	v_mov_b32_e32 v10, v0
	v_mov_b32_e32 v11, v0
	v_mov_b32_e32 v12, v0
	v_mov_b32_e32 v13, v0
	v_mov_b32_e32 v14, v0
	v_mov_b32_e32 v15, v0
	v_mov_b32_e32 v16, v0
	v_mov_b32_e32 v17, v0
	v_mov_b32_e32 v18, v0
	v_mov_b32_e32 v19, v0
	v_mov_b32_e32 v20, v0
	v_mov_b32_e32 v21, v0
	v_mov_b32_e32 v22, v0
	v_mov_b32_e32 v23, v0
	v_mov_b32_e32 v24, v0
	v_mov_b32_e32 v25, v0
	v_mov_b32_e32 v26, v0
	v_mov_b32_e32 v27, v0
	v_mov_b32_e32 v28, v0
	v_mov_b32_e32 v29, v0
	v_mov_b32_e32 v30, v0
	v_mov_b32_e32 v31, v0
	v_mov_b32_e32 v32, v0
	v_mov_b32_e32 v33, v0
	v_mov_b32_e32 v34, v0
	v_mov_b32_e32 v35, v0
	v_mov_b32_e32 v36, v0
	v_mov_b32_e32 v37, v0
	v_mov_b32_e32 v38, v0
	v_mov_b32_e32 v39, v0
	v_mov_b32_e32 v40, v0
	v_mov_b32_e32 v41, v0
	v_mov_b32_e32 v42, v0
	v_mov_b32_e32 v43, v0
	v_mov_b32_e32 v44, v0
	v_mov_b32_e32 v45, v0
	v_mov_b32_e32 v46, v0
	v_mov_b32_e32 v47, v0
	v_mov_b32_e32 v48, v0
	v_mov_b32_e32 v49, v0
	v_mov_b32_e32 v50, v0
	v_mov_b32_e32 v51, v0
	v_mov_b32_e32 v52, v0
	v_mov_b32_e32 v53, v0
	v_mov_b32_e32 v54, v0
	v_mov_b32_e32 v55, v0
	v_mov_b32_e32 v56, v0
	v_mov_b32_e32 v57, v0
	v_mov_b32_e32 v58, v0
	v_mov_b32_e32 v59, v0
	v_mov_b32_e32 v60, v0
	v_mov_b32_e32 v61, v0
	v_mov_b32_e32 v62, v0
	v_mov_b32_e32 v63, v0
	v_mov_b32_e32 v64, v0
	v_mov_b32_e32 v65, v0
	v_mov_b32_e32 v66, v0
	v_mov_b32_e32 v67, v0
	v_mov_b32_e32 v68, v0
	v_mov_b32_e32 v69, v0
	v_mov_b32_e32 v70, v0
	v_mov_b32_e32 v71, v0
	v_mov_b32_e32 v72, v0
	v_mov_b32_e32 v73, v0
	v_mov_b32_e32 v74, v0
	v_mov_b32_e32 v75, v0
	v_mov_b32_e32 v76, v0
	v_mov_b32_e32 v77, v0
	v_mov_b32_e32 v78, v0
	v_mov_b32_e32 v79, v0
	v_mov_b32_e32 v80, v0
	v_mov_b32_e32 v81, v0
	v_mov_b32_e32 v82, v0
	v_mov_b32_e32 v83, v0
	v_mov_b32_e32 v84, v0
	v_mov_b32_e32 v85, v0
	v_mov_b32_e32 v86, v0
	v_mov_b32_e32 v87, v0
	v_mov_b32_e32 v88, v0
	v_mov_b32_e32 v89, v0
	v_mov_b32_e32 v90, v0
	v_mov_b32_e32 v91, v0
	v_mov_b32_e32 v92, v0
	v_mov_b32_e32 v93, v0
	v_mov_b32_e32 v94, v0
	v_mov_b32_e32 v95, v0
	s_waitcnt lgkmcnt(0)
	s_barrier
.LBB0_780:
	s_add_i32 s10, s9, 2
	s_cmp_lt_u32 s9, 14
	s_cselect_b64 s[12:13], -1, 0
	s_and_b64 vcc, s[12:13], exec
	s_cselect_b32 s2, s8, 0x3c0
	s_lshl_b64 s[12:13], s[2:3], 1
	v_lshl_add_u64 v[158:159], v[180:181], 0, s[12:13]
	global_load_dwordx4 v[138:141], v[158:159], off
	v_lshl_add_u64 v[146:147], v[158:159], 0, s[40:41]
	global_load_dwordx4 v[142:145], v[146:147], off
	v_lshl_add_u64 v[150:151], v[158:159], 0, s[18:19]
	global_load_dwordx4 v[146:149], v[150:151], off
	v_lshl_add_u64 v[154:155], v[158:159], 0, s[92:93]
	global_load_dwordx4 v[150:153], v[154:155], off
	v_lshl_add_u64 v[160:161], v[158:159], 0, s[62:63]
	global_load_dwordx4 v[154:157], v[160:161], off
	v_lshl_add_u64 v[162:163], v[158:159], 0, s[50:51]
	global_load_dwordx4 v[158:161], v[162:163], off
	v_lshl_add_u64 v[174:175], v[182:183], 0, s[12:13]
	global_load_dwordx4 v[162:165], v[174:175], off
	v_lshl_add_u64 v[170:171], v[174:175], 0, s[40:41]
	global_load_dwordx4 v[166:169], v[170:171], off
	v_lshl_add_u64 v[176:177], v[174:175], 0, s[18:19]
	global_load_dwordx4 v[170:173], v[176:177], off
	v_lshl_add_u64 v[186:187], v[174:175], 0, s[92:93]
	global_load_dwordx4 v[174:177], v[186:187], off
	s_min_u32 s2, s9, 12
	s_lshl_b32 s2, s2, 7
	s_addk_i32 s8, 0x80
	s_mov_b32 s9, s10
	ds_read_b128 v[186:189], v179
	ds_read_b128 v[190:193], v184 offset:27648
	ds_read_b128 v[194:197], v179 offset:4608
	ds_read_b128 v[198:201], v184 offset:32256
	ds_read_b128 v[202:205], v179 offset:9216
	ds_read_b128 v[206:209], v179 offset:32
	ds_read_b128 v[210:213], v184 offset:27680
	ds_read_b128 v[214:217], v179 offset:4640
	ds_read_b128 v[218:221], v184 offset:32288
	ds_read_b128 v[222:225], v179 offset:9248
	s_waitcnt lgkmcnt(5)
	v_mfma_f32_32x32x16_bf16 v[80:95], v[186:189], v[190:193], v[80:95]
	v_mfma_f32_32x32x16_bf16 v[64:79], v[186:189], v[198:201], v[64:79]
	v_mfma_f32_32x32x16_bf16 v[48:63], v[194:197], v[190:193], v[48:63]
	v_mfma_f32_32x32x16_bf16 v[32:47], v[194:197], v[198:201], v[32:47]
	v_mfma_f32_32x32x16_bf16 v[16:31], v[202:205], v[190:193], v[16:31]
	v_mfma_f32_32x32x16_bf16 v[0:15], v[202:205], v[198:201], v[0:15]
	ds_read_b128 v[186:189], v179 offset:64
	ds_read_b128 v[190:193], v184 offset:27712
	ds_read_b128 v[194:197], v179 offset:4672
	ds_read_b128 v[198:201], v184 offset:32320
	ds_read_b128 v[202:205], v179 offset:9280
	s_waitcnt lgkmcnt(5)
	v_mfma_f32_32x32x16_bf16 v[80:95], v[206:209], v[210:213], v[80:95]
	v_mfma_f32_32x32x16_bf16 v[64:79], v[206:209], v[218:221], v[64:79]
	v_mfma_f32_32x32x16_bf16 v[48:63], v[214:217], v[210:213], v[48:63]
	v_mfma_f32_32x32x16_bf16 v[32:47], v[214:217], v[218:221], v[32:47]
	v_mfma_f32_32x32x16_bf16 v[16:31], v[222:225], v[210:213], v[16:31]
	v_mfma_f32_32x32x16_bf16 v[0:15], v[222:225], v[218:221], v[0:15]
	ds_read_b128 v[206:209], v179 offset:96
	ds_read_b128 v[210:213], v184 offset:27744
	ds_read_b128 v[214:217], v179 offset:4704
	ds_read_b128 v[218:221], v184 offset:32352
	ds_read_b128 v[222:225], v179 offset:9312
	s_waitcnt lgkmcnt(0)
	s_waitcnt vmcnt(10)
	s_barrier
	v_mfma_f32_32x32x16_bf16 v[80:95], v[186:189], v[190:193], v[80:95]
	ds_write_b128 v97, v[98:101]
	ds_write_b128 v97, v[102:105] offset:4608
	v_mfma_f32_32x32x16_bf16 v[64:79], v[186:189], v[198:201], v[64:79]
	ds_write_b128 v97, v[106:109] offset:9216
	ds_write_b128 v97, v[110:113] offset:13824
	v_mfma_f32_32x32x16_bf16 v[48:63], v[194:197], v[190:193], v[48:63]
	ds_write_b128 v97, v[114:117] offset:18432
	ds_write_b128 v97, v[118:121] offset:23040
	v_mfma_f32_32x32x16_bf16 v[32:47], v[194:197], v[198:201], v[32:47]
	ds_write_b128 v97, v[122:125] offset:27648
	ds_write_b128 v97, v[126:129] offset:32256
	v_mfma_f32_32x32x16_bf16 v[16:31], v[202:205], v[190:193], v[16:31]
	ds_write_b128 v97, v[130:133] offset:36864
	ds_write_b128 v97, v[134:137] offset:41472
	v_mfma_f32_32x32x16_bf16 v[0:15], v[202:205], v[198:201], v[0:15]
	v_lshl_add_u64 v[118:119], v[180:181], 0, s[2:3]
	v_mfma_f32_32x32x16_bf16 v[80:95], v[206:209], v[210:213], v[80:95]
	v_mfma_f32_32x32x16_bf16 v[64:79], v[206:209], v[218:221], v[64:79]
	v_mfma_f32_32x32x16_bf16 v[48:63], v[214:217], v[210:213], v[48:63]
	v_mfma_f32_32x32x16_bf16 v[32:47], v[214:217], v[218:221], v[32:47]
	v_mfma_f32_32x32x16_bf16 v[16:31], v[222:225], v[210:213], v[16:31]
	v_mfma_f32_32x32x16_bf16 v[0:15], v[222:225], v[218:221], v[0:15]
	s_waitcnt lgkmcnt(0)
	s_barrier
	v_lshl_add_u64 v[102:103], v[118:119], 0, s[22:23]
	global_load_dwordx4 v[98:101], v[102:103], off
	v_lshl_add_u64 v[106:107], v[118:119], 0, s[76:77]
	global_load_dwordx4 v[102:105], v[106:107], off
	v_lshl_add_u64 v[110:111], v[118:119], 0, s[26:27]
	global_load_dwordx4 v[106:109], v[110:111], off
	v_lshl_add_u64 v[114:115], v[118:119], 0, s[70:71]
	global_load_dwordx4 v[110:113], v[114:115], off
	v_lshl_add_u64 v[120:121], v[118:119], 0, s[48:49]
	global_load_dwordx4 v[114:117], v[120:121], off
	v_lshl_add_u64 v[122:123], v[118:119], 0, s[52:53]
	global_load_dwordx4 v[118:121], v[122:123], off
	v_lshl_add_u64 v[134:135], v[182:183], 0, s[2:3]
	v_lshl_add_u64 v[126:127], v[134:135], 0, s[22:23]
	global_load_dwordx4 v[122:125], v[126:127], off
	v_lshl_add_u64 v[130:131], v[134:135], 0, s[76:77]
	global_load_dwordx4 v[126:129], v[130:131], off
	v_lshl_add_u64 v[136:137], v[134:135], 0, s[26:27]
	global_load_dwordx4 v[130:133], v[136:137], off
	v_lshl_add_u64 v[186:187], v[134:135], 0, s[70:71]
	global_load_dwordx4 v[134:137], v[186:187], off
	ds_read_b128 v[186:189], v179
	ds_read_b128 v[190:193], v184 offset:27648
	ds_read_b128 v[194:197], v179 offset:4608
	ds_read_b128 v[198:201], v184 offset:32256
	ds_read_b128 v[202:205], v179 offset:9216
	ds_read_b128 v[206:209], v179 offset:32
	ds_read_b128 v[210:213], v184 offset:27680
	ds_read_b128 v[214:217], v179 offset:4640
	ds_read_b128 v[218:221], v184 offset:32288
	ds_read_b128 v[222:225], v179 offset:9248
	s_waitcnt lgkmcnt(5)
	v_mfma_f32_32x32x16_bf16 v[80:95], v[186:189], v[190:193], v[80:95]
	v_mfma_f32_32x32x16_bf16 v[64:79], v[186:189], v[198:201], v[64:79]
	v_mfma_f32_32x32x16_bf16 v[48:63], v[194:197], v[190:193], v[48:63]
	v_mfma_f32_32x32x16_bf16 v[32:47], v[194:197], v[198:201], v[32:47]
	v_mfma_f32_32x32x16_bf16 v[16:31], v[202:205], v[190:193], v[16:31]
	v_mfma_f32_32x32x16_bf16 v[0:15], v[202:205], v[198:201], v[0:15]
	ds_read_b128 v[186:189], v179 offset:64
	ds_read_b128 v[190:193], v184 offset:27712
	ds_read_b128 v[194:197], v179 offset:4672
	ds_read_b128 v[198:201], v184 offset:32320
	ds_read_b128 v[202:205], v179 offset:9280
	s_waitcnt lgkmcnt(5)
	v_mfma_f32_32x32x16_bf16 v[80:95], v[206:209], v[210:213], v[80:95]
	v_mfma_f32_32x32x16_bf16 v[64:79], v[206:209], v[218:221], v[64:79]
	v_mfma_f32_32x32x16_bf16 v[48:63], v[214:217], v[210:213], v[48:63]
	v_mfma_f32_32x32x16_bf16 v[32:47], v[214:217], v[218:221], v[32:47]
	v_mfma_f32_32x32x16_bf16 v[16:31], v[222:225], v[210:213], v[16:31]
	v_mfma_f32_32x32x16_bf16 v[0:15], v[222:225], v[218:221], v[0:15]
	ds_read_b128 v[206:209], v179 offset:96
	ds_read_b128 v[210:213], v184 offset:27744
	ds_read_b128 v[214:217], v179 offset:4704
	ds_read_b128 v[218:221], v184 offset:32352
	ds_read_b128 v[222:225], v179 offset:9312
	s_waitcnt lgkmcnt(0)
	s_waitcnt vmcnt(10)
	s_barrier
	v_mfma_f32_32x32x16_bf16 v[80:95], v[186:189], v[190:193], v[80:95]
	ds_write_b128 v97, v[138:141]
	ds_write_b128 v97, v[142:145] offset:4608
	v_mfma_f32_32x32x16_bf16 v[64:79], v[186:189], v[198:201], v[64:79]
	ds_write_b128 v97, v[146:149] offset:9216
	ds_write_b128 v97, v[150:153] offset:13824
	v_mfma_f32_32x32x16_bf16 v[48:63], v[194:197], v[190:193], v[48:63]
	ds_write_b128 v97, v[154:157] offset:18432
	ds_write_b128 v97, v[158:161] offset:23040
	v_mfma_f32_32x32x16_bf16 v[32:47], v[194:197], v[198:201], v[32:47]
	ds_write_b128 v97, v[162:165] offset:27648
	ds_write_b128 v97, v[166:169] offset:32256
	v_mfma_f32_32x32x16_bf16 v[16:31], v[202:205], v[190:193], v[16:31]
	ds_write_b128 v97, v[170:173] offset:36864
	ds_write_b128 v97, v[174:177] offset:41472
	v_mfma_f32_32x32x16_bf16 v[0:15], v[202:205], v[198:201], v[0:15]
	v_mfma_f32_32x32x16_bf16 v[80:95], v[206:209], v[210:213], v[80:95]
	v_mfma_f32_32x32x16_bf16 v[64:79], v[206:209], v[218:221], v[64:79]
	v_mfma_f32_32x32x16_bf16 v[48:63], v[214:217], v[210:213], v[48:63]
	v_mfma_f32_32x32x16_bf16 v[32:47], v[214:217], v[218:221], v[32:47]
	v_mfma_f32_32x32x16_bf16 v[16:31], v[222:225], v[210:213], v[16:31]
	v_mfma_f32_32x32x16_bf16 v[0:15], v[222:225], v[218:221], v[0:15]
	s_waitcnt lgkmcnt(0)
	s_barrier
	s_cbranch_vccnz .LBB0_780
	s_waitcnt vmcnt(0)
	s_lshl_b64 s[4:5], s[4:5], 1
	s_add_u32 s4, s39, s4
	s_addc_u32 s5, s42, s5
	s_add_u32 s4, s4, s6
	s_addc_u32 s5, s5, s7
	v_and_b32_e32 v97, 0x5f, v244
	v_lshrrev_b32_e32 v98, 7, v244
	v_mul_u32_u24_e32 v98, 0x60, v98
	v_lshrrev_b32_e32 v99, 3, v244
	v_and_or_b32 v98, v99, 4, v98
	v_lshl_or_b32 v99, v98, 10, v97
	v_lshlrev_b32_e32 v99, 1, v99
	s_mov_b64 s[12:13], s[0:1]
	global_load_ushort v100, v99, s[12:13]
	s_add_u32 s12, s12, 0x800
	s_addc_u32 s13, s13, 0
	global_load_ushort v101, v99, s[12:13]
	s_add_u32 s12, s12, 0x800
	s_addc_u32 s13, s13, 0
	global_load_ushort v102, v99, s[12:13]
	s_add_u32 s12, s12, 0x800
	s_addc_u32 s13, s13, 0
	global_load_ushort v103, v99, s[12:13]
	s_add_u32 s12, s12, 0x2800
	s_addc_u32 s13, s13, 0
	global_load_ushort v104, v99, s[12:13]
	s_add_u32 s12, s12, 0x800
	s_addc_u32 s13, s13, 0
	global_load_ushort v105, v99, s[12:13]
	s_add_u32 s12, s12, 0x800
	s_addc_u32 s13, s13, 0
	global_load_ushort v106, v99, s[12:13]
	s_add_u32 s12, s12, 0x800
	s_addc_u32 s13, s13, 0
	global_load_ushort v107, v99, s[12:13]
	s_add_u32 s12, s12, 0x2800
	s_addc_u32 s13, s13, 0
	global_load_ushort v108, v99, s[12:13]
	s_add_u32 s12, s12, 0x800
	s_addc_u32 s13, s13, 0
	global_load_ushort v109, v99, s[12:13]
	s_add_u32 s12, s12, 0x800
	s_addc_u32 s13, s13, 0
	global_load_ushort v110, v99, s[12:13]
	s_add_u32 s12, s12, 0x800
	s_addc_u32 s13, s13, 0
	global_load_ushort v111, v99, s[12:13]
	s_add_u32 s12, s12, 0x2800
	s_addc_u32 s13, s13, 0
	global_load_ushort v112, v99, s[12:13]
	s_add_u32 s12, s12, 0x800
	s_addc_u32 s13, s13, 0
	global_load_ushort v113, v99, s[12:13]
	s_add_u32 s12, s12, 0x800
	s_addc_u32 s13, s13, 0
	global_load_ushort v114, v99, s[12:13]
	s_add_u32 s12, s12, 0x800
	s_addc_u32 s13, s13, 0
	global_load_ushort v115, v99, s[12:13]
	s_mov_b64 s[50:51], s[4:5]
	global_load_ushort v116, v99, s[50:51]
	s_add_u32 s50, s50, 0x800
	s_addc_u32 s51, s51, 0
	global_load_ushort v117, v99, s[50:51]
	s_add_u32 s50, s50, 0x800
	s_addc_u32 s51, s51, 0
	global_load_ushort v118, v99, s[50:51]
	s_add_u32 s50, s50, 0x800
	s_addc_u32 s51, s51, 0
	global_load_ushort v119, v99, s[50:51]
	s_add_u32 s50, s50, 0x2800
	s_addc_u32 s51, s51, 0
	global_load_ushort v120, v99, s[50:51]
	s_add_u32 s50, s50, 0x800
	s_addc_u32 s51, s51, 0
	global_load_ushort v121, v99, s[50:51]
	s_add_u32 s50, s50, 0x800
	s_addc_u32 s51, s51, 0
	global_load_ushort v122, v99, s[50:51]
	s_add_u32 s50, s50, 0x800
	s_addc_u32 s51, s51, 0
	global_load_ushort v123, v99, s[50:51]
	s_add_u32 s50, s50, 0x2800
	s_addc_u32 s51, s51, 0
	global_load_ushort v124, v99, s[50:51]
	s_add_u32 s50, s50, 0x800
	s_addc_u32 s51, s51, 0
	global_load_ushort v125, v99, s[50:51]
	s_add_u32 s50, s50, 0x800
	s_addc_u32 s51, s51, 0
	global_load_ushort v126, v99, s[50:51]
	s_add_u32 s50, s50, 0x800
	s_addc_u32 s51, s51, 0
	global_load_ushort v127, v99, s[50:51]
	s_add_u32 s50, s50, 0x2800
	s_addc_u32 s51, s51, 0
	global_load_ushort v128, v99, s[50:51]
	s_add_u32 s50, s50, 0x800
	s_addc_u32 s51, s51, 0
	global_load_ushort v129, v99, s[50:51]
	s_add_u32 s50, s50, 0x800
	s_addc_u32 s51, s51, 0
	global_load_ushort v130, v99, s[50:51]
	s_add_u32 s50, s50, 0x800
	s_addc_u32 s51, s51, 0
	global_load_ushort v131, v99, s[50:51]
	s_waitcnt vmcnt(0)
	v_lshlrev_b32_e32 v100, 16, v100
	v_lshlrev_b32_e32 v116, 16, v116
	v_fmac_f32_e32 v100, v80, v116
	v_cvt_pk_bf16_f32 v100, v100, v100
	v_lshlrev_b32_e32 v101, 16, v101
	v_lshlrev_b32_e32 v117, 16, v117
	v_fmac_f32_e32 v101, v81, v117
	v_cvt_pk_bf16_f32 v101, v101, v101
	v_lshlrev_b32_e32 v102, 16, v102
	v_lshlrev_b32_e32 v118, 16, v118
	v_fmac_f32_e32 v102, v82, v118
	v_cvt_pk_bf16_f32 v102, v102, v102
	v_lshlrev_b32_e32 v103, 16, v103
	v_lshlrev_b32_e32 v119, 16, v119
	v_fmac_f32_e32 v103, v83, v119
	v_cvt_pk_bf16_f32 v103, v103, v103
	v_lshlrev_b32_e32 v104, 16, v104
	v_lshlrev_b32_e32 v120, 16, v120
	v_fmac_f32_e32 v104, v84, v120
	v_cvt_pk_bf16_f32 v104, v104, v104
	v_lshlrev_b32_e32 v105, 16, v105
	v_lshlrev_b32_e32 v121, 16, v121
	v_fmac_f32_e32 v105, v85, v121
	v_cvt_pk_bf16_f32 v105, v105, v105
	v_lshlrev_b32_e32 v106, 16, v106
	v_lshlrev_b32_e32 v122, 16, v122
	v_fmac_f32_e32 v106, v86, v122
	v_cvt_pk_bf16_f32 v106, v106, v106
	v_lshlrev_b32_e32 v107, 16, v107
	v_lshlrev_b32_e32 v123, 16, v123
	v_fmac_f32_e32 v107, v87, v123
	v_cvt_pk_bf16_f32 v107, v107, v107
	v_lshlrev_b32_e32 v108, 16, v108
	v_lshlrev_b32_e32 v124, 16, v124
	v_fmac_f32_e32 v108, v88, v124
	v_cvt_pk_bf16_f32 v108, v108, v108
	v_lshlrev_b32_e32 v109, 16, v109
	v_lshlrev_b32_e32 v125, 16, v125
	v_fmac_f32_e32 v109, v89, v125
	v_cvt_pk_bf16_f32 v109, v109, v109
	v_lshlrev_b32_e32 v110, 16, v110
	v_lshlrev_b32_e32 v126, 16, v126
	v_fmac_f32_e32 v110, v90, v126
	v_cvt_pk_bf16_f32 v110, v110, v110
	v_lshlrev_b32_e32 v111, 16, v111
	v_lshlrev_b32_e32 v127, 16, v127
	v_fmac_f32_e32 v111, v91, v127
	v_cvt_pk_bf16_f32 v111, v111, v111
	v_lshlrev_b32_e32 v112, 16, v112
	v_lshlrev_b32_e32 v128, 16, v128
	v_fmac_f32_e32 v112, v92, v128
	v_cvt_pk_bf16_f32 v112, v112, v112
	v_lshlrev_b32_e32 v113, 16, v113
	v_lshlrev_b32_e32 v129, 16, v129
	v_fmac_f32_e32 v113, v93, v129
	v_cvt_pk_bf16_f32 v113, v113, v113
	v_lshlrev_b32_e32 v114, 16, v114
	v_lshlrev_b32_e32 v130, 16, v130
	v_fmac_f32_e32 v114, v94, v130
	v_cvt_pk_bf16_f32 v114, v114, v114
	v_lshlrev_b32_e32 v115, 16, v115
	v_lshlrev_b32_e32 v131, 16, v131
	v_fmac_f32_e32 v115, v95, v131
	v_cvt_pk_bf16_f32 v115, v115, v115
	s_mov_b64 s[52:53], s[0:1]
	global_store_short v99, v100, s[52:53]
	s_add_u32 s52, s52, 0x800
	s_addc_u32 s53, s53, 0
	global_store_short v99, v101, s[52:53]
	s_add_u32 s52, s52, 0x800
	s_addc_u32 s53, s53, 0
	global_store_short v99, v102, s[52:53]
	s_add_u32 s52, s52, 0x800
	s_addc_u32 s53, s53, 0
	global_store_short v99, v103, s[52:53]
	s_add_u32 s52, s52, 0x2800
	s_addc_u32 s53, s53, 0
	global_store_short v99, v104, s[52:53]
	s_add_u32 s52, s52, 0x800
	s_addc_u32 s53, s53, 0
	global_store_short v99, v105, s[52:53]
	s_add_u32 s52, s52, 0x800
	s_addc_u32 s53, s53, 0
	global_store_short v99, v106, s[52:53]
	s_add_u32 s52, s52, 0x800
	s_addc_u32 s53, s53, 0
	global_store_short v99, v107, s[52:53]
	s_add_u32 s52, s52, 0x2800
	s_addc_u32 s53, s53, 0
	global_store_short v99, v108, s[52:53]
	s_add_u32 s52, s52, 0x800
	s_addc_u32 s53, s53, 0
	global_store_short v99, v109, s[52:53]
	s_add_u32 s52, s52, 0x800
	s_addc_u32 s53, s53, 0
	global_store_short v99, v110, s[52:53]
	s_add_u32 s52, s52, 0x800
	s_addc_u32 s53, s53, 0
	global_store_short v99, v111, s[52:53]
	s_add_u32 s52, s52, 0x2800
	s_addc_u32 s53, s53, 0
	global_store_short v99, v112, s[52:53]
	s_add_u32 s52, s52, 0x800
	s_addc_u32 s53, s53, 0
	global_store_short v99, v113, s[52:53]
	s_add_u32 s52, s52, 0x800
	s_addc_u32 s53, s53, 0
	global_store_short v99, v114, s[52:53]
	s_add_u32 s52, s52, 0x800
	s_addc_u32 s53, s53, 0
	global_store_short v99, v115, s[52:53]
	s_mov_b64 s[12:13], s[0:1]
	s_add_u32 s12, s12, 0x10000
	s_addc_u32 s13, s13, 0
	global_load_ushort v100, v99, s[12:13]
	s_add_u32 s12, s12, 0x800
	s_addc_u32 s13, s13, 0
	global_load_ushort v101, v99, s[12:13]
	s_add_u32 s12, s12, 0x800
	s_addc_u32 s13, s13, 0
	global_load_ushort v102, v99, s[12:13]
	s_add_u32 s12, s12, 0x800
	s_addc_u32 s13, s13, 0
	global_load_ushort v103, v99, s[12:13]
	s_add_u32 s12, s12, 0x2800
	s_addc_u32 s13, s13, 0
	global_load_ushort v104, v99, s[12:13]
	s_add_u32 s12, s12, 0x800
	s_addc_u32 s13, s13, 0
	global_load_ushort v105, v99, s[12:13]
	s_add_u32 s12, s12, 0x800
	s_addc_u32 s13, s13, 0
	global_load_ushort v106, v99, s[12:13]
	s_add_u32 s12, s12, 0x800
	s_addc_u32 s13, s13, 0
	global_load_ushort v107, v99, s[12:13]
	s_add_u32 s12, s12, 0x2800
	s_addc_u32 s13, s13, 0
	global_load_ushort v108, v99, s[12:13]
	s_add_u32 s12, s12, 0x800
	s_addc_u32 s13, s13, 0
	global_load_ushort v109, v99, s[12:13]
	s_add_u32 s12, s12, 0x800
	s_addc_u32 s13, s13, 0
	global_load_ushort v110, v99, s[12:13]
	s_add_u32 s12, s12, 0x800
	s_addc_u32 s13, s13, 0
	global_load_ushort v111, v99, s[12:13]
	s_add_u32 s12, s12, 0x2800
	s_addc_u32 s13, s13, 0
	global_load_ushort v112, v99, s[12:13]
	s_add_u32 s12, s12, 0x800
	s_addc_u32 s13, s13, 0
	global_load_ushort v113, v99, s[12:13]
	s_add_u32 s12, s12, 0x800
	s_addc_u32 s13, s13, 0
	global_load_ushort v114, v99, s[12:13]
	s_add_u32 s12, s12, 0x800
	s_addc_u32 s13, s13, 0
	global_load_ushort v115, v99, s[12:13]
	s_mov_b64 s[50:51], s[4:5]
	s_add_u32 s50, s50, 0x10000
	s_addc_u32 s51, s51, 0
	global_load_ushort v116, v99, s[50:51]
	s_add_u32 s50, s50, 0x800
	s_addc_u32 s51, s51, 0
	global_load_ushort v117, v99, s[50:51]
	s_add_u32 s50, s50, 0x800
	s_addc_u32 s51, s51, 0
	global_load_ushort v118, v99, s[50:51]
	s_add_u32 s50, s50, 0x800
	s_addc_u32 s51, s51, 0
	global_load_ushort v119, v99, s[50:51]
	s_add_u32 s50, s50, 0x2800
	s_addc_u32 s51, s51, 0
	global_load_ushort v120, v99, s[50:51]
	s_add_u32 s50, s50, 0x800
	s_addc_u32 s51, s51, 0
	global_load_ushort v121, v99, s[50:51]
	s_add_u32 s50, s50, 0x800
	s_addc_u32 s51, s51, 0
	global_load_ushort v122, v99, s[50:51]
	s_add_u32 s50, s50, 0x800
	s_addc_u32 s51, s51, 0
	global_load_ushort v123, v99, s[50:51]
	s_add_u32 s50, s50, 0x2800
	s_addc_u32 s51, s51, 0
	global_load_ushort v124, v99, s[50:51]
	s_add_u32 s50, s50, 0x800
	s_addc_u32 s51, s51, 0
	global_load_ushort v125, v99, s[50:51]
	s_add_u32 s50, s50, 0x800
	s_addc_u32 s51, s51, 0
	global_load_ushort v126, v99, s[50:51]
	s_add_u32 s50, s50, 0x800
	s_addc_u32 s51, s51, 0
	global_load_ushort v127, v99, s[50:51]
	s_add_u32 s50, s50, 0x2800
	s_addc_u32 s51, s51, 0
	global_load_ushort v128, v99, s[50:51]
	s_add_u32 s50, s50, 0x800
	s_addc_u32 s51, s51, 0
	global_load_ushort v129, v99, s[50:51]
	s_add_u32 s50, s50, 0x800
	s_addc_u32 s51, s51, 0
	global_load_ushort v130, v99, s[50:51]
	s_add_u32 s50, s50, 0x800
	s_addc_u32 s51, s51, 0
	global_load_ushort v131, v99, s[50:51]
	s_waitcnt vmcnt(0)
	v_lshlrev_b32_e32 v100, 16, v100
	v_lshlrev_b32_e32 v116, 16, v116
	v_fmac_f32_e32 v100, v48, v116
	v_cvt_pk_bf16_f32 v100, v100, v100
	v_lshlrev_b32_e32 v101, 16, v101
	v_lshlrev_b32_e32 v117, 16, v117
	v_fmac_f32_e32 v101, v49, v117
	v_cvt_pk_bf16_f32 v101, v101, v101
	v_lshlrev_b32_e32 v102, 16, v102
	v_lshlrev_b32_e32 v118, 16, v118
	v_fmac_f32_e32 v102, v50, v118
	v_cvt_pk_bf16_f32 v102, v102, v102
	v_lshlrev_b32_e32 v103, 16, v103
	v_lshlrev_b32_e32 v119, 16, v119
	v_fmac_f32_e32 v103, v51, v119
	v_cvt_pk_bf16_f32 v103, v103, v103
	v_lshlrev_b32_e32 v104, 16, v104
	v_lshlrev_b32_e32 v120, 16, v120
	v_fmac_f32_e32 v104, v52, v120
	v_cvt_pk_bf16_f32 v104, v104, v104
	v_lshlrev_b32_e32 v105, 16, v105
	v_lshlrev_b32_e32 v121, 16, v121
	v_fmac_f32_e32 v105, v53, v121
	v_cvt_pk_bf16_f32 v105, v105, v105
	v_lshlrev_b32_e32 v106, 16, v106
	v_lshlrev_b32_e32 v122, 16, v122
	v_fmac_f32_e32 v106, v54, v122
	v_cvt_pk_bf16_f32 v106, v106, v106
	v_lshlrev_b32_e32 v107, 16, v107
	v_lshlrev_b32_e32 v123, 16, v123
	v_fmac_f32_e32 v107, v55, v123
	v_cvt_pk_bf16_f32 v107, v107, v107
	v_lshlrev_b32_e32 v108, 16, v108
	v_lshlrev_b32_e32 v124, 16, v124
	v_fmac_f32_e32 v108, v56, v124
	v_cvt_pk_bf16_f32 v108, v108, v108
	v_lshlrev_b32_e32 v109, 16, v109
	v_lshlrev_b32_e32 v125, 16, v125
	v_fmac_f32_e32 v109, v57, v125
	v_cvt_pk_bf16_f32 v109, v109, v109
	v_lshlrev_b32_e32 v110, 16, v110
	v_lshlrev_b32_e32 v126, 16, v126
	v_fmac_f32_e32 v110, v58, v126
	v_cvt_pk_bf16_f32 v110, v110, v110
	v_lshlrev_b32_e32 v111, 16, v111
	v_lshlrev_b32_e32 v127, 16, v127
	v_fmac_f32_e32 v111, v59, v127
	v_cvt_pk_bf16_f32 v111, v111, v111
	v_lshlrev_b32_e32 v112, 16, v112
	v_lshlrev_b32_e32 v128, 16, v128
	v_fmac_f32_e32 v112, v60, v128
	v_cvt_pk_bf16_f32 v112, v112, v112
	v_lshlrev_b32_e32 v113, 16, v113
	v_lshlrev_b32_e32 v129, 16, v129
	v_fmac_f32_e32 v113, v61, v129
	v_cvt_pk_bf16_f32 v113, v113, v113
	v_lshlrev_b32_e32 v114, 16, v114
	v_lshlrev_b32_e32 v130, 16, v130
	v_fmac_f32_e32 v114, v62, v130
	v_cvt_pk_bf16_f32 v114, v114, v114
	v_lshlrev_b32_e32 v115, 16, v115
	v_lshlrev_b32_e32 v131, 16, v131
	v_fmac_f32_e32 v115, v63, v131
	v_cvt_pk_bf16_f32 v115, v115, v115
	s_mov_b64 s[52:53], s[0:1]
	s_add_u32 s52, s52, 0x10000
	s_addc_u32 s53, s53, 0
	global_store_short v99, v100, s[52:53]
	s_add_u32 s52, s52, 0x800
	s_addc_u32 s53, s53, 0
	global_store_short v99, v101, s[52:53]
	s_add_u32 s52, s52, 0x800
	s_addc_u32 s53, s53, 0
	global_store_short v99, v102, s[52:53]
	s_add_u32 s52, s52, 0x800
	s_addc_u32 s53, s53, 0
	global_store_short v99, v103, s[52:53]
	s_add_u32 s52, s52, 0x2800
	s_addc_u32 s53, s53, 0
	global_store_short v99, v104, s[52:53]
	s_add_u32 s52, s52, 0x800
	s_addc_u32 s53, s53, 0
	global_store_short v99, v105, s[52:53]
	s_add_u32 s52, s52, 0x800
	s_addc_u32 s53, s53, 0
	global_store_short v99, v106, s[52:53]
	s_add_u32 s52, s52, 0x800
	s_addc_u32 s53, s53, 0
	global_store_short v99, v107, s[52:53]
	s_add_u32 s52, s52, 0x2800
	s_addc_u32 s53, s53, 0
	global_store_short v99, v108, s[52:53]
	s_add_u32 s52, s52, 0x800
	s_addc_u32 s53, s53, 0
	global_store_short v99, v109, s[52:53]
	s_add_u32 s52, s52, 0x800
	s_addc_u32 s53, s53, 0
	global_store_short v99, v110, s[52:53]
	s_add_u32 s52, s52, 0x800
	s_addc_u32 s53, s53, 0
	global_store_short v99, v111, s[52:53]
	s_add_u32 s52, s52, 0x2800
	s_addc_u32 s53, s53, 0
	global_store_short v99, v112, s[52:53]
	s_add_u32 s52, s52, 0x800
	s_addc_u32 s53, s53, 0
	global_store_short v99, v113, s[52:53]
	s_add_u32 s52, s52, 0x800
	s_addc_u32 s53, s53, 0
	global_store_short v99, v114, s[52:53]
	s_add_u32 s52, s52, 0x800
	s_addc_u32 s53, s53, 0
	global_store_short v99, v115, s[52:53]
	s_mov_b64 s[12:13], s[0:1]
	s_add_u32 s12, s12, 0x20000
	s_addc_u32 s13, s13, 0
	global_load_ushort v100, v99, s[12:13]
	s_add_u32 s12, s12, 0x800
	s_addc_u32 s13, s13, 0
	global_load_ushort v101, v99, s[12:13]
	s_add_u32 s12, s12, 0x800
	s_addc_u32 s13, s13, 0
	global_load_ushort v102, v99, s[12:13]
	s_add_u32 s12, s12, 0x800
	s_addc_u32 s13, s13, 0
	global_load_ushort v103, v99, s[12:13]
	s_add_u32 s12, s12, 0x2800
	s_addc_u32 s13, s13, 0
	global_load_ushort v104, v99, s[12:13]
	s_add_u32 s12, s12, 0x800
	s_addc_u32 s13, s13, 0
	global_load_ushort v105, v99, s[12:13]
	s_add_u32 s12, s12, 0x800
	s_addc_u32 s13, s13, 0
	global_load_ushort v106, v99, s[12:13]
	s_add_u32 s12, s12, 0x800
	s_addc_u32 s13, s13, 0
	global_load_ushort v107, v99, s[12:13]
	s_add_u32 s12, s12, 0x2800
	s_addc_u32 s13, s13, 0
	global_load_ushort v108, v99, s[12:13]
	s_add_u32 s12, s12, 0x800
	s_addc_u32 s13, s13, 0
	global_load_ushort v109, v99, s[12:13]
	s_add_u32 s12, s12, 0x800
	s_addc_u32 s13, s13, 0
	global_load_ushort v110, v99, s[12:13]
	s_add_u32 s12, s12, 0x800
	s_addc_u32 s13, s13, 0
	global_load_ushort v111, v99, s[12:13]
	s_add_u32 s12, s12, 0x2800
	s_addc_u32 s13, s13, 0
	global_load_ushort v112, v99, s[12:13]
	s_add_u32 s12, s12, 0x800
	s_addc_u32 s13, s13, 0
	global_load_ushort v113, v99, s[12:13]
	s_add_u32 s12, s12, 0x800
	s_addc_u32 s13, s13, 0
	global_load_ushort v114, v99, s[12:13]
	s_add_u32 s12, s12, 0x800
	s_addc_u32 s13, s13, 0
	global_load_ushort v115, v99, s[12:13]
	s_mov_b64 s[50:51], s[4:5]
	s_add_u32 s50, s50, 0x20000
	s_addc_u32 s51, s51, 0
	global_load_ushort v116, v99, s[50:51]
	s_add_u32 s50, s50, 0x800
	s_addc_u32 s51, s51, 0
	global_load_ushort v117, v99, s[50:51]
	s_add_u32 s50, s50, 0x800
	s_addc_u32 s51, s51, 0
	global_load_ushort v118, v99, s[50:51]
	s_add_u32 s50, s50, 0x800
	s_addc_u32 s51, s51, 0
	global_load_ushort v119, v99, s[50:51]
	s_add_u32 s50, s50, 0x2800
	s_addc_u32 s51, s51, 0
	global_load_ushort v120, v99, s[50:51]
	s_add_u32 s50, s50, 0x800
	s_addc_u32 s51, s51, 0
	global_load_ushort v121, v99, s[50:51]
	s_add_u32 s50, s50, 0x800
	s_addc_u32 s51, s51, 0
	global_load_ushort v122, v99, s[50:51]
	s_add_u32 s50, s50, 0x800
	s_addc_u32 s51, s51, 0
	global_load_ushort v123, v99, s[50:51]
	s_add_u32 s50, s50, 0x2800
	s_addc_u32 s51, s51, 0
	global_load_ushort v124, v99, s[50:51]
	s_add_u32 s50, s50, 0x800
	s_addc_u32 s51, s51, 0
	global_load_ushort v125, v99, s[50:51]
	s_add_u32 s50, s50, 0x800
	s_addc_u32 s51, s51, 0
	global_load_ushort v126, v99, s[50:51]
	s_add_u32 s50, s50, 0x800
	s_addc_u32 s51, s51, 0
	global_load_ushort v127, v99, s[50:51]
	s_add_u32 s50, s50, 0x2800
	s_addc_u32 s51, s51, 0
	global_load_ushort v128, v99, s[50:51]
	s_add_u32 s50, s50, 0x800
	s_addc_u32 s51, s51, 0
	global_load_ushort v129, v99, s[50:51]
	s_add_u32 s50, s50, 0x800
	s_addc_u32 s51, s51, 0
	global_load_ushort v130, v99, s[50:51]
	s_add_u32 s50, s50, 0x800
	s_addc_u32 s51, s51, 0
	global_load_ushort v131, v99, s[50:51]
	s_waitcnt vmcnt(0)
	v_lshlrev_b32_e32 v100, 16, v100
	v_lshlrev_b32_e32 v116, 16, v116
	v_fmac_f32_e32 v100, v16, v116
	v_cvt_pk_bf16_f32 v100, v100, v100
	v_lshlrev_b32_e32 v101, 16, v101
	v_lshlrev_b32_e32 v117, 16, v117
	v_fmac_f32_e32 v101, v17, v117
	v_cvt_pk_bf16_f32 v101, v101, v101
	v_lshlrev_b32_e32 v102, 16, v102
	v_lshlrev_b32_e32 v118, 16, v118
	v_fmac_f32_e32 v102, v18, v118
	v_cvt_pk_bf16_f32 v102, v102, v102
	v_lshlrev_b32_e32 v103, 16, v103
	v_lshlrev_b32_e32 v119, 16, v119
	v_fmac_f32_e32 v103, v19, v119
	v_cvt_pk_bf16_f32 v103, v103, v103
	v_lshlrev_b32_e32 v104, 16, v104
	v_lshlrev_b32_e32 v120, 16, v120
	v_fmac_f32_e32 v104, v20, v120
	v_cvt_pk_bf16_f32 v104, v104, v104
	v_lshlrev_b32_e32 v105, 16, v105
	v_lshlrev_b32_e32 v121, 16, v121
	v_fmac_f32_e32 v105, v21, v121
	v_cvt_pk_bf16_f32 v105, v105, v105
	v_lshlrev_b32_e32 v106, 16, v106
	v_lshlrev_b32_e32 v122, 16, v122
	v_fmac_f32_e32 v106, v22, v122
	v_cvt_pk_bf16_f32 v106, v106, v106
	v_lshlrev_b32_e32 v107, 16, v107
	v_lshlrev_b32_e32 v123, 16, v123
	v_fmac_f32_e32 v107, v23, v123
	v_cvt_pk_bf16_f32 v107, v107, v107
	v_lshlrev_b32_e32 v108, 16, v108
	v_lshlrev_b32_e32 v124, 16, v124
	v_fmac_f32_e32 v108, v24, v124
	v_cvt_pk_bf16_f32 v108, v108, v108
	v_lshlrev_b32_e32 v109, 16, v109
	v_lshlrev_b32_e32 v125, 16, v125
	v_fmac_f32_e32 v109, v25, v125
	v_cvt_pk_bf16_f32 v109, v109, v109
	v_lshlrev_b32_e32 v110, 16, v110
	v_lshlrev_b32_e32 v126, 16, v126
	v_fmac_f32_e32 v110, v26, v126
	v_cvt_pk_bf16_f32 v110, v110, v110
	v_lshlrev_b32_e32 v111, 16, v111
	v_lshlrev_b32_e32 v127, 16, v127
	v_fmac_f32_e32 v111, v27, v127
	v_cvt_pk_bf16_f32 v111, v111, v111
	v_lshlrev_b32_e32 v112, 16, v112
	v_lshlrev_b32_e32 v128, 16, v128
	v_fmac_f32_e32 v112, v28, v128
	v_cvt_pk_bf16_f32 v112, v112, v112
	v_lshlrev_b32_e32 v113, 16, v113
	v_lshlrev_b32_e32 v129, 16, v129
	v_fmac_f32_e32 v113, v29, v129
	v_cvt_pk_bf16_f32 v113, v113, v113
	v_lshlrev_b32_e32 v114, 16, v114
	v_lshlrev_b32_e32 v130, 16, v130
	v_fmac_f32_e32 v114, v30, v130
	v_cvt_pk_bf16_f32 v114, v114, v114
	v_lshlrev_b32_e32 v115, 16, v115
	v_lshlrev_b32_e32 v131, 16, v131
	v_fmac_f32_e32 v115, v31, v131
	v_cvt_pk_bf16_f32 v115, v115, v115
	s_mov_b64 s[52:53], s[0:1]
	s_add_u32 s52, s52, 0x20000
	s_addc_u32 s53, s53, 0
	global_store_short v99, v100, s[52:53]
	s_add_u32 s52, s52, 0x800
	s_addc_u32 s53, s53, 0
	global_store_short v99, v101, s[52:53]
	s_add_u32 s52, s52, 0x800
	s_addc_u32 s53, s53, 0
	global_store_short v99, v102, s[52:53]
	s_add_u32 s52, s52, 0x800
	s_addc_u32 s53, s53, 0
	global_store_short v99, v103, s[52:53]
	s_add_u32 s52, s52, 0x2800
	s_addc_u32 s53, s53, 0
	global_store_short v99, v104, s[52:53]
	s_add_u32 s52, s52, 0x800
	s_addc_u32 s53, s53, 0
	global_store_short v99, v105, s[52:53]
	s_add_u32 s52, s52, 0x800
	s_addc_u32 s53, s53, 0
	global_store_short v99, v106, s[52:53]
	s_add_u32 s52, s52, 0x800
	s_addc_u32 s53, s53, 0
	global_store_short v99, v107, s[52:53]
	s_add_u32 s52, s52, 0x2800
	s_addc_u32 s53, s53, 0
	global_store_short v99, v108, s[52:53]
	s_add_u32 s52, s52, 0x800
	s_addc_u32 s53, s53, 0
	global_store_short v99, v109, s[52:53]
	s_add_u32 s52, s52, 0x800
	s_addc_u32 s53, s53, 0
	global_store_short v99, v110, s[52:53]
	s_add_u32 s52, s52, 0x800
	s_addc_u32 s53, s53, 0
	global_store_short v99, v111, s[52:53]
	s_add_u32 s52, s52, 0x2800
	s_addc_u32 s53, s53, 0
	global_store_short v99, v112, s[52:53]
	s_add_u32 s52, s52, 0x800
	s_addc_u32 s53, s53, 0
	global_store_short v99, v113, s[52:53]
	s_add_u32 s52, s52, 0x800
	s_addc_u32 s53, s53, 0
	global_store_short v99, v114, s[52:53]
	s_add_u32 s52, s52, 0x800
	s_addc_u32 s53, s53, 0
	global_store_short v99, v115, s[52:53]
	s_mov_b64 s[12:13], s[0:1]
	global_load_ushort v100, v99, s[12:13] offset:64
	s_add_u32 s12, s12, 0x800
	s_addc_u32 s13, s13, 0
	global_load_ushort v101, v99, s[12:13] offset:64
	s_add_u32 s12, s12, 0x800
	s_addc_u32 s13, s13, 0
	global_load_ushort v102, v99, s[12:13] offset:64
	s_add_u32 s12, s12, 0x800
	s_addc_u32 s13, s13, 0
	global_load_ushort v103, v99, s[12:13] offset:64
	s_add_u32 s12, s12, 0x2800
	s_addc_u32 s13, s13, 0
	global_load_ushort v104, v99, s[12:13] offset:64
	s_add_u32 s12, s12, 0x800
	s_addc_u32 s13, s13, 0
	global_load_ushort v105, v99, s[12:13] offset:64
	s_add_u32 s12, s12, 0x800
	s_addc_u32 s13, s13, 0
	global_load_ushort v106, v99, s[12:13] offset:64
	s_add_u32 s12, s12, 0x800
	s_addc_u32 s13, s13, 0
	global_load_ushort v107, v99, s[12:13] offset:64
	s_add_u32 s12, s12, 0x2800
	s_addc_u32 s13, s13, 0
	global_load_ushort v108, v99, s[12:13] offset:64
	s_add_u32 s12, s12, 0x800
	s_addc_u32 s13, s13, 0
	global_load_ushort v109, v99, s[12:13] offset:64
	s_add_u32 s12, s12, 0x800
	s_addc_u32 s13, s13, 0
	global_load_ushort v110, v99, s[12:13] offset:64
	s_add_u32 s12, s12, 0x800
	s_addc_u32 s13, s13, 0
	global_load_ushort v111, v99, s[12:13] offset:64
	s_add_u32 s12, s12, 0x2800
	s_addc_u32 s13, s13, 0
	global_load_ushort v112, v99, s[12:13] offset:64
	s_add_u32 s12, s12, 0x800
	s_addc_u32 s13, s13, 0
	global_load_ushort v113, v99, s[12:13] offset:64
	s_add_u32 s12, s12, 0x800
	s_addc_u32 s13, s13, 0
	global_load_ushort v114, v99, s[12:13] offset:64
	s_add_u32 s12, s12, 0x800
	s_addc_u32 s13, s13, 0
	global_load_ushort v115, v99, s[12:13] offset:64
	s_mov_b64 s[50:51], s[4:5]
	global_load_ushort v116, v99, s[50:51] offset:64
	s_add_u32 s50, s50, 0x800
	s_addc_u32 s51, s51, 0
	global_load_ushort v117, v99, s[50:51] offset:64
	s_add_u32 s50, s50, 0x800
	s_addc_u32 s51, s51, 0
	global_load_ushort v118, v99, s[50:51] offset:64
	s_add_u32 s50, s50, 0x800
	s_addc_u32 s51, s51, 0
	global_load_ushort v119, v99, s[50:51] offset:64
	s_add_u32 s50, s50, 0x2800
	s_addc_u32 s51, s51, 0
	global_load_ushort v120, v99, s[50:51] offset:64
	s_add_u32 s50, s50, 0x800
	s_addc_u32 s51, s51, 0
	global_load_ushort v121, v99, s[50:51] offset:64
	s_add_u32 s50, s50, 0x800
	s_addc_u32 s51, s51, 0
	global_load_ushort v122, v99, s[50:51] offset:64
	s_add_u32 s50, s50, 0x800
	s_addc_u32 s51, s51, 0
	global_load_ushort v123, v99, s[50:51] offset:64
	s_add_u32 s50, s50, 0x2800
	s_addc_u32 s51, s51, 0
	global_load_ushort v124, v99, s[50:51] offset:64
	s_add_u32 s50, s50, 0x800
	s_addc_u32 s51, s51, 0
	global_load_ushort v125, v99, s[50:51] offset:64
	s_add_u32 s50, s50, 0x800
	s_addc_u32 s51, s51, 0
	global_load_ushort v126, v99, s[50:51] offset:64
	s_add_u32 s50, s50, 0x800
	s_addc_u32 s51, s51, 0
	global_load_ushort v127, v99, s[50:51] offset:64
	s_add_u32 s50, s50, 0x2800
	s_addc_u32 s51, s51, 0
	global_load_ushort v128, v99, s[50:51] offset:64
	s_add_u32 s50, s50, 0x800
	s_addc_u32 s51, s51, 0
	global_load_ushort v129, v99, s[50:51] offset:64
	s_add_u32 s50, s50, 0x800
	s_addc_u32 s51, s51, 0
	global_load_ushort v130, v99, s[50:51] offset:64
	s_add_u32 s50, s50, 0x800
	s_addc_u32 s51, s51, 0
	global_load_ushort v131, v99, s[50:51] offset:64
	s_waitcnt vmcnt(0)
	v_lshlrev_b32_e32 v100, 16, v100
	v_lshlrev_b32_e32 v116, 16, v116
	v_fmac_f32_e32 v100, v64, v116
	v_cvt_pk_bf16_f32 v100, v100, v100
	v_lshlrev_b32_e32 v101, 16, v101
	v_lshlrev_b32_e32 v117, 16, v117
	v_fmac_f32_e32 v101, v65, v117
	v_cvt_pk_bf16_f32 v101, v101, v101
	v_lshlrev_b32_e32 v102, 16, v102
	v_lshlrev_b32_e32 v118, 16, v118
	v_fmac_f32_e32 v102, v66, v118
	v_cvt_pk_bf16_f32 v102, v102, v102
	v_lshlrev_b32_e32 v103, 16, v103
	v_lshlrev_b32_e32 v119, 16, v119
	v_fmac_f32_e32 v103, v67, v119
	v_cvt_pk_bf16_f32 v103, v103, v103
	v_lshlrev_b32_e32 v104, 16, v104
	v_lshlrev_b32_e32 v120, 16, v120
	v_fmac_f32_e32 v104, v68, v120
	v_cvt_pk_bf16_f32 v104, v104, v104
	v_lshlrev_b32_e32 v105, 16, v105
	v_lshlrev_b32_e32 v121, 16, v121
	v_fmac_f32_e32 v105, v69, v121
	v_cvt_pk_bf16_f32 v105, v105, v105
	v_lshlrev_b32_e32 v106, 16, v106
	v_lshlrev_b32_e32 v122, 16, v122
	v_fmac_f32_e32 v106, v70, v122
	v_cvt_pk_bf16_f32 v106, v106, v106
	v_lshlrev_b32_e32 v107, 16, v107
	v_lshlrev_b32_e32 v123, 16, v123
	v_fmac_f32_e32 v107, v71, v123
	v_cvt_pk_bf16_f32 v107, v107, v107
	v_lshlrev_b32_e32 v108, 16, v108
	v_lshlrev_b32_e32 v124, 16, v124
	v_fmac_f32_e32 v108, v72, v124
	v_cvt_pk_bf16_f32 v108, v108, v108
	v_lshlrev_b32_e32 v109, 16, v109
	v_lshlrev_b32_e32 v125, 16, v125
	v_fmac_f32_e32 v109, v73, v125
	v_cvt_pk_bf16_f32 v109, v109, v109
	v_lshlrev_b32_e32 v110, 16, v110
	v_lshlrev_b32_e32 v126, 16, v126
	v_fmac_f32_e32 v110, v74, v126
	v_cvt_pk_bf16_f32 v110, v110, v110
	v_lshlrev_b32_e32 v111, 16, v111
	v_lshlrev_b32_e32 v127, 16, v127
	v_fmac_f32_e32 v111, v75, v127
	v_cvt_pk_bf16_f32 v111, v111, v111
	v_lshlrev_b32_e32 v112, 16, v112
	v_lshlrev_b32_e32 v128, 16, v128
	v_fmac_f32_e32 v112, v76, v128
	v_cvt_pk_bf16_f32 v112, v112, v112
	v_lshlrev_b32_e32 v113, 16, v113
	v_lshlrev_b32_e32 v129, 16, v129
	v_fmac_f32_e32 v113, v77, v129
	v_cvt_pk_bf16_f32 v113, v113, v113
	v_lshlrev_b32_e32 v114, 16, v114
	v_lshlrev_b32_e32 v130, 16, v130
	v_fmac_f32_e32 v114, v78, v130
	v_cvt_pk_bf16_f32 v114, v114, v114
	v_lshlrev_b32_e32 v115, 16, v115
	v_lshlrev_b32_e32 v131, 16, v131
	v_fmac_f32_e32 v115, v79, v131
	v_cvt_pk_bf16_f32 v115, v115, v115
	s_mov_b64 s[52:53], s[0:1]
	global_store_short v99, v100, s[52:53] offset:64
	s_add_u32 s52, s52, 0x800
	s_addc_u32 s53, s53, 0
	global_store_short v99, v101, s[52:53] offset:64
	s_add_u32 s52, s52, 0x800
	s_addc_u32 s53, s53, 0
	global_store_short v99, v102, s[52:53] offset:64
	s_add_u32 s52, s52, 0x800
	s_addc_u32 s53, s53, 0
	global_store_short v99, v103, s[52:53] offset:64
	s_add_u32 s52, s52, 0x2800
	s_addc_u32 s53, s53, 0
	global_store_short v99, v104, s[52:53] offset:64
	s_add_u32 s52, s52, 0x800
	s_addc_u32 s53, s53, 0
	global_store_short v99, v105, s[52:53] offset:64
	s_add_u32 s52, s52, 0x800
	s_addc_u32 s53, s53, 0
	global_store_short v99, v106, s[52:53] offset:64
	s_add_u32 s52, s52, 0x800
	s_addc_u32 s53, s53, 0
	global_store_short v99, v107, s[52:53] offset:64
	s_add_u32 s52, s52, 0x2800
	s_addc_u32 s53, s53, 0
	global_store_short v99, v108, s[52:53] offset:64
	s_add_u32 s52, s52, 0x800
	s_addc_u32 s53, s53, 0
	global_store_short v99, v109, s[52:53] offset:64
	s_add_u32 s52, s52, 0x800
	s_addc_u32 s53, s53, 0
	global_store_short v99, v110, s[52:53] offset:64
	s_add_u32 s52, s52, 0x800
	s_addc_u32 s53, s53, 0
	global_store_short v99, v111, s[52:53] offset:64
	s_add_u32 s52, s52, 0x2800
	s_addc_u32 s53, s53, 0
	global_store_short v99, v112, s[52:53] offset:64
	s_add_u32 s52, s52, 0x800
	s_addc_u32 s53, s53, 0
	global_store_short v99, v113, s[52:53] offset:64
	s_add_u32 s52, s52, 0x800
	s_addc_u32 s53, s53, 0
	global_store_short v99, v114, s[52:53] offset:64
	s_add_u32 s52, s52, 0x800
	s_addc_u32 s53, s53, 0
	global_store_short v99, v115, s[52:53] offset:64
	s_mov_b64 s[12:13], s[0:1]
	s_add_u32 s12, s12, 0x10000
	s_addc_u32 s13, s13, 0
	global_load_ushort v100, v99, s[12:13] offset:64
	s_add_u32 s12, s12, 0x800
	s_addc_u32 s13, s13, 0
	global_load_ushort v101, v99, s[12:13] offset:64
	s_add_u32 s12, s12, 0x800
	s_addc_u32 s13, s13, 0
	global_load_ushort v102, v99, s[12:13] offset:64
	s_add_u32 s12, s12, 0x800
	s_addc_u32 s13, s13, 0
	global_load_ushort v103, v99, s[12:13] offset:64
	s_add_u32 s12, s12, 0x2800
	s_addc_u32 s13, s13, 0
	global_load_ushort v104, v99, s[12:13] offset:64
	s_add_u32 s12, s12, 0x800
	s_addc_u32 s13, s13, 0
	global_load_ushort v105, v99, s[12:13] offset:64
	s_add_u32 s12, s12, 0x800
	s_addc_u32 s13, s13, 0
	global_load_ushort v106, v99, s[12:13] offset:64
	s_add_u32 s12, s12, 0x800
	s_addc_u32 s13, s13, 0
	global_load_ushort v107, v99, s[12:13] offset:64
	s_add_u32 s12, s12, 0x2800
	s_addc_u32 s13, s13, 0
	global_load_ushort v108, v99, s[12:13] offset:64
	s_add_u32 s12, s12, 0x800
	s_addc_u32 s13, s13, 0
	global_load_ushort v109, v99, s[12:13] offset:64
	s_add_u32 s12, s12, 0x800
	s_addc_u32 s13, s13, 0
	global_load_ushort v110, v99, s[12:13] offset:64
	s_add_u32 s12, s12, 0x800
	s_addc_u32 s13, s13, 0
	global_load_ushort v111, v99, s[12:13] offset:64
	s_add_u32 s12, s12, 0x2800
	s_addc_u32 s13, s13, 0
	global_load_ushort v112, v99, s[12:13] offset:64
	s_add_u32 s12, s12, 0x800
	s_addc_u32 s13, s13, 0
	global_load_ushort v113, v99, s[12:13] offset:64
	s_add_u32 s12, s12, 0x800
	s_addc_u32 s13, s13, 0
	global_load_ushort v114, v99, s[12:13] offset:64
	s_add_u32 s12, s12, 0x800
	s_addc_u32 s13, s13, 0
	global_load_ushort v115, v99, s[12:13] offset:64
	s_mov_b64 s[50:51], s[4:5]
	s_add_u32 s50, s50, 0x10000
	s_addc_u32 s51, s51, 0
	global_load_ushort v116, v99, s[50:51] offset:64
	s_add_u32 s50, s50, 0x800
	s_addc_u32 s51, s51, 0
	global_load_ushort v117, v99, s[50:51] offset:64
	s_add_u32 s50, s50, 0x800
	s_addc_u32 s51, s51, 0
	global_load_ushort v118, v99, s[50:51] offset:64
	s_add_u32 s50, s50, 0x800
	s_addc_u32 s51, s51, 0
	global_load_ushort v119, v99, s[50:51] offset:64
	s_add_u32 s50, s50, 0x2800
	s_addc_u32 s51, s51, 0
	global_load_ushort v120, v99, s[50:51] offset:64
	s_add_u32 s50, s50, 0x800
	s_addc_u32 s51, s51, 0
	global_load_ushort v121, v99, s[50:51] offset:64
	s_add_u32 s50, s50, 0x800
	s_addc_u32 s51, s51, 0
	global_load_ushort v122, v99, s[50:51] offset:64
	s_add_u32 s50, s50, 0x800
	s_addc_u32 s51, s51, 0
	global_load_ushort v123, v99, s[50:51] offset:64
	s_add_u32 s50, s50, 0x2800
	s_addc_u32 s51, s51, 0
	global_load_ushort v124, v99, s[50:51] offset:64
	s_add_u32 s50, s50, 0x800
	s_addc_u32 s51, s51, 0
	global_load_ushort v125, v99, s[50:51] offset:64
	s_add_u32 s50, s50, 0x800
	s_addc_u32 s51, s51, 0
	global_load_ushort v126, v99, s[50:51] offset:64
	s_add_u32 s50, s50, 0x800
	s_addc_u32 s51, s51, 0
	global_load_ushort v127, v99, s[50:51] offset:64
	s_add_u32 s50, s50, 0x2800
	s_addc_u32 s51, s51, 0
	global_load_ushort v128, v99, s[50:51] offset:64
	s_add_u32 s50, s50, 0x800
	s_addc_u32 s51, s51, 0
	global_load_ushort v129, v99, s[50:51] offset:64
	s_add_u32 s50, s50, 0x800
	s_addc_u32 s51, s51, 0
	global_load_ushort v130, v99, s[50:51] offset:64
	s_add_u32 s50, s50, 0x800
	s_addc_u32 s51, s51, 0
	global_load_ushort v131, v99, s[50:51] offset:64
	s_waitcnt vmcnt(0)
	v_lshlrev_b32_e32 v100, 16, v100
	v_lshlrev_b32_e32 v116, 16, v116
	v_fmac_f32_e32 v100, v32, v116
	v_cvt_pk_bf16_f32 v100, v100, v100
	v_lshlrev_b32_e32 v101, 16, v101
	v_lshlrev_b32_e32 v117, 16, v117
	v_fmac_f32_e32 v101, v33, v117
	v_cvt_pk_bf16_f32 v101, v101, v101
	v_lshlrev_b32_e32 v102, 16, v102
	v_lshlrev_b32_e32 v118, 16, v118
	v_fmac_f32_e32 v102, v34, v118
	v_cvt_pk_bf16_f32 v102, v102, v102
	v_lshlrev_b32_e32 v103, 16, v103
	v_lshlrev_b32_e32 v119, 16, v119
	v_fmac_f32_e32 v103, v35, v119
	v_cvt_pk_bf16_f32 v103, v103, v103
	v_lshlrev_b32_e32 v104, 16, v104
	v_lshlrev_b32_e32 v120, 16, v120
	v_fmac_f32_e32 v104, v36, v120
	v_cvt_pk_bf16_f32 v104, v104, v104
	v_lshlrev_b32_e32 v105, 16, v105
	v_lshlrev_b32_e32 v121, 16, v121
	v_fmac_f32_e32 v105, v37, v121
	v_cvt_pk_bf16_f32 v105, v105, v105
	v_lshlrev_b32_e32 v106, 16, v106
	v_lshlrev_b32_e32 v122, 16, v122
	v_fmac_f32_e32 v106, v38, v122
	v_cvt_pk_bf16_f32 v106, v106, v106
	v_lshlrev_b32_e32 v107, 16, v107
	v_lshlrev_b32_e32 v123, 16, v123
	v_fmac_f32_e32 v107, v39, v123
	v_cvt_pk_bf16_f32 v107, v107, v107
	v_lshlrev_b32_e32 v108, 16, v108
	v_lshlrev_b32_e32 v124, 16, v124
	v_fmac_f32_e32 v108, v40, v124
	v_cvt_pk_bf16_f32 v108, v108, v108
	v_lshlrev_b32_e32 v109, 16, v109
	v_lshlrev_b32_e32 v125, 16, v125
	v_fmac_f32_e32 v109, v41, v125
	v_cvt_pk_bf16_f32 v109, v109, v109
	v_lshlrev_b32_e32 v110, 16, v110
	v_lshlrev_b32_e32 v126, 16, v126
	v_fmac_f32_e32 v110, v42, v126
	v_cvt_pk_bf16_f32 v110, v110, v110
	v_lshlrev_b32_e32 v111, 16, v111
	v_lshlrev_b32_e32 v127, 16, v127
	v_fmac_f32_e32 v111, v43, v127
	v_cvt_pk_bf16_f32 v111, v111, v111
	v_lshlrev_b32_e32 v112, 16, v112
	v_lshlrev_b32_e32 v128, 16, v128
	v_fmac_f32_e32 v112, v44, v128
	v_cvt_pk_bf16_f32 v112, v112, v112
	v_lshlrev_b32_e32 v113, 16, v113
	v_lshlrev_b32_e32 v129, 16, v129
	v_fmac_f32_e32 v113, v45, v129
	v_cvt_pk_bf16_f32 v113, v113, v113
	v_lshlrev_b32_e32 v114, 16, v114
	v_lshlrev_b32_e32 v130, 16, v130
	v_fmac_f32_e32 v114, v46, v130
	v_cvt_pk_bf16_f32 v114, v114, v114
	v_lshlrev_b32_e32 v115, 16, v115
	v_lshlrev_b32_e32 v131, 16, v131
	v_fmac_f32_e32 v115, v47, v131
	v_cvt_pk_bf16_f32 v115, v115, v115
	s_mov_b64 s[52:53], s[0:1]
	s_add_u32 s52, s52, 0x10000
	s_addc_u32 s53, s53, 0
	global_store_short v99, v100, s[52:53] offset:64
	s_add_u32 s52, s52, 0x800
	s_addc_u32 s53, s53, 0
	global_store_short v99, v101, s[52:53] offset:64
	s_add_u32 s52, s52, 0x800
	s_addc_u32 s53, s53, 0
	global_store_short v99, v102, s[52:53] offset:64
	s_add_u32 s52, s52, 0x800
	s_addc_u32 s53, s53, 0
	global_store_short v99, v103, s[52:53] offset:64
	s_add_u32 s52, s52, 0x2800
	s_addc_u32 s53, s53, 0
	global_store_short v99, v104, s[52:53] offset:64
	s_add_u32 s52, s52, 0x800
	s_addc_u32 s53, s53, 0
	global_store_short v99, v105, s[52:53] offset:64
	s_add_u32 s52, s52, 0x800
	s_addc_u32 s53, s53, 0
	global_store_short v99, v106, s[52:53] offset:64
	s_add_u32 s52, s52, 0x800
	s_addc_u32 s53, s53, 0
	global_store_short v99, v107, s[52:53] offset:64
	s_add_u32 s52, s52, 0x2800
	s_addc_u32 s53, s53, 0
	global_store_short v99, v108, s[52:53] offset:64
	s_add_u32 s52, s52, 0x800
	s_addc_u32 s53, s53, 0
	global_store_short v99, v109, s[52:53] offset:64
	s_add_u32 s52, s52, 0x800
	s_addc_u32 s53, s53, 0
	global_store_short v99, v110, s[52:53] offset:64
	s_add_u32 s52, s52, 0x800
	s_addc_u32 s53, s53, 0
	global_store_short v99, v111, s[52:53] offset:64
	s_add_u32 s52, s52, 0x2800
	s_addc_u32 s53, s53, 0
	global_store_short v99, v112, s[52:53] offset:64
	s_add_u32 s52, s52, 0x800
	s_addc_u32 s53, s53, 0
	global_store_short v99, v113, s[52:53] offset:64
	s_add_u32 s52, s52, 0x800
	s_addc_u32 s53, s53, 0
	global_store_short v99, v114, s[52:53] offset:64
	s_add_u32 s52, s52, 0x800
	s_addc_u32 s53, s53, 0
	global_store_short v99, v115, s[52:53] offset:64
	s_mov_b64 s[12:13], s[0:1]
	s_add_u32 s12, s12, 0x20000
	s_addc_u32 s13, s13, 0
	global_load_ushort v100, v99, s[12:13] offset:64
	s_add_u32 s12, s12, 0x800
	s_addc_u32 s13, s13, 0
	global_load_ushort v101, v99, s[12:13] offset:64
	s_add_u32 s12, s12, 0x800
	s_addc_u32 s13, s13, 0
	global_load_ushort v102, v99, s[12:13] offset:64
	s_add_u32 s12, s12, 0x800
	s_addc_u32 s13, s13, 0
	global_load_ushort v103, v99, s[12:13] offset:64
	s_add_u32 s12, s12, 0x2800
	s_addc_u32 s13, s13, 0
	global_load_ushort v104, v99, s[12:13] offset:64
	s_add_u32 s12, s12, 0x800
	s_addc_u32 s13, s13, 0
	global_load_ushort v105, v99, s[12:13] offset:64
	s_add_u32 s12, s12, 0x800
	s_addc_u32 s13, s13, 0
	global_load_ushort v106, v99, s[12:13] offset:64
	s_add_u32 s12, s12, 0x800
	s_addc_u32 s13, s13, 0
	global_load_ushort v107, v99, s[12:13] offset:64
	s_add_u32 s12, s12, 0x2800
	s_addc_u32 s13, s13, 0
	global_load_ushort v108, v99, s[12:13] offset:64
	s_add_u32 s12, s12, 0x800
	s_addc_u32 s13, s13, 0
	global_load_ushort v109, v99, s[12:13] offset:64
	s_add_u32 s12, s12, 0x800
	s_addc_u32 s13, s13, 0
	global_load_ushort v110, v99, s[12:13] offset:64
	s_add_u32 s12, s12, 0x800
	s_addc_u32 s13, s13, 0
	global_load_ushort v111, v99, s[12:13] offset:64
	s_add_u32 s12, s12, 0x2800
	s_addc_u32 s13, s13, 0
	global_load_ushort v112, v99, s[12:13] offset:64
	s_add_u32 s12, s12, 0x800
	s_addc_u32 s13, s13, 0
	global_load_ushort v113, v99, s[12:13] offset:64
	s_add_u32 s12, s12, 0x800
	s_addc_u32 s13, s13, 0
	global_load_ushort v114, v99, s[12:13] offset:64
	s_add_u32 s12, s12, 0x800
	s_addc_u32 s13, s13, 0
	global_load_ushort v115, v99, s[12:13] offset:64
	s_mov_b64 s[50:51], s[4:5]
	s_add_u32 s50, s50, 0x20000
	s_addc_u32 s51, s51, 0
	global_load_ushort v116, v99, s[50:51] offset:64
	s_add_u32 s50, s50, 0x800
	s_addc_u32 s51, s51, 0
	global_load_ushort v117, v99, s[50:51] offset:64
	s_add_u32 s50, s50, 0x800
	s_addc_u32 s51, s51, 0
	global_load_ushort v118, v99, s[50:51] offset:64
	s_add_u32 s50, s50, 0x800
	s_addc_u32 s51, s51, 0
	global_load_ushort v119, v99, s[50:51] offset:64
	s_add_u32 s50, s50, 0x2800
	s_addc_u32 s51, s51, 0
	global_load_ushort v120, v99, s[50:51] offset:64
	s_add_u32 s50, s50, 0x800
	s_addc_u32 s51, s51, 0
	global_load_ushort v121, v99, s[50:51] offset:64
	s_add_u32 s50, s50, 0x800
	s_addc_u32 s51, s51, 0
	global_load_ushort v122, v99, s[50:51] offset:64
	s_add_u32 s50, s50, 0x800
	s_addc_u32 s51, s51, 0
	global_load_ushort v123, v99, s[50:51] offset:64
	s_add_u32 s50, s50, 0x2800
	s_addc_u32 s51, s51, 0
	global_load_ushort v124, v99, s[50:51] offset:64
	s_add_u32 s50, s50, 0x800
	s_addc_u32 s51, s51, 0
	global_load_ushort v125, v99, s[50:51] offset:64
	s_add_u32 s50, s50, 0x800
	s_addc_u32 s51, s51, 0
	global_load_ushort v126, v99, s[50:51] offset:64
	s_add_u32 s50, s50, 0x800
	s_addc_u32 s51, s51, 0
	global_load_ushort v127, v99, s[50:51] offset:64
	s_add_u32 s50, s50, 0x2800
	s_addc_u32 s51, s51, 0
	global_load_ushort v128, v99, s[50:51] offset:64
	s_add_u32 s50, s50, 0x800
	s_addc_u32 s51, s51, 0
	global_load_ushort v129, v99, s[50:51] offset:64
	s_add_u32 s50, s50, 0x800
	s_addc_u32 s51, s51, 0
	global_load_ushort v130, v99, s[50:51] offset:64
	s_add_u32 s50, s50, 0x800
	s_addc_u32 s51, s51, 0
	global_load_ushort v131, v99, s[50:51] offset:64
	s_waitcnt vmcnt(0)
	v_lshlrev_b32_e32 v100, 16, v100
	v_lshlrev_b32_e32 v116, 16, v116
	v_fmac_f32_e32 v100, v0, v116
	v_cvt_pk_bf16_f32 v100, v100, v100
	v_lshlrev_b32_e32 v101, 16, v101
	v_lshlrev_b32_e32 v117, 16, v117
	v_fmac_f32_e32 v101, v1, v117
	v_cvt_pk_bf16_f32 v101, v101, v101
	v_lshlrev_b32_e32 v102, 16, v102
	v_lshlrev_b32_e32 v118, 16, v118
	v_fmac_f32_e32 v102, v2, v118
	v_cvt_pk_bf16_f32 v102, v102, v102
	v_lshlrev_b32_e32 v103, 16, v103
	v_lshlrev_b32_e32 v119, 16, v119
	v_fmac_f32_e32 v103, v3, v119
	v_cvt_pk_bf16_f32 v103, v103, v103
	v_lshlrev_b32_e32 v104, 16, v104
	v_lshlrev_b32_e32 v120, 16, v120
	v_fmac_f32_e32 v104, v4, v120
	v_cvt_pk_bf16_f32 v104, v104, v104
	v_lshlrev_b32_e32 v105, 16, v105
	v_lshlrev_b32_e32 v121, 16, v121
	v_fmac_f32_e32 v105, v5, v121
	v_cvt_pk_bf16_f32 v105, v105, v105
	v_lshlrev_b32_e32 v106, 16, v106
	v_lshlrev_b32_e32 v122, 16, v122
	v_fmac_f32_e32 v106, v6, v122
	v_cvt_pk_bf16_f32 v106, v106, v106
	v_lshlrev_b32_e32 v107, 16, v107
	v_lshlrev_b32_e32 v123, 16, v123
	v_fmac_f32_e32 v107, v7, v123
	v_cvt_pk_bf16_f32 v107, v107, v107
	v_lshlrev_b32_e32 v108, 16, v108
	v_lshlrev_b32_e32 v124, 16, v124
	v_fmac_f32_e32 v108, v8, v124
	v_cvt_pk_bf16_f32 v108, v108, v108
	v_lshlrev_b32_e32 v109, 16, v109
	v_lshlrev_b32_e32 v125, 16, v125
	v_fmac_f32_e32 v109, v9, v125
	v_cvt_pk_bf16_f32 v109, v109, v109
	v_lshlrev_b32_e32 v110, 16, v110
	v_lshlrev_b32_e32 v126, 16, v126
	v_fmac_f32_e32 v110, v10, v126
	v_cvt_pk_bf16_f32 v110, v110, v110
	v_lshlrev_b32_e32 v111, 16, v111
	v_lshlrev_b32_e32 v127, 16, v127
	v_fmac_f32_e32 v111, v11, v127
	v_cvt_pk_bf16_f32 v111, v111, v111
	v_lshlrev_b32_e32 v112, 16, v112
	v_lshlrev_b32_e32 v128, 16, v128
	v_fmac_f32_e32 v112, v12, v128
	v_cvt_pk_bf16_f32 v112, v112, v112
	v_lshlrev_b32_e32 v113, 16, v113
	v_lshlrev_b32_e32 v129, 16, v129
	v_fmac_f32_e32 v113, v13, v129
	v_cvt_pk_bf16_f32 v113, v113, v113
	v_lshlrev_b32_e32 v114, 16, v114
	v_lshlrev_b32_e32 v130, 16, v130
	v_fmac_f32_e32 v114, v14, v130
	v_cvt_pk_bf16_f32 v114, v114, v114
	v_lshlrev_b32_e32 v115, 16, v115
	v_lshlrev_b32_e32 v131, 16, v131
	v_fmac_f32_e32 v115, v15, v131
	v_cvt_pk_bf16_f32 v115, v115, v115
	s_mov_b64 s[52:53], s[0:1]
	s_add_u32 s52, s52, 0x20000
	s_addc_u32 s53, s53, 0
	global_store_short v99, v100, s[52:53] offset:64
	s_add_u32 s52, s52, 0x800
	s_addc_u32 s53, s53, 0
	global_store_short v99, v101, s[52:53] offset:64
	s_add_u32 s52, s52, 0x800
	s_addc_u32 s53, s53, 0
	global_store_short v99, v102, s[52:53] offset:64
	s_add_u32 s52, s52, 0x800
	s_addc_u32 s53, s53, 0
	global_store_short v99, v103, s[52:53] offset:64
	s_add_u32 s52, s52, 0x2800
	s_addc_u32 s53, s53, 0
	global_store_short v99, v104, s[52:53] offset:64
	s_add_u32 s52, s52, 0x800
	s_addc_u32 s53, s53, 0
	global_store_short v99, v105, s[52:53] offset:64
	s_add_u32 s52, s52, 0x800
	s_addc_u32 s53, s53, 0
	global_store_short v99, v106, s[52:53] offset:64
	s_add_u32 s52, s52, 0x800
	s_addc_u32 s53, s53, 0
	global_store_short v99, v107, s[52:53] offset:64
	s_add_u32 s52, s52, 0x2800
	s_addc_u32 s53, s53, 0
	global_store_short v99, v108, s[52:53] offset:64
	s_add_u32 s52, s52, 0x800
	s_addc_u32 s53, s53, 0
	global_store_short v99, v109, s[52:53] offset:64
	s_add_u32 s52, s52, 0x800
	s_addc_u32 s53, s53, 0
	global_store_short v99, v110, s[52:53] offset:64
	s_add_u32 s52, s52, 0x800
	s_addc_u32 s53, s53, 0
	global_store_short v99, v111, s[52:53] offset:64
	s_add_u32 s52, s52, 0x2800
	s_addc_u32 s53, s53, 0
	global_store_short v99, v112, s[52:53] offset:64
	s_add_u32 s52, s52, 0x800
	s_addc_u32 s53, s53, 0
	global_store_short v99, v113, s[52:53] offset:64
	s_add_u32 s52, s52, 0x800
	s_addc_u32 s53, s53, 0
	global_store_short v99, v114, s[52:53] offset:64
	s_add_u32 s52, s52, 0x800
	s_addc_u32 s53, s53, 0
	global_store_short v99, v115, s[52:53] offset:64
	s_mov_b64 s[50:51], 0x50000
	s_mov_b64 s[52:53], 0x50180
	s_load_dword s0, s[90:91], 0x0
	s_waitcnt lgkmcnt(0)
	s_add_i32 s14, s14, s0
	s_cmpk_lt_i32 s14, 0x200
	s_cbranch_scc1 .LBB0_777

.LBB0_838:
	s_add_i32 s8, s9, 2
	s_cmp_lt_u32 s9, 14
	s_cselect_b64 s[10:11], -1, 0
	s_and_b64 vcc, s[10:11], exec
	s_cselect_b32 s2, s7, 0x3c0
	s_lshl_b64 s[10:11], s[2:3], 1
	v_lshl_add_u64 v[158:159], v[180:181], 0, s[10:11]
	global_load_dwordx4 v[138:141], v[158:159], off
	v_lshl_add_u64 v[146:147], v[158:159], 0, s[40:41]
	global_load_dwordx4 v[142:145], v[146:147], off
	v_lshl_add_u64 v[150:151], v[158:159], 0, s[18:19]
	global_load_dwordx4 v[146:149], v[150:151], off
	v_lshl_add_u64 v[154:155], v[158:159], 0, s[92:93]
	global_load_dwordx4 v[150:153], v[154:155], off
	v_lshl_add_u64 v[160:161], v[158:159], 0, s[62:63]
	global_load_dwordx4 v[154:157], v[160:161], off
	v_lshl_add_u64 v[162:163], v[158:159], 0, s[50:51]
	global_load_dwordx4 v[158:161], v[162:163], off
	v_lshl_add_u64 v[174:175], v[182:183], 0, s[10:11]
	global_load_dwordx4 v[162:165], v[174:175], off
	v_lshl_add_u64 v[170:171], v[174:175], 0, s[40:41]
	global_load_dwordx4 v[166:169], v[170:171], off
	v_lshl_add_u64 v[176:177], v[174:175], 0, s[18:19]
	global_load_dwordx4 v[170:173], v[176:177], off
	v_lshl_add_u64 v[186:187], v[174:175], 0, s[92:93]
	global_load_dwordx4 v[174:177], v[186:187], off
	s_min_u32 s2, s9, 12
	s_lshl_b32 s2, s2, 7
	s_addk_i32 s7, 0x80
	s_mov_b32 s9, s8
	ds_read_b128 v[186:189], v179
	ds_read_b128 v[190:193], v184 offset:27648
	ds_read_b128 v[194:197], v179 offset:4608
	ds_read_b128 v[198:201], v184 offset:32256
	ds_read_b128 v[202:205], v179 offset:9216
	ds_read_b128 v[206:209], v179 offset:32
	ds_read_b128 v[210:213], v184 offset:27680
	ds_read_b128 v[214:217], v179 offset:4640
	ds_read_b128 v[218:221], v184 offset:32288
	ds_read_b128 v[222:225], v179 offset:9248
	s_waitcnt lgkmcnt(5)
	v_mfma_f32_32x32x16_bf16 v[80:95], v[186:189], v[190:193], v[80:95]
	v_mfma_f32_32x32x16_bf16 v[32:47], v[186:189], v[198:201], v[32:47]
	v_mfma_f32_32x32x16_bf16 v[64:79], v[194:197], v[190:193], v[64:79]
	v_mfma_f32_32x32x16_bf16 v[16:31], v[194:197], v[198:201], v[16:31]
	v_mfma_f32_32x32x16_bf16 v[48:63], v[202:205], v[190:193], v[48:63]
	v_mfma_f32_32x32x16_bf16 v[0:15], v[202:205], v[198:201], v[0:15]
	ds_read_b128 v[186:189], v179 offset:64
	ds_read_b128 v[190:193], v184 offset:27712
	ds_read_b128 v[194:197], v179 offset:4672
	ds_read_b128 v[198:201], v184 offset:32320
	ds_read_b128 v[202:205], v179 offset:9280
	s_waitcnt lgkmcnt(5)
	v_mfma_f32_32x32x16_bf16 v[80:95], v[206:209], v[210:213], v[80:95]
	v_mfma_f32_32x32x16_bf16 v[32:47], v[206:209], v[218:221], v[32:47]
	v_mfma_f32_32x32x16_bf16 v[64:79], v[214:217], v[210:213], v[64:79]
	v_mfma_f32_32x32x16_bf16 v[16:31], v[214:217], v[218:221], v[16:31]
	v_mfma_f32_32x32x16_bf16 v[48:63], v[222:225], v[210:213], v[48:63]
	v_mfma_f32_32x32x16_bf16 v[0:15], v[222:225], v[218:221], v[0:15]
	ds_read_b128 v[206:209], v179 offset:96
	ds_read_b128 v[210:213], v184 offset:27744
	ds_read_b128 v[214:217], v179 offset:4704
	ds_read_b128 v[218:221], v184 offset:32352
	ds_read_b128 v[222:225], v179 offset:9312
	s_waitcnt lgkmcnt(0)
	s_waitcnt vmcnt(10)
	s_barrier
	v_mfma_f32_32x32x16_bf16 v[80:95], v[186:189], v[190:193], v[80:95]
	ds_write_b128 v97, v[98:101]
	ds_write_b128 v97, v[102:105] offset:4608
	v_mfma_f32_32x32x16_bf16 v[32:47], v[186:189], v[198:201], v[32:47]
	ds_write_b128 v97, v[106:109] offset:9216
	ds_write_b128 v97, v[110:113] offset:13824
	v_mfma_f32_32x32x16_bf16 v[64:79], v[194:197], v[190:193], v[64:79]
	ds_write_b128 v97, v[114:117] offset:18432
	ds_write_b128 v97, v[118:121] offset:23040
	v_mfma_f32_32x32x16_bf16 v[16:31], v[194:197], v[198:201], v[16:31]
	ds_write_b128 v97, v[122:125] offset:27648
	ds_write_b128 v97, v[126:129] offset:32256
	v_mfma_f32_32x32x16_bf16 v[48:63], v[202:205], v[190:193], v[48:63]
	ds_write_b128 v97, v[130:133] offset:36864
	ds_write_b128 v97, v[134:137] offset:41472
	v_mfma_f32_32x32x16_bf16 v[0:15], v[202:205], v[198:201], v[0:15]
	v_lshl_add_u64 v[118:119], v[180:181], 0, s[2:3]
	v_mfma_f32_32x32x16_bf16 v[80:95], v[206:209], v[210:213], v[80:95]
	v_mfma_f32_32x32x16_bf16 v[32:47], v[206:209], v[218:221], v[32:47]
	v_mfma_f32_32x32x16_bf16 v[64:79], v[214:217], v[210:213], v[64:79]
	v_mfma_f32_32x32x16_bf16 v[16:31], v[214:217], v[218:221], v[16:31]
	v_mfma_f32_32x32x16_bf16 v[48:63], v[222:225], v[210:213], v[48:63]
	v_mfma_f32_32x32x16_bf16 v[0:15], v[222:225], v[218:221], v[0:15]
	s_waitcnt lgkmcnt(0)
	s_barrier
	v_lshl_add_u64 v[102:103], v[118:119], 0, s[22:23]
	global_load_dwordx4 v[98:101], v[102:103], off
	v_lshl_add_u64 v[106:107], v[118:119], 0, s[76:77]
	global_load_dwordx4 v[102:105], v[106:107], off
	v_lshl_add_u64 v[110:111], v[118:119], 0, s[26:27]
	global_load_dwordx4 v[106:109], v[110:111], off
	v_lshl_add_u64 v[114:115], v[118:119], 0, s[70:71]
	global_load_dwordx4 v[110:113], v[114:115], off
	v_lshl_add_u64 v[120:121], v[118:119], 0, s[12:13]
	global_load_dwordx4 v[114:117], v[120:121], off
	v_lshl_add_u64 v[122:123], v[118:119], 0, s[14:15]
	global_load_dwordx4 v[118:121], v[122:123], off
	v_lshl_add_u64 v[134:135], v[182:183], 0, s[2:3]
	v_lshl_add_u64 v[126:127], v[134:135], 0, s[22:23]
	global_load_dwordx4 v[122:125], v[126:127], off
	v_lshl_add_u64 v[130:131], v[134:135], 0, s[76:77]
	global_load_dwordx4 v[126:129], v[130:131], off
	v_lshl_add_u64 v[136:137], v[134:135], 0, s[26:27]
	global_load_dwordx4 v[130:133], v[136:137], off
	v_lshl_add_u64 v[186:187], v[134:135], 0, s[70:71]
	global_load_dwordx4 v[134:137], v[186:187], off
	ds_read_b128 v[186:189], v179
	ds_read_b128 v[190:193], v184 offset:27648
	ds_read_b128 v[194:197], v179 offset:4608
	ds_read_b128 v[198:201], v184 offset:32256
	ds_read_b128 v[202:205], v179 offset:9216
	ds_read_b128 v[206:209], v179 offset:32
	ds_read_b128 v[210:213], v184 offset:27680
	ds_read_b128 v[214:217], v179 offset:4640
	ds_read_b128 v[218:221], v184 offset:32288
	ds_read_b128 v[222:225], v179 offset:9248
	s_waitcnt lgkmcnt(5)
	v_mfma_f32_32x32x16_bf16 v[80:95], v[186:189], v[190:193], v[80:95]
	v_mfma_f32_32x32x16_bf16 v[32:47], v[186:189], v[198:201], v[32:47]
	v_mfma_f32_32x32x16_bf16 v[64:79], v[194:197], v[190:193], v[64:79]
	v_mfma_f32_32x32x16_bf16 v[16:31], v[194:197], v[198:201], v[16:31]
	v_mfma_f32_32x32x16_bf16 v[48:63], v[202:205], v[190:193], v[48:63]
	v_mfma_f32_32x32x16_bf16 v[0:15], v[202:205], v[198:201], v[0:15]
	ds_read_b128 v[186:189], v179 offset:64
	ds_read_b128 v[190:193], v184 offset:27712
	ds_read_b128 v[194:197], v179 offset:4672
	ds_read_b128 v[198:201], v184 offset:32320
	ds_read_b128 v[202:205], v179 offset:9280
	s_waitcnt lgkmcnt(5)
	v_mfma_f32_32x32x16_bf16 v[80:95], v[206:209], v[210:213], v[80:95]
	v_mfma_f32_32x32x16_bf16 v[32:47], v[206:209], v[218:221], v[32:47]
	v_mfma_f32_32x32x16_bf16 v[64:79], v[214:217], v[210:213], v[64:79]
	v_mfma_f32_32x32x16_bf16 v[16:31], v[214:217], v[218:221], v[16:31]
	v_mfma_f32_32x32x16_bf16 v[48:63], v[222:225], v[210:213], v[48:63]
	v_mfma_f32_32x32x16_bf16 v[0:15], v[222:225], v[218:221], v[0:15]
	ds_read_b128 v[206:209], v179 offset:96
	ds_read_b128 v[210:213], v184 offset:27744
	ds_read_b128 v[214:217], v179 offset:4704
	ds_read_b128 v[218:221], v184 offset:32352
	ds_read_b128 v[222:225], v179 offset:9312
	s_waitcnt lgkmcnt(0)
	s_waitcnt vmcnt(10)
	s_barrier
	v_mfma_f32_32x32x16_bf16 v[80:95], v[186:189], v[190:193], v[80:95]
	ds_write_b128 v97, v[138:141]
	ds_write_b128 v97, v[142:145] offset:4608
	v_mfma_f32_32x32x16_bf16 v[32:47], v[186:189], v[198:201], v[32:47]
	ds_write_b128 v97, v[146:149] offset:9216
	ds_write_b128 v97, v[150:153] offset:13824
	v_mfma_f32_32x32x16_bf16 v[64:79], v[194:197], v[190:193], v[64:79]
	ds_write_b128 v97, v[154:157] offset:18432
	ds_write_b128 v97, v[158:161] offset:23040
	v_mfma_f32_32x32x16_bf16 v[16:31], v[194:197], v[198:201], v[16:31]
	ds_write_b128 v97, v[162:165] offset:27648
	ds_write_b128 v97, v[166:169] offset:32256
	v_mfma_f32_32x32x16_bf16 v[48:63], v[202:205], v[190:193], v[48:63]
	ds_write_b128 v97, v[170:173] offset:36864
	ds_write_b128 v97, v[174:177] offset:41472
	v_mfma_f32_32x32x16_bf16 v[0:15], v[202:205], v[198:201], v[0:15]
	v_mfma_f32_32x32x16_bf16 v[80:95], v[206:209], v[210:213], v[80:95]
	v_mfma_f32_32x32x16_bf16 v[32:47], v[206:209], v[218:221], v[32:47]
	v_mfma_f32_32x32x16_bf16 v[64:79], v[214:217], v[210:213], v[64:79]
	v_mfma_f32_32x32x16_bf16 v[16:31], v[214:217], v[218:221], v[16:31]
	v_mfma_f32_32x32x16_bf16 v[48:63], v[222:225], v[210:213], v[48:63]
	v_mfma_f32_32x32x16_bf16 v[0:15], v[222:225], v[218:221], v[0:15]
	s_waitcnt lgkmcnt(0)
	s_barrier
	s_cbranch_vccnz .LBB0_838
	s_waitcnt vmcnt(0)
	s_mov_b64 s[8:9], s[0:1]
	s_mov_b64 s[0:1], s[4:5]
	s_mov_b64 s[4:5], s[8:9]
	s_lshl_b64 s[8:9], s[0:1], 12
	s_lshl_b64 s[10:11], s[4:5], 2
	s_add_u32 s8, s8, s10
	s_addc_u32 s9, s9, s11
	s_add_i32 s1, s0, 0xfffff000
	s_lshr_b32 s1, s1, 10
	s_add_i32 s1, s1, 1
	s_cmp_gt_i32 s6, 21
	s_cselect_b32 s1, s1, 0
	s_add_i32 s2, s0, 0xfffff0bf
	s_lshr_b32 s2, s2, 10
	s_add_i32 s2, s2, 1
	s_cmp_gt_i32 s6, 20
	s_cselect_b32 s6, s2, 0
	s_and_b32 s0, s0, 0x3c0
	s_sub_i32 s0, 0x400, s0
	s_cmp_lg_u32 s1, s6
	s_cselect_b32 s2, s0, 0xc0
	v_readlane_b32 s4, v255, 24
	v_readlane_b32 s5, v255, 25
	v_and_b32_e32 v179, 0x5f, v244
	v_ashrrev_i32_e32 v98, 7, v244
	s_add_u32 s4, s4, s10
	s_addc_u32 s5, s5, s11
	s_mul_i32 s0, s1, 0x6000
	s_mul_i32 s7, s6, 0x6000
	s_add_u32 s0, s4, s0
	s_addc_u32 s1, s5, 0
	s_add_u32 s6, s4, s7
	s_addc_u32 s7, s5, 0
	v_mul_u32_u24_e32 v98, 0x60, v98
	v_lshrrev_b32_e32 v97, 3, v244
	v_and_or_b32 v216, v97, 4, v98
	v_lshlrev_b32_e32 v97, 2, v179
	v_lshl_or_b32 v99, v216, 10, v179
	v_lshlrev_b32_e32 v99, 2, v99
	v_sub_u32_e32 v217, s2, v216
	global_load_dword v214, v97, s[0:1]
	global_load_dword v215, v97, s[6:7]
	global_load_dword v218, v97, s[0:1] offset:128
	global_load_dword v219, v97, s[6:7] offset:128
	v_readlane_b32 s4, v255, 20
	v_readlane_b32 s5, v255, 21
	v_readlane_b32 s10, v255, 22
	v_readlane_b32 s11, v255, 23
	s_add_u32 s4, s4, s8
	s_addc_u32 s5, s5, s9
	s_add_u32 s10, s10, s8
	s_addc_u32 s11, s11, s9
	s_mov_b64 s[0:1], s[4:5]
	global_load_dword v100, v99, s[0:1]
	s_add_u32 s0, s0, 0x1000
	s_addc_u32 s1, s1, 0
	global_load_dword v101, v99, s[0:1]
	s_add_u32 s0, s0, 0x1000
	s_addc_u32 s1, s1, 0
	global_load_dword v102, v99, s[0:1]
	s_add_u32 s0, s0, 0x1000
	s_addc_u32 s1, s1, 0
	global_load_dword v103, v99, s[0:1]
	s_add_u32 s0, s0, 0x5000
	s_addc_u32 s1, s1, 0
	global_load_dword v104, v99, s[0:1]
	s_add_u32 s0, s0, 0x1000
	s_addc_u32 s1, s1, 0
	global_load_dword v105, v99, s[0:1]
	s_add_u32 s0, s0, 0x1000
	s_addc_u32 s1, s1, 0
	global_load_dword v106, v99, s[0:1]
	s_add_u32 s0, s0, 0x1000
	s_addc_u32 s1, s1, 0
	global_load_dword v107, v99, s[0:1]
	s_add_u32 s0, s0, 0x5000
	s_addc_u32 s1, s1, 0
	global_load_dword v108, v99, s[0:1]
	s_add_u32 s0, s0, 0x1000
	s_addc_u32 s1, s1, 0
	global_load_dword v109, v99, s[0:1]
	s_add_u32 s0, s0, 0x1000
	s_addc_u32 s1, s1, 0
	global_load_dword v110, v99, s[0:1]
	s_add_u32 s0, s0, 0x1000
	s_addc_u32 s1, s1, 0
	global_load_dword v111, v99, s[0:1]
	s_add_u32 s0, s0, 0x5000
	s_addc_u32 s1, s1, 0
	global_load_dword v112, v99, s[0:1]
	s_add_u32 s0, s0, 0x1000
	s_addc_u32 s1, s1, 0
	global_load_dword v113, v99, s[0:1]
	s_add_u32 s0, s0, 0x1000
	s_addc_u32 s1, s1, 0
	global_load_dword v114, v99, s[0:1]
	s_add_u32 s0, s0, 0x1000
	s_addc_u32 s1, s1, 0
	global_load_dword v115, v99, s[0:1]
	s_add_u32 s0, s0, 0x5000
	s_addc_u32 s1, s1, 0
	global_load_dword v116, v99, s[0:1]
	s_add_u32 s0, s0, 0x1000
	s_addc_u32 s1, s1, 0
	global_load_dword v117, v99, s[0:1]
	s_add_u32 s0, s0, 0x1000
	s_addc_u32 s1, s1, 0
	global_load_dword v118, v99, s[0:1]
	s_add_u32 s0, s0, 0x1000
	s_addc_u32 s1, s1, 0
	global_load_dword v119, v99, s[0:1]
	s_add_u32 s0, s0, 0x5000
	s_addc_u32 s1, s1, 0
	global_load_dword v120, v99, s[0:1]
	s_add_u32 s0, s0, 0x1000
	s_addc_u32 s1, s1, 0
	global_load_dword v121, v99, s[0:1]
	s_add_u32 s0, s0, 0x1000
	s_addc_u32 s1, s1, 0
	global_load_dword v122, v99, s[0:1]
	s_add_u32 s0, s0, 0x1000
	s_addc_u32 s1, s1, 0
	global_load_dword v123, v99, s[0:1]
	s_add_u32 s0, s0, 0x5000
	s_addc_u32 s1, s1, 0
	global_load_dword v124, v99, s[0:1]
	s_add_u32 s0, s0, 0x1000
	s_addc_u32 s1, s1, 0
	global_load_dword v125, v99, s[0:1]
	s_add_u32 s0, s0, 0x1000
	s_addc_u32 s1, s1, 0
	global_load_dword v126, v99, s[0:1]
	s_add_u32 s0, s0, 0x1000
	s_addc_u32 s1, s1, 0
	global_load_dword v127, v99, s[0:1]
	s_add_u32 s0, s0, 0x5000
	s_addc_u32 s1, s1, 0
	global_load_dword v128, v99, s[0:1]
	s_add_u32 s0, s0, 0x1000
	s_addc_u32 s1, s1, 0
	global_load_dword v129, v99, s[0:1]
	s_add_u32 s0, s0, 0x1000
	s_addc_u32 s1, s1, 0
	global_load_dword v130, v99, s[0:1]
	s_add_u32 s0, s0, 0x1000
	s_addc_u32 s1, s1, 0
	global_load_dword v131, v99, s[0:1]
	s_add_u32 s0, s0, 0x5000
	s_addc_u32 s1, s1, 0
	global_load_dword v132, v99, s[0:1]
	s_add_u32 s0, s0, 0x1000
	s_addc_u32 s1, s1, 0
	global_load_dword v133, v99, s[0:1]
	s_add_u32 s0, s0, 0x1000
	s_addc_u32 s1, s1, 0
	global_load_dword v134, v99, s[0:1]
	s_add_u32 s0, s0, 0x1000
	s_addc_u32 s1, s1, 0
	global_load_dword v135, v99, s[0:1]
	s_add_u32 s0, s0, 0x5000
	s_addc_u32 s1, s1, 0
	global_load_dword v136, v99, s[0:1]
	s_add_u32 s0, s0, 0x1000
	s_addc_u32 s1, s1, 0
	global_load_dword v137, v99, s[0:1]
	s_add_u32 s0, s0, 0x1000
	s_addc_u32 s1, s1, 0
	global_load_dword v138, v99, s[0:1]
	s_add_u32 s0, s0, 0x1000
	s_addc_u32 s1, s1, 0
	global_load_dword v139, v99, s[0:1]
	s_add_u32 s0, s0, 0x5000
	s_addc_u32 s1, s1, 0
	global_load_dword v140, v99, s[0:1]
	s_add_u32 s0, s0, 0x1000
	s_addc_u32 s1, s1, 0
	global_load_dword v141, v99, s[0:1]
	s_add_u32 s0, s0, 0x1000
	s_addc_u32 s1, s1, 0
	global_load_dword v142, v99, s[0:1]
	s_add_u32 s0, s0, 0x1000
	s_addc_u32 s1, s1, 0
	global_load_dword v143, v99, s[0:1]
	s_add_u32 s0, s0, 0x5000
	s_addc_u32 s1, s1, 0
	global_load_dword v144, v99, s[0:1]
	s_add_u32 s0, s0, 0x1000
	s_addc_u32 s1, s1, 0
	global_load_dword v145, v99, s[0:1]
	s_add_u32 s0, s0, 0x1000
	s_addc_u32 s1, s1, 0
	global_load_dword v146, v99, s[0:1]
	s_add_u32 s0, s0, 0x1000
	s_addc_u32 s1, s1, 0
	global_load_dword v147, v99, s[0:1]
	s_waitcnt vmcnt(0)
	v_cmp_lt_i32_e32 vcc, 0, v217
	v_mul_f32_e32 v100, 0x3fd744fd, v100
	s_nop 0
	v_cndmask_b32_e32 v97, v215, v214, vcc
	v_fmac_f32_e32 v100, v80, v97
	v_cmp_lt_i32_e32 vcc, 1, v217
	v_mul_f32_e32 v101, 0x3fd744fd, v101
	s_nop 0
	v_cndmask_b32_e32 v97, v215, v214, vcc
	v_fmac_f32_e32 v101, v81, v97
	v_cmp_lt_i32_e32 vcc, 2, v217
	v_mul_f32_e32 v102, 0x3fd744fd, v102
	s_nop 0
	v_cndmask_b32_e32 v97, v215, v214, vcc
	v_fmac_f32_e32 v102, v82, v97
	v_cmp_lt_i32_e32 vcc, 3, v217
	v_mul_f32_e32 v103, 0x3fd744fd, v103
	s_nop 0
	v_cndmask_b32_e32 v97, v215, v214, vcc
	v_fmac_f32_e32 v103, v83, v97
	v_cmp_lt_i32_e32 vcc, 8, v217
	v_mul_f32_e32 v104, 0x3fd744fd, v104
	s_nop 0
	v_cndmask_b32_e32 v97, v215, v214, vcc
	v_fmac_f32_e32 v104, v84, v97
	v_cmp_lt_i32_e32 vcc, 9, v217
	v_mul_f32_e32 v105, 0x3fd744fd, v105
	s_nop 0
	v_cndmask_b32_e32 v97, v215, v214, vcc
	v_fmac_f32_e32 v105, v85, v97
	v_cmp_lt_i32_e32 vcc, 10, v217
	v_mul_f32_e32 v106, 0x3fd744fd, v106
	s_nop 0
	v_cndmask_b32_e32 v97, v215, v214, vcc
	v_fmac_f32_e32 v106, v86, v97
	v_cmp_lt_i32_e32 vcc, 11, v217
	v_mul_f32_e32 v107, 0x3fd744fd, v107
	s_nop 0
	v_cndmask_b32_e32 v97, v215, v214, vcc
	v_fmac_f32_e32 v107, v87, v97
	v_cmp_lt_i32_e32 vcc, 16, v217
	v_mul_f32_e32 v108, 0x3fd744fd, v108
	s_nop 0
	v_cndmask_b32_e32 v97, v215, v214, vcc
	v_fmac_f32_e32 v108, v88, v97
	v_cmp_lt_i32_e32 vcc, 17, v217
	v_mul_f32_e32 v109, 0x3fd744fd, v109
	s_nop 0
	v_cndmask_b32_e32 v97, v215, v214, vcc
	v_fmac_f32_e32 v109, v89, v97
	v_cmp_lt_i32_e32 vcc, 18, v217
	v_mul_f32_e32 v110, 0x3fd744fd, v110
	s_nop 0
	v_cndmask_b32_e32 v97, v215, v214, vcc
	v_fmac_f32_e32 v110, v90, v97
	v_cmp_lt_i32_e32 vcc, 19, v217
	v_mul_f32_e32 v111, 0x3fd744fd, v111
	s_nop 0
	v_cndmask_b32_e32 v97, v215, v214, vcc
	v_fmac_f32_e32 v111, v91, v97
	v_cmp_lt_i32_e32 vcc, 24, v217
	v_mul_f32_e32 v112, 0x3fd744fd, v112
	s_nop 0
	v_cndmask_b32_e32 v97, v215, v214, vcc
	v_fmac_f32_e32 v112, v92, v97
	v_cmp_lt_i32_e32 vcc, 25, v217
	v_mul_f32_e32 v113, 0x3fd744fd, v113
	s_nop 0
	v_cndmask_b32_e32 v97, v215, v214, vcc
	v_fmac_f32_e32 v113, v93, v97
	v_cmp_lt_i32_e32 vcc, 26, v217
	v_mul_f32_e32 v114, 0x3fd744fd, v114
	s_nop 0
	v_cndmask_b32_e32 v97, v215, v214, vcc
	v_fmac_f32_e32 v114, v94, v97
	v_cmp_lt_i32_e32 vcc, 27, v217
	v_mul_f32_e32 v115, 0x3fd744fd, v115
	s_nop 0
	v_cndmask_b32_e32 v97, v215, v214, vcc
	v_fmac_f32_e32 v115, v95, v97
	v_cmp_lt_i32_e32 vcc, 32, v217
	v_mul_f32_e32 v116, 0x3fd744fd, v116
	s_nop 0
	v_cndmask_b32_e32 v97, v215, v214, vcc
	v_fmac_f32_e32 v116, v64, v97
	v_cmp_lt_i32_e32 vcc, 33, v217
	v_mul_f32_e32 v117, 0x3fd744fd, v117
	s_nop 0
	v_cndmask_b32_e32 v97, v215, v214, vcc
	v_fmac_f32_e32 v117, v65, v97
	v_cmp_lt_i32_e32 vcc, 34, v217
	v_mul_f32_e32 v118, 0x3fd744fd, v118
	s_nop 0
	v_cndmask_b32_e32 v97, v215, v214, vcc
	v_fmac_f32_e32 v118, v66, v97
	v_cmp_lt_i32_e32 vcc, 35, v217
	v_mul_f32_e32 v119, 0x3fd744fd, v119
	s_nop 0
	v_cndmask_b32_e32 v97, v215, v214, vcc
	v_fmac_f32_e32 v119, v67, v97
	v_cmp_lt_i32_e32 vcc, 40, v217
	v_mul_f32_e32 v120, 0x3fd744fd, v120
	s_nop 0
	v_cndmask_b32_e32 v97, v215, v214, vcc
	v_fmac_f32_e32 v120, v68, v97
	v_cmp_lt_i32_e32 vcc, 41, v217
	v_mul_f32_e32 v121, 0x3fd744fd, v121
	s_nop 0
	v_cndmask_b32_e32 v97, v215, v214, vcc
	v_fmac_f32_e32 v121, v69, v97
	v_cmp_lt_i32_e32 vcc, 42, v217
	v_mul_f32_e32 v122, 0x3fd744fd, v122
	s_nop 0
	v_cndmask_b32_e32 v97, v215, v214, vcc
	v_fmac_f32_e32 v122, v70, v97
	v_cmp_lt_i32_e32 vcc, 43, v217
	v_mul_f32_e32 v123, 0x3fd744fd, v123
	s_nop 0
	v_cndmask_b32_e32 v97, v215, v214, vcc
	v_fmac_f32_e32 v123, v71, v97
	v_cmp_lt_i32_e32 vcc, 48, v217
	v_mul_f32_e32 v124, 0x3fd744fd, v124
	s_nop 0
	v_cndmask_b32_e32 v97, v215, v214, vcc
	v_fmac_f32_e32 v124, v72, v97
	v_cmp_lt_i32_e32 vcc, 49, v217
	v_mul_f32_e32 v125, 0x3fd744fd, v125
	s_nop 0
	v_cndmask_b32_e32 v97, v215, v214, vcc
	v_fmac_f32_e32 v125, v73, v97
	v_cmp_lt_i32_e32 vcc, 50, v217
	v_mul_f32_e32 v126, 0x3fd744fd, v126
	s_nop 0
	v_cndmask_b32_e32 v97, v215, v214, vcc
	v_fmac_f32_e32 v126, v74, v97
	v_cmp_lt_i32_e32 vcc, 51, v217
	v_mul_f32_e32 v127, 0x3fd744fd, v127
	s_nop 0
	v_cndmask_b32_e32 v97, v215, v214, vcc
	v_fmac_f32_e32 v127, v75, v97
	v_cmp_lt_i32_e32 vcc, 56, v217
	v_mul_f32_e32 v128, 0x3fd744fd, v128
	s_nop 0
	v_cndmask_b32_e32 v97, v215, v214, vcc
	v_fmac_f32_e32 v128, v76, v97
	v_cmp_lt_i32_e32 vcc, 57, v217
	v_mul_f32_e32 v129, 0x3fd744fd, v129
	s_nop 0
	v_cndmask_b32_e32 v97, v215, v214, vcc
	v_fmac_f32_e32 v129, v77, v97
	v_cmp_lt_i32_e32 vcc, 58, v217
	v_mul_f32_e32 v130, 0x3fd744fd, v130
	s_nop 0
	v_cndmask_b32_e32 v97, v215, v214, vcc
	v_fmac_f32_e32 v130, v78, v97
	v_cmp_lt_i32_e32 vcc, 59, v217
	v_mul_f32_e32 v131, 0x3fd744fd, v131
	s_nop 0
	v_cndmask_b32_e32 v97, v215, v214, vcc
	v_fmac_f32_e32 v131, v79, v97
	v_cmp_lt_i32_e32 vcc, 64, v217
	v_mul_f32_e32 v132, 0x3fd744fd, v132
	s_nop 0
	v_cndmask_b32_e32 v97, v215, v214, vcc
	v_fmac_f32_e32 v132, v48, v97
	v_cmp_lt_i32_e32 vcc, 0x41, v217
	v_mul_f32_e32 v133, 0x3fd744fd, v133
	s_nop 0
	v_cndmask_b32_e32 v97, v215, v214, vcc
	v_fmac_f32_e32 v133, v49, v97
	v_cmp_lt_i32_e32 vcc, 0x42, v217
	v_mul_f32_e32 v134, 0x3fd744fd, v134
	s_nop 0
	v_cndmask_b32_e32 v97, v215, v214, vcc
	v_fmac_f32_e32 v134, v50, v97
	v_cmp_lt_i32_e32 vcc, 0x43, v217
	v_mul_f32_e32 v135, 0x3fd744fd, v135
	s_nop 0
	v_cndmask_b32_e32 v97, v215, v214, vcc
	v_fmac_f32_e32 v135, v51, v97
	v_cmp_lt_i32_e32 vcc, 0x48, v217
	v_mul_f32_e32 v136, 0x3fd744fd, v136
	s_nop 0
	v_cndmask_b32_e32 v97, v215, v214, vcc
	v_fmac_f32_e32 v136, v52, v97
	v_cmp_lt_i32_e32 vcc, 0x49, v217
	v_mul_f32_e32 v137, 0x3fd744fd, v137
	s_nop 0
	v_cndmask_b32_e32 v97, v215, v214, vcc
	v_fmac_f32_e32 v137, v53, v97
	v_cmp_lt_i32_e32 vcc, 0x4a, v217
	v_mul_f32_e32 v138, 0x3fd744fd, v138
	s_nop 0
	v_cndmask_b32_e32 v97, v215, v214, vcc
	v_fmac_f32_e32 v138, v54, v97
	v_cmp_lt_i32_e32 vcc, 0x4b, v217
	v_mul_f32_e32 v139, 0x3fd744fd, v139
	s_nop 0
	v_cndmask_b32_e32 v97, v215, v214, vcc
	v_fmac_f32_e32 v139, v55, v97
	v_cmp_lt_i32_e32 vcc, 0x50, v217
	v_mul_f32_e32 v140, 0x3fd744fd, v140
	s_nop 0
	v_cndmask_b32_e32 v97, v215, v214, vcc
	v_fmac_f32_e32 v140, v56, v97
	v_cmp_lt_i32_e32 vcc, 0x51, v217
	v_mul_f32_e32 v141, 0x3fd744fd, v141
	s_nop 0
	v_cndmask_b32_e32 v97, v215, v214, vcc
	v_fmac_f32_e32 v141, v57, v97
	v_cmp_lt_i32_e32 vcc, 0x52, v217
	v_mul_f32_e32 v142, 0x3fd744fd, v142
	s_nop 0
	v_cndmask_b32_e32 v97, v215, v214, vcc
	v_fmac_f32_e32 v142, v58, v97
	v_cmp_lt_i32_e32 vcc, 0x53, v217
	v_mul_f32_e32 v143, 0x3fd744fd, v143
	s_nop 0
	v_cndmask_b32_e32 v97, v215, v214, vcc
	v_fmac_f32_e32 v143, v59, v97
	v_cmp_lt_i32_e32 vcc, 0x58, v217
	v_mul_f32_e32 v144, 0x3fd744fd, v144
	s_nop 0
	v_cndmask_b32_e32 v97, v215, v214, vcc
	v_fmac_f32_e32 v144, v60, v97
	v_cmp_lt_i32_e32 vcc, 0x59, v217
	v_mul_f32_e32 v145, 0x3fd744fd, v145
	s_nop 0
	v_cndmask_b32_e32 v97, v215, v214, vcc
	v_fmac_f32_e32 v145, v61, v97
	v_cmp_lt_i32_e32 vcc, 0x5a, v217
	v_mul_f32_e32 v146, 0x3fd744fd, v146
	s_nop 0
	v_cndmask_b32_e32 v97, v215, v214, vcc
	v_fmac_f32_e32 v146, v62, v97
	v_cmp_lt_i32_e32 vcc, 0x5b, v217
	v_mul_f32_e32 v147, 0x3fd744fd, v147
	s_nop 0
	v_cndmask_b32_e32 v97, v215, v214, vcc
	v_fmac_f32_e32 v147, v63, v97
	s_mov_b64 s[0:1], s[10:11]
	global_store_dword v99, v100, s[0:1]
	s_add_u32 s0, s0, 0x1000
	s_addc_u32 s1, s1, 0
	global_store_dword v99, v101, s[0:1]
	s_add_u32 s0, s0, 0x1000
	s_addc_u32 s1, s1, 0
	global_store_dword v99, v102, s[0:1]
	s_add_u32 s0, s0, 0x1000
	s_addc_u32 s1, s1, 0
	global_store_dword v99, v103, s[0:1]
	s_add_u32 s0, s0, 0x5000
	s_addc_u32 s1, s1, 0
	global_store_dword v99, v104, s[0:1]
	s_add_u32 s0, s0, 0x1000
	s_addc_u32 s1, s1, 0
	global_store_dword v99, v105, s[0:1]
	s_add_u32 s0, s0, 0x1000
	s_addc_u32 s1, s1, 0
	global_store_dword v99, v106, s[0:1]
	s_add_u32 s0, s0, 0x1000
	s_addc_u32 s1, s1, 0
	global_store_dword v99, v107, s[0:1]
	s_add_u32 s0, s0, 0x5000
	s_addc_u32 s1, s1, 0
	global_store_dword v99, v108, s[0:1]
	s_add_u32 s0, s0, 0x1000
	s_addc_u32 s1, s1, 0
	global_store_dword v99, v109, s[0:1]
	s_add_u32 s0, s0, 0x1000
	s_addc_u32 s1, s1, 0
	global_store_dword v99, v110, s[0:1]
	s_add_u32 s0, s0, 0x1000
	s_addc_u32 s1, s1, 0
	global_store_dword v99, v111, s[0:1]
	s_add_u32 s0, s0, 0x5000
	s_addc_u32 s1, s1, 0
	global_store_dword v99, v112, s[0:1]
	s_add_u32 s0, s0, 0x1000
	s_addc_u32 s1, s1, 0
	global_store_dword v99, v113, s[0:1]
	s_add_u32 s0, s0, 0x1000
	s_addc_u32 s1, s1, 0
	global_store_dword v99, v114, s[0:1]
	s_add_u32 s0, s0, 0x1000
	s_addc_u32 s1, s1, 0
	global_store_dword v99, v115, s[0:1]
	s_add_u32 s0, s0, 0x5000
	s_addc_u32 s1, s1, 0
	global_store_dword v99, v116, s[0:1]
	s_add_u32 s0, s0, 0x1000
	s_addc_u32 s1, s1, 0
	global_store_dword v99, v117, s[0:1]
	s_add_u32 s0, s0, 0x1000
	s_addc_u32 s1, s1, 0
	global_store_dword v99, v118, s[0:1]
	s_add_u32 s0, s0, 0x1000
	s_addc_u32 s1, s1, 0
	global_store_dword v99, v119, s[0:1]
	s_add_u32 s0, s0, 0x5000
	s_addc_u32 s1, s1, 0
	global_store_dword v99, v120, s[0:1]
	s_add_u32 s0, s0, 0x1000
	s_addc_u32 s1, s1, 0
	global_store_dword v99, v121, s[0:1]
	s_add_u32 s0, s0, 0x1000
	s_addc_u32 s1, s1, 0
	global_store_dword v99, v122, s[0:1]
	s_add_u32 s0, s0, 0x1000
	s_addc_u32 s1, s1, 0
	global_store_dword v99, v123, s[0:1]
	s_add_u32 s0, s0, 0x5000
	s_addc_u32 s1, s1, 0
	global_store_dword v99, v124, s[0:1]
	s_add_u32 s0, s0, 0x1000
	s_addc_u32 s1, s1, 0
	global_store_dword v99, v125, s[0:1]
	s_add_u32 s0, s0, 0x1000
	s_addc_u32 s1, s1, 0
	global_store_dword v99, v126, s[0:1]
	s_add_u32 s0, s0, 0x1000
	s_addc_u32 s1, s1, 0
	global_store_dword v99, v127, s[0:1]
	s_add_u32 s0, s0, 0x5000
	s_addc_u32 s1, s1, 0
	global_store_dword v99, v128, s[0:1]
	s_add_u32 s0, s0, 0x1000
	s_addc_u32 s1, s1, 0
	global_store_dword v99, v129, s[0:1]
	s_add_u32 s0, s0, 0x1000
	s_addc_u32 s1, s1, 0
	global_store_dword v99, v130, s[0:1]
	s_add_u32 s0, s0, 0x1000
	s_addc_u32 s1, s1, 0
	global_store_dword v99, v131, s[0:1]
	s_add_u32 s0, s0, 0x5000
	s_addc_u32 s1, s1, 0
	global_store_dword v99, v132, s[0:1]
	s_add_u32 s0, s0, 0x1000
	s_addc_u32 s1, s1, 0
	global_store_dword v99, v133, s[0:1]
	s_add_u32 s0, s0, 0x1000
	s_addc_u32 s1, s1, 0
	global_store_dword v99, v134, s[0:1]
	s_add_u32 s0, s0, 0x1000
	s_addc_u32 s1, s1, 0
	global_store_dword v99, v135, s[0:1]
	s_add_u32 s0, s0, 0x5000
	s_addc_u32 s1, s1, 0
	global_store_dword v99, v136, s[0:1]
	s_add_u32 s0, s0, 0x1000
	s_addc_u32 s1, s1, 0
	global_store_dword v99, v137, s[0:1]
	s_add_u32 s0, s0, 0x1000
	s_addc_u32 s1, s1, 0
	global_store_dword v99, v138, s[0:1]
	s_add_u32 s0, s0, 0x1000
	s_addc_u32 s1, s1, 0
	global_store_dword v99, v139, s[0:1]
	s_add_u32 s0, s0, 0x5000
	s_addc_u32 s1, s1, 0
	global_store_dword v99, v140, s[0:1]
	s_add_u32 s0, s0, 0x1000
	s_addc_u32 s1, s1, 0
	global_store_dword v99, v141, s[0:1]
	s_add_u32 s0, s0, 0x1000
	s_addc_u32 s1, s1, 0
	global_store_dword v99, v142, s[0:1]
	s_add_u32 s0, s0, 0x1000
	s_addc_u32 s1, s1, 0
	global_store_dword v99, v143, s[0:1]
	s_add_u32 s0, s0, 0x5000
	s_addc_u32 s1, s1, 0
	global_store_dword v99, v144, s[0:1]
	s_add_u32 s0, s0, 0x1000
	s_addc_u32 s1, s1, 0
	global_store_dword v99, v145, s[0:1]
	s_add_u32 s0, s0, 0x1000
	s_addc_u32 s1, s1, 0
	global_store_dword v99, v146, s[0:1]
	s_add_u32 s0, s0, 0x1000
	s_addc_u32 s1, s1, 0
	global_store_dword v99, v147, s[0:1]
	s_mov_b64 s[0:1], s[4:5]
	global_load_dword v100, v99, s[0:1] offset:128
	s_add_u32 s0, s0, 0x1000
	s_addc_u32 s1, s1, 0
	global_load_dword v101, v99, s[0:1] offset:128
	s_add_u32 s0, s0, 0x1000
	s_addc_u32 s1, s1, 0
	global_load_dword v102, v99, s[0:1] offset:128
	s_add_u32 s0, s0, 0x1000
	s_addc_u32 s1, s1, 0
	global_load_dword v103, v99, s[0:1] offset:128
	s_add_u32 s0, s0, 0x5000
	s_addc_u32 s1, s1, 0
	global_load_dword v104, v99, s[0:1] offset:128
	s_add_u32 s0, s0, 0x1000
	s_addc_u32 s1, s1, 0
	global_load_dword v105, v99, s[0:1] offset:128
	s_add_u32 s0, s0, 0x1000
	s_addc_u32 s1, s1, 0
	global_load_dword v106, v99, s[0:1] offset:128
	s_add_u32 s0, s0, 0x1000
	s_addc_u32 s1, s1, 0
	global_load_dword v107, v99, s[0:1] offset:128
	s_add_u32 s0, s0, 0x5000
	s_addc_u32 s1, s1, 0
	global_load_dword v108, v99, s[0:1] offset:128
	s_add_u32 s0, s0, 0x1000
	s_addc_u32 s1, s1, 0
	global_load_dword v109, v99, s[0:1] offset:128
	s_add_u32 s0, s0, 0x1000
	s_addc_u32 s1, s1, 0
	global_load_dword v110, v99, s[0:1] offset:128
	s_add_u32 s0, s0, 0x1000
	s_addc_u32 s1, s1, 0
	global_load_dword v111, v99, s[0:1] offset:128
	s_add_u32 s0, s0, 0x5000
	s_addc_u32 s1, s1, 0
	global_load_dword v112, v99, s[0:1] offset:128
	s_add_u32 s0, s0, 0x1000
	s_addc_u32 s1, s1, 0
	global_load_dword v113, v99, s[0:1] offset:128
	s_add_u32 s0, s0, 0x1000
	s_addc_u32 s1, s1, 0
	global_load_dword v114, v99, s[0:1] offset:128
	s_add_u32 s0, s0, 0x1000
	s_addc_u32 s1, s1, 0
	global_load_dword v115, v99, s[0:1] offset:128
	s_add_u32 s0, s0, 0x5000
	s_addc_u32 s1, s1, 0
	global_load_dword v116, v99, s[0:1] offset:128
	s_add_u32 s0, s0, 0x1000
	s_addc_u32 s1, s1, 0
	global_load_dword v117, v99, s[0:1] offset:128
	s_add_u32 s0, s0, 0x1000
	s_addc_u32 s1, s1, 0
	global_load_dword v118, v99, s[0:1] offset:128
	s_add_u32 s0, s0, 0x1000
	s_addc_u32 s1, s1, 0
	global_load_dword v119, v99, s[0:1] offset:128
	s_add_u32 s0, s0, 0x5000
	s_addc_u32 s1, s1, 0
	global_load_dword v120, v99, s[0:1] offset:128
	s_add_u32 s0, s0, 0x1000
	s_addc_u32 s1, s1, 0
	global_load_dword v121, v99, s[0:1] offset:128
	s_add_u32 s0, s0, 0x1000
	s_addc_u32 s1, s1, 0
	global_load_dword v122, v99, s[0:1] offset:128
	s_add_u32 s0, s0, 0x1000
	s_addc_u32 s1, s1, 0
	global_load_dword v123, v99, s[0:1] offset:128
	s_add_u32 s0, s0, 0x5000
	s_addc_u32 s1, s1, 0
	global_load_dword v124, v99, s[0:1] offset:128
	s_add_u32 s0, s0, 0x1000
	s_addc_u32 s1, s1, 0
	global_load_dword v125, v99, s[0:1] offset:128
	s_add_u32 s0, s0, 0x1000
	s_addc_u32 s1, s1, 0
	global_load_dword v126, v99, s[0:1] offset:128
	s_add_u32 s0, s0, 0x1000
	s_addc_u32 s1, s1, 0
	global_load_dword v127, v99, s[0:1] offset:128
	s_add_u32 s0, s0, 0x5000
	s_addc_u32 s1, s1, 0
	global_load_dword v128, v99, s[0:1] offset:128
	s_add_u32 s0, s0, 0x1000
	s_addc_u32 s1, s1, 0
	global_load_dword v129, v99, s[0:1] offset:128
	s_add_u32 s0, s0, 0x1000
	s_addc_u32 s1, s1, 0
	global_load_dword v130, v99, s[0:1] offset:128
	s_add_u32 s0, s0, 0x1000
	s_addc_u32 s1, s1, 0
	global_load_dword v131, v99, s[0:1] offset:128
	s_add_u32 s0, s0, 0x5000
	s_addc_u32 s1, s1, 0
	global_load_dword v132, v99, s[0:1] offset:128
	s_add_u32 s0, s0, 0x1000
	s_addc_u32 s1, s1, 0
	global_load_dword v133, v99, s[0:1] offset:128
	s_add_u32 s0, s0, 0x1000
	s_addc_u32 s1, s1, 0
	global_load_dword v134, v99, s[0:1] offset:128
	s_add_u32 s0, s0, 0x1000
	s_addc_u32 s1, s1, 0
	global_load_dword v135, v99, s[0:1] offset:128
	s_add_u32 s0, s0, 0x5000
	s_addc_u32 s1, s1, 0
	global_load_dword v136, v99, s[0:1] offset:128
	s_add_u32 s0, s0, 0x1000
	s_addc_u32 s1, s1, 0
	global_load_dword v137, v99, s[0:1] offset:128
	s_add_u32 s0, s0, 0x1000
	s_addc_u32 s1, s1, 0
	global_load_dword v138, v99, s[0:1] offset:128
	s_add_u32 s0, s0, 0x1000
	s_addc_u32 s1, s1, 0
	global_load_dword v139, v99, s[0:1] offset:128
	s_add_u32 s0, s0, 0x5000
	s_addc_u32 s1, s1, 0
	global_load_dword v140, v99, s[0:1] offset:128
	s_add_u32 s0, s0, 0x1000
	s_addc_u32 s1, s1, 0
	global_load_dword v141, v99, s[0:1] offset:128
	s_add_u32 s0, s0, 0x1000
	s_addc_u32 s1, s1, 0
	global_load_dword v142, v99, s[0:1] offset:128
	s_add_u32 s0, s0, 0x1000
	s_addc_u32 s1, s1, 0
	global_load_dword v143, v99, s[0:1] offset:128
	s_add_u32 s0, s0, 0x5000
	s_addc_u32 s1, s1, 0
	global_load_dword v144, v99, s[0:1] offset:128
	s_add_u32 s0, s0, 0x1000
	s_addc_u32 s1, s1, 0
	global_load_dword v145, v99, s[0:1] offset:128
	s_add_u32 s0, s0, 0x1000
	s_addc_u32 s1, s1, 0
	global_load_dword v146, v99, s[0:1] offset:128
	s_add_u32 s0, s0, 0x1000
	s_addc_u32 s1, s1, 0
	global_load_dword v147, v99, s[0:1] offset:128
	s_waitcnt vmcnt(0)
	v_cmp_lt_i32_e32 vcc, 0, v217
	v_mul_f32_e32 v100, 0x3fd744fd, v100
	s_nop 0
	v_cndmask_b32_e32 v97, v219, v218, vcc
	v_fmac_f32_e32 v100, v32, v97
	v_cmp_lt_i32_e32 vcc, 1, v217
	v_mul_f32_e32 v101, 0x3fd744fd, v101
	s_nop 0
	v_cndmask_b32_e32 v97, v219, v218, vcc
	v_fmac_f32_e32 v101, v33, v97
	v_cmp_lt_i32_e32 vcc, 2, v217
	v_mul_f32_e32 v102, 0x3fd744fd, v102
	s_nop 0
	v_cndmask_b32_e32 v97, v219, v218, vcc
	v_fmac_f32_e32 v102, v34, v97
	v_cmp_lt_i32_e32 vcc, 3, v217
	v_mul_f32_e32 v103, 0x3fd744fd, v103
	s_nop 0
	v_cndmask_b32_e32 v97, v219, v218, vcc
	v_fmac_f32_e32 v103, v35, v97
	v_cmp_lt_i32_e32 vcc, 8, v217
	v_mul_f32_e32 v104, 0x3fd744fd, v104
	s_nop 0
	v_cndmask_b32_e32 v97, v219, v218, vcc
	v_fmac_f32_e32 v104, v36, v97
	v_cmp_lt_i32_e32 vcc, 9, v217
	v_mul_f32_e32 v105, 0x3fd744fd, v105
	s_nop 0
	v_cndmask_b32_e32 v97, v219, v218, vcc
	v_fmac_f32_e32 v105, v37, v97
	v_cmp_lt_i32_e32 vcc, 10, v217
	v_mul_f32_e32 v106, 0x3fd744fd, v106
	s_nop 0
	v_cndmask_b32_e32 v97, v219, v218, vcc
	v_fmac_f32_e32 v106, v38, v97
	v_cmp_lt_i32_e32 vcc, 11, v217
	v_mul_f32_e32 v107, 0x3fd744fd, v107
	s_nop 0
	v_cndmask_b32_e32 v97, v219, v218, vcc
	v_fmac_f32_e32 v107, v39, v97
	v_cmp_lt_i32_e32 vcc, 16, v217
	v_mul_f32_e32 v108, 0x3fd744fd, v108
	s_nop 0
	v_cndmask_b32_e32 v97, v219, v218, vcc
	v_fmac_f32_e32 v108, v40, v97
	v_cmp_lt_i32_e32 vcc, 17, v217
	v_mul_f32_e32 v109, 0x3fd744fd, v109
	s_nop 0
	v_cndmask_b32_e32 v97, v219, v218, vcc
	v_fmac_f32_e32 v109, v41, v97
	v_cmp_lt_i32_e32 vcc, 18, v217
	v_mul_f32_e32 v110, 0x3fd744fd, v110
	s_nop 0
	v_cndmask_b32_e32 v97, v219, v218, vcc
	v_fmac_f32_e32 v110, v42, v97
	v_cmp_lt_i32_e32 vcc, 19, v217
	v_mul_f32_e32 v111, 0x3fd744fd, v111
	s_nop 0
	v_cndmask_b32_e32 v97, v219, v218, vcc
	v_fmac_f32_e32 v111, v43, v97
	v_cmp_lt_i32_e32 vcc, 24, v217
	v_mul_f32_e32 v112, 0x3fd744fd, v112
	s_nop 0
	v_cndmask_b32_e32 v97, v219, v218, vcc
	v_fmac_f32_e32 v112, v44, v97
	v_cmp_lt_i32_e32 vcc, 25, v217
	v_mul_f32_e32 v113, 0x3fd744fd, v113
	s_nop 0
	v_cndmask_b32_e32 v97, v219, v218, vcc
	v_fmac_f32_e32 v113, v45, v97
	v_cmp_lt_i32_e32 vcc, 26, v217
	v_mul_f32_e32 v114, 0x3fd744fd, v114
	s_nop 0
	v_cndmask_b32_e32 v97, v219, v218, vcc
	v_fmac_f32_e32 v114, v46, v97
	v_cmp_lt_i32_e32 vcc, 27, v217
	v_mul_f32_e32 v115, 0x3fd744fd, v115
	s_nop 0
	v_cndmask_b32_e32 v97, v219, v218, vcc
	v_fmac_f32_e32 v115, v47, v97
	v_cmp_lt_i32_e32 vcc, 32, v217
	v_mul_f32_e32 v116, 0x3fd744fd, v116
	s_nop 0
	v_cndmask_b32_e32 v97, v219, v218, vcc
	v_fmac_f32_e32 v116, v16, v97
	v_cmp_lt_i32_e32 vcc, 33, v217
	v_mul_f32_e32 v117, 0x3fd744fd, v117
	s_nop 0
	v_cndmask_b32_e32 v97, v219, v218, vcc
	v_fmac_f32_e32 v117, v17, v97
	v_cmp_lt_i32_e32 vcc, 34, v217
	v_mul_f32_e32 v118, 0x3fd744fd, v118
	s_nop 0
	v_cndmask_b32_e32 v97, v219, v218, vcc
	v_fmac_f32_e32 v118, v18, v97
	v_cmp_lt_i32_e32 vcc, 35, v217
	v_mul_f32_e32 v119, 0x3fd744fd, v119
	s_nop 0
	v_cndmask_b32_e32 v97, v219, v218, vcc
	v_fmac_f32_e32 v119, v19, v97
	v_cmp_lt_i32_e32 vcc, 40, v217
	v_mul_f32_e32 v120, 0x3fd744fd, v120
	s_nop 0
	v_cndmask_b32_e32 v97, v219, v218, vcc
	v_fmac_f32_e32 v120, v20, v97
	v_cmp_lt_i32_e32 vcc, 41, v217
	v_mul_f32_e32 v121, 0x3fd744fd, v121
	s_nop 0
	v_cndmask_b32_e32 v97, v219, v218, vcc
	v_fmac_f32_e32 v121, v21, v97
	v_cmp_lt_i32_e32 vcc, 42, v217
	v_mul_f32_e32 v122, 0x3fd744fd, v122
	s_nop 0
	v_cndmask_b32_e32 v97, v219, v218, vcc
	v_fmac_f32_e32 v122, v22, v97
	v_cmp_lt_i32_e32 vcc, 43, v217
	v_mul_f32_e32 v123, 0x3fd744fd, v123
	s_nop 0
	v_cndmask_b32_e32 v97, v219, v218, vcc
	v_fmac_f32_e32 v123, v23, v97
	v_cmp_lt_i32_e32 vcc, 48, v217
	v_mul_f32_e32 v124, 0x3fd744fd, v124
	s_nop 0
	v_cndmask_b32_e32 v97, v219, v218, vcc
	v_fmac_f32_e32 v124, v24, v97
	v_cmp_lt_i32_e32 vcc, 49, v217
	v_mul_f32_e32 v125, 0x3fd744fd, v125
	s_nop 0
	v_cndmask_b32_e32 v97, v219, v218, vcc
	v_fmac_f32_e32 v125, v25, v97
	v_cmp_lt_i32_e32 vcc, 50, v217
	v_mul_f32_e32 v126, 0x3fd744fd, v126
	s_nop 0
	v_cndmask_b32_e32 v97, v219, v218, vcc
	v_fmac_f32_e32 v126, v26, v97
	v_cmp_lt_i32_e32 vcc, 51, v217
	v_mul_f32_e32 v127, 0x3fd744fd, v127
	s_nop 0
	v_cndmask_b32_e32 v97, v219, v218, vcc
	v_fmac_f32_e32 v127, v27, v97
	v_cmp_lt_i32_e32 vcc, 56, v217
	v_mul_f32_e32 v128, 0x3fd744fd, v128
	s_nop 0
	v_cndmask_b32_e32 v97, v219, v218, vcc
	v_fmac_f32_e32 v128, v28, v97
	v_cmp_lt_i32_e32 vcc, 57, v217
	v_mul_f32_e32 v129, 0x3fd744fd, v129
	s_nop 0
	v_cndmask_b32_e32 v97, v219, v218, vcc
	v_fmac_f32_e32 v129, v29, v97
	v_cmp_lt_i32_e32 vcc, 58, v217
	v_mul_f32_e32 v130, 0x3fd744fd, v130
	s_nop 0
	v_cndmask_b32_e32 v97, v219, v218, vcc
	v_fmac_f32_e32 v130, v30, v97
	v_cmp_lt_i32_e32 vcc, 59, v217
	v_mul_f32_e32 v131, 0x3fd744fd, v131
	s_nop 0
	v_cndmask_b32_e32 v97, v219, v218, vcc
	v_fmac_f32_e32 v131, v31, v97
	v_cmp_lt_i32_e32 vcc, 64, v217
	v_mul_f32_e32 v132, 0x3fd744fd, v132
	s_nop 0
	v_cndmask_b32_e32 v97, v219, v218, vcc
	v_fmac_f32_e32 v132, v0, v97
	v_cmp_lt_i32_e32 vcc, 0x41, v217
	v_mul_f32_e32 v133, 0x3fd744fd, v133
	s_nop 0
	v_cndmask_b32_e32 v97, v219, v218, vcc
	v_fmac_f32_e32 v133, v1, v97
	v_cmp_lt_i32_e32 vcc, 0x42, v217
	v_mul_f32_e32 v134, 0x3fd744fd, v134
	s_nop 0
	v_cndmask_b32_e32 v97, v219, v218, vcc
	v_fmac_f32_e32 v134, v2, v97
	v_cmp_lt_i32_e32 vcc, 0x43, v217
	v_mul_f32_e32 v135, 0x3fd744fd, v135
	s_nop 0
	v_cndmask_b32_e32 v97, v219, v218, vcc
	v_fmac_f32_e32 v135, v3, v97
	v_cmp_lt_i32_e32 vcc, 0x48, v217
	v_mul_f32_e32 v136, 0x3fd744fd, v136
	s_nop 0
	v_cndmask_b32_e32 v97, v219, v218, vcc
	v_fmac_f32_e32 v136, v4, v97
	v_cmp_lt_i32_e32 vcc, 0x49, v217
	v_mul_f32_e32 v137, 0x3fd744fd, v137
	s_nop 0
	v_cndmask_b32_e32 v97, v219, v218, vcc
	v_fmac_f32_e32 v137, v5, v97
	v_cmp_lt_i32_e32 vcc, 0x4a, v217
	v_mul_f32_e32 v138, 0x3fd744fd, v138
	s_nop 0
	v_cndmask_b32_e32 v97, v219, v218, vcc
	v_fmac_f32_e32 v138, v6, v97
	v_cmp_lt_i32_e32 vcc, 0x4b, v217
	v_mul_f32_e32 v139, 0x3fd744fd, v139
	s_nop 0
	v_cndmask_b32_e32 v97, v219, v218, vcc
	v_fmac_f32_e32 v139, v7, v97
	v_cmp_lt_i32_e32 vcc, 0x50, v217
	v_mul_f32_e32 v140, 0x3fd744fd, v140
	s_nop 0
	v_cndmask_b32_e32 v97, v219, v218, vcc
	v_fmac_f32_e32 v140, v8, v97
	v_cmp_lt_i32_e32 vcc, 0x51, v217
	v_mul_f32_e32 v141, 0x3fd744fd, v141
	s_nop 0
	v_cndmask_b32_e32 v97, v219, v218, vcc
	v_fmac_f32_e32 v141, v9, v97
	v_cmp_lt_i32_e32 vcc, 0x52, v217
	v_mul_f32_e32 v142, 0x3fd744fd, v142
	s_nop 0
	v_cndmask_b32_e32 v97, v219, v218, vcc
	v_fmac_f32_e32 v142, v10, v97
	v_cmp_lt_i32_e32 vcc, 0x53, v217
	v_mul_f32_e32 v143, 0x3fd744fd, v143
	s_nop 0
	v_cndmask_b32_e32 v97, v219, v218, vcc
	v_fmac_f32_e32 v143, v11, v97
	v_cmp_lt_i32_e32 vcc, 0x58, v217
	v_mul_f32_e32 v144, 0x3fd744fd, v144
	s_nop 0
	v_cndmask_b32_e32 v97, v219, v218, vcc
	v_fmac_f32_e32 v144, v12, v97
	v_cmp_lt_i32_e32 vcc, 0x59, v217
	v_mul_f32_e32 v145, 0x3fd744fd, v145
	s_nop 0
	v_cndmask_b32_e32 v97, v219, v218, vcc
	v_fmac_f32_e32 v145, v13, v97
	v_cmp_lt_i32_e32 vcc, 0x5a, v217
	v_mul_f32_e32 v146, 0x3fd744fd, v146
	s_nop 0
	v_cndmask_b32_e32 v97, v219, v218, vcc
	v_fmac_f32_e32 v146, v14, v97
	v_cmp_lt_i32_e32 vcc, 0x5b, v217
	v_mul_f32_e32 v147, 0x3fd744fd, v147
	s_nop 0
	v_cndmask_b32_e32 v97, v219, v218, vcc
	v_fmac_f32_e32 v147, v15, v97
	s_mov_b64 s[0:1], s[10:11]
	global_store_dword v99, v100, s[0:1] offset:128
	s_add_u32 s0, s0, 0x1000
	s_addc_u32 s1, s1, 0
	global_store_dword v99, v101, s[0:1] offset:128
	s_add_u32 s0, s0, 0x1000
	s_addc_u32 s1, s1, 0
	global_store_dword v99, v102, s[0:1] offset:128
	s_add_u32 s0, s0, 0x1000
	s_addc_u32 s1, s1, 0
	global_store_dword v99, v103, s[0:1] offset:128
	s_add_u32 s0, s0, 0x5000
	s_addc_u32 s1, s1, 0
	global_store_dword v99, v104, s[0:1] offset:128
	s_add_u32 s0, s0, 0x1000
	s_addc_u32 s1, s1, 0
	global_store_dword v99, v105, s[0:1] offset:128
	s_add_u32 s0, s0, 0x1000
	s_addc_u32 s1, s1, 0
	global_store_dword v99, v106, s[0:1] offset:128
	s_add_u32 s0, s0, 0x1000
	s_addc_u32 s1, s1, 0
	global_store_dword v99, v107, s[0:1] offset:128
	s_add_u32 s0, s0, 0x5000
	s_addc_u32 s1, s1, 0
	global_store_dword v99, v108, s[0:1] offset:128
	s_add_u32 s0, s0, 0x1000
	s_addc_u32 s1, s1, 0
	global_store_dword v99, v109, s[0:1] offset:128
	s_add_u32 s0, s0, 0x1000
	s_addc_u32 s1, s1, 0
	global_store_dword v99, v110, s[0:1] offset:128
	s_add_u32 s0, s0, 0x1000
	s_addc_u32 s1, s1, 0
	global_store_dword v99, v111, s[0:1] offset:128
	s_add_u32 s0, s0, 0x5000
	s_addc_u32 s1, s1, 0
	global_store_dword v99, v112, s[0:1] offset:128
	s_add_u32 s0, s0, 0x1000
	s_addc_u32 s1, s1, 0
	global_store_dword v99, v113, s[0:1] offset:128
	s_add_u32 s0, s0, 0x1000
	s_addc_u32 s1, s1, 0
	global_store_dword v99, v114, s[0:1] offset:128
	s_add_u32 s0, s0, 0x1000
	s_addc_u32 s1, s1, 0
	global_store_dword v99, v115, s[0:1] offset:128
	s_add_u32 s0, s0, 0x5000
	s_addc_u32 s1, s1, 0
	global_store_dword v99, v116, s[0:1] offset:128
	s_add_u32 s0, s0, 0x1000
	s_addc_u32 s1, s1, 0
	global_store_dword v99, v117, s[0:1] offset:128
	s_add_u32 s0, s0, 0x1000
	s_addc_u32 s1, s1, 0
	global_store_dword v99, v118, s[0:1] offset:128
	s_add_u32 s0, s0, 0x1000
	s_addc_u32 s1, s1, 0
	global_store_dword v99, v119, s[0:1] offset:128
	s_add_u32 s0, s0, 0x5000
	s_addc_u32 s1, s1, 0
	global_store_dword v99, v120, s[0:1] offset:128
	s_add_u32 s0, s0, 0x1000
	s_addc_u32 s1, s1, 0
	global_store_dword v99, v121, s[0:1] offset:128
	s_add_u32 s0, s0, 0x1000
	s_addc_u32 s1, s1, 0
	global_store_dword v99, v122, s[0:1] offset:128
	s_add_u32 s0, s0, 0x1000
	s_addc_u32 s1, s1, 0
	global_store_dword v99, v123, s[0:1] offset:128
	s_add_u32 s0, s0, 0x5000
	s_addc_u32 s1, s1, 0
	global_store_dword v99, v124, s[0:1] offset:128
	s_add_u32 s0, s0, 0x1000
	s_addc_u32 s1, s1, 0
	global_store_dword v99, v125, s[0:1] offset:128
	s_add_u32 s0, s0, 0x1000
	s_addc_u32 s1, s1, 0
	global_store_dword v99, v126, s[0:1] offset:128
	s_add_u32 s0, s0, 0x1000
	s_addc_u32 s1, s1, 0
	global_store_dword v99, v127, s[0:1] offset:128
	s_add_u32 s0, s0, 0x5000
	s_addc_u32 s1, s1, 0
	global_store_dword v99, v128, s[0:1] offset:128
	s_add_u32 s0, s0, 0x1000
	s_addc_u32 s1, s1, 0
	global_store_dword v99, v129, s[0:1] offset:128
	s_add_u32 s0, s0, 0x1000
	s_addc_u32 s1, s1, 0
	global_store_dword v99, v130, s[0:1] offset:128
	s_add_u32 s0, s0, 0x1000
	s_addc_u32 s1, s1, 0
	global_store_dword v99, v131, s[0:1] offset:128
	s_add_u32 s0, s0, 0x5000
	s_addc_u32 s1, s1, 0
	global_store_dword v99, v132, s[0:1] offset:128
	s_add_u32 s0, s0, 0x1000
	s_addc_u32 s1, s1, 0
	global_store_dword v99, v133, s[0:1] offset:128
	s_add_u32 s0, s0, 0x1000
	s_addc_u32 s1, s1, 0
	global_store_dword v99, v134, s[0:1] offset:128
	s_add_u32 s0, s0, 0x1000
	s_addc_u32 s1, s1, 0
	global_store_dword v99, v135, s[0:1] offset:128
	s_add_u32 s0, s0, 0x5000
	s_addc_u32 s1, s1, 0
	global_store_dword v99, v136, s[0:1] offset:128
	s_add_u32 s0, s0, 0x1000
	s_addc_u32 s1, s1, 0
	global_store_dword v99, v137, s[0:1] offset:128
	s_add_u32 s0, s0, 0x1000
	s_addc_u32 s1, s1, 0
	global_store_dword v99, v138, s[0:1] offset:128
	s_add_u32 s0, s0, 0x1000
	s_addc_u32 s1, s1, 0
	global_store_dword v99, v139, s[0:1] offset:128
	s_add_u32 s0, s0, 0x5000
	s_addc_u32 s1, s1, 0
	global_store_dword v99, v140, s[0:1] offset:128
	s_add_u32 s0, s0, 0x1000
	s_addc_u32 s1, s1, 0
	global_store_dword v99, v141, s[0:1] offset:128
	s_add_u32 s0, s0, 0x1000
	s_addc_u32 s1, s1, 0
	global_store_dword v99, v142, s[0:1] offset:128
	s_add_u32 s0, s0, 0x1000
	s_addc_u32 s1, s1, 0
	global_store_dword v99, v143, s[0:1] offset:128
	s_add_u32 s0, s0, 0x5000
	s_addc_u32 s1, s1, 0
	global_store_dword v99, v144, s[0:1] offset:128
	s_add_u32 s0, s0, 0x1000
	s_addc_u32 s1, s1, 0
	global_store_dword v99, v145, s[0:1] offset:128
	s_add_u32 s0, s0, 0x1000
	s_addc_u32 s1, s1, 0
	global_store_dword v99, v146, s[0:1] offset:128
	s_add_u32 s0, s0, 0x1000
	s_addc_u32 s1, s1, 0
	global_store_dword v99, v147, s[0:1] offset:128
	v_readlane_b32 s0, v255, 9
	s_add_i32 s33, s33, s0
	s_cmpk_lt_i32 s33, 0x200
	s_movk_i32 s45, 0x60
	s_mov_b64 s[50:51], 0x50000
	s_mov_b64 s[62:63], 0x40000
	s_mov_b64 s[64:65], 0x20080
	s_mov_b64 s[66:67], 0x30080
	s_mov_b64 s[70:71], 0x30180
	s_mov_b64 s[96:97], 0x10080
	s_mov_b64 s[94:95], 0x80
	s_mov_b64 s[92:93], 0x30000
	s_movk_i32 s85, 0x90
	s_mov_b64 s[80:81], 0x40080
	s_mov_b64 s[76:77], 0x10180
	s_cbranch_scc1 .LBB0_837
	v_readlane_b32 s86, v255, 3
	v_readlane_b32 s90, v255, 5
	v_readlane_b32 s84, v255, 2
	v_readlane_b32 s87, v255, 4
	v_readlane_b32 s91, v255, 6
	s_mov_b32 s68, 0xfffffc0
	s_mov_b32 s69, 0xbfb8aa3b
	s_movk_i32 s60, 0xc4
	s_movk_i32 s56, 0xcc
	s_movk_i32 s57, 0xd4
	s_movk_i32 s58, 0xdc
	s_movk_i32 s59, 0xe4
	s_mov_b64 s[82:83], 0x4000
	s_mov_b64 s[78:79], 0x8000
	s_mov_b64 s[74:75], 0x8180
	s_movk_i32 s61, 0xfff
	s_mov_b32 s54, 0x800000
	s_movk_i32 s55, 0x2fff
	v_readlane_b32 s46, v255, 8
	s_mov_b64 s[72:73], 0x2c000
	s_mov_b64 s[88:89], 0x58000
	v_readlane_b32 s47, v255, 14
	v_mov_b32_e32 v238, v245
	v_mov_b32_e32 v242, 0x2000
	v_mov_b32_e32 v243, 0x7f800000
	v_mov_b32_e32 v245, 0x7fc00000
	v_mov_b32_e32 v246, 0xff800000

.LBB0_992:
	s_add_i32 s13, s12, 2
	s_cmp_lt_u32 s12, 14
	s_cselect_b64 s[14:15], -1, 0
	s_and_b64 vcc, s[14:15], exec
	s_cselect_b32 s2, s1, 0x3c0
	s_lshl_b64 s[14:15], s[2:3], 1
	ds_read_b128 v[138:141], v134
	ds_read_b128 v[146:149], v135 offset:18432
	ds_read_b128 v[142:145], v134 offset:4608
	ds_read_b128 v[150:153], v135 offset:23040
	ds_read_b128 v[154:157], v134 offset:32
	ds_read_b128 v[162:165], v135 offset:18464
	ds_read_b128 v[158:161], v134 offset:4640
	ds_read_b128 v[166:169], v135 offset:23072
	v_lshl_add_u64 v[170:171], v[130:131], 0, s[14:15]
	v_lshl_add_u64 v[172:173], v[132:133], 0, s[14:15]
	global_load_dwordx4 v[98:101], v[170:171], off
	global_load_dwordx4 v[102:105], v[172:173], off
	v_lshl_add_u64 v[174:175], v[170:171], 0, s[40:41]
	global_load_dwordx4 v[106:109], v[174:175], off
	v_lshl_add_u64 v[174:175], v[172:173], 0, s[40:41]
	global_load_dwordx4 v[110:113], v[174:175], off
	v_lshl_add_u64 v[174:175], v[170:171], 0, s[18:19]
	global_load_dwordx4 v[114:117], v[174:175], off
	v_lshl_add_u64 v[174:175], v[172:173], 0, s[18:19]
	global_load_dwordx4 v[118:121], v[174:175], off
	v_lshl_add_u64 v[174:175], v[170:171], 0, s[92:93]
	global_load_dwordx4 v[122:125], v[174:175], off
	v_lshl_add_u64 v[174:175], v[172:173], 0, s[92:93]
	global_load_dwordx4 v[126:129], v[174:175], off
	s_waitcnt lgkmcnt(4)
	v_mfma_f32_32x32x16_bf16 v[48:63], v[138:141], v[146:149], v[48:63]
	v_mfma_f32_32x32x16_bf16 v[32:47], v[138:141], v[150:153], v[32:47]
	v_mfma_f32_32x32x16_bf16 v[16:31], v[142:145], v[146:149], v[16:31]
	v_mfma_f32_32x32x16_bf16 v[0:15], v[142:145], v[150:153], v[0:15]
	ds_read_b128 v[138:141], v134 offset:64
	ds_read_b128 v[146:149], v135 offset:18496
	ds_read_b128 v[142:145], v134 offset:4672
	ds_read_b128 v[150:153], v135 offset:23104
	s_waitcnt lgkmcnt(4)
	v_mfma_f32_32x32x16_bf16 v[48:63], v[154:157], v[162:165], v[48:63]
	v_mfma_f32_32x32x16_bf16 v[32:47], v[154:157], v[166:169], v[32:47]
	v_mfma_f32_32x32x16_bf16 v[16:31], v[158:161], v[162:165], v[16:31]
	v_mfma_f32_32x32x16_bf16 v[0:15], v[158:161], v[166:169], v[0:15]
	ds_read_b128 v[154:157], v134 offset:96
	ds_read_b128 v[162:165], v135 offset:18528
	ds_read_b128 v[158:161], v134 offset:4704
	ds_read_b128 v[166:169], v135 offset:23136
	s_waitcnt lgkmcnt(4)
	v_mfma_f32_32x32x16_bf16 v[48:63], v[138:141], v[146:149], v[48:63]
	s_waitcnt vmcnt(8)
	ds_write_b128 v97, v[64:67] offset:36864
	ds_write_b128 v97, v[68:71] offset:55296
	v_mfma_f32_32x32x16_bf16 v[32:47], v[138:141], v[150:153], v[32:47]
	ds_write_b128 v97, v[72:75] offset:41472
	ds_write_b128 v97, v[76:79] offset:59904
	v_mfma_f32_32x32x16_bf16 v[16:31], v[142:145], v[146:149], v[16:31]
	ds_write_b128 v97, v[80:83] offset:46080
	ds_write_b128 v97, v[84:87] offset:64512
	v_mfma_f32_32x32x16_bf16 v[0:15], v[142:145], v[150:153], v[0:15]
	ds_write_b128 v97, v[88:91] offset:50688
	ds_write_b128 v136, v[92:95] offset:55296
	s_waitcnt lgkmcnt(8)
	v_mfma_f32_32x32x16_bf16 v[48:63], v[154:157], v[162:165], v[48:63]
	v_mfma_f32_32x32x16_bf16 v[32:47], v[154:157], v[166:169], v[32:47]
	v_mfma_f32_32x32x16_bf16 v[16:31], v[158:161], v[162:165], v[16:31]
	v_mfma_f32_32x32x16_bf16 v[0:15], v[158:161], v[166:169], v[0:15]
	s_waitcnt lgkmcnt(0)
	s_barrier
	s_min_u32 s2, s12, 12
	s_lshl_b32 s2, s2, 7
	s_addk_i32 s1, 0x80
	s_mov_b32 s12, s13
	ds_read_b128 v[138:141], v134 offset:36864
	ds_read_b128 v[146:149], v135 offset:55296
	ds_read_b128 v[142:145], v134 offset:41472
	ds_read_b128 v[150:153], v135 offset:59904
	ds_read_b128 v[154:157], v134 offset:36896
	ds_read_b128 v[162:165], v135 offset:55328
	ds_read_b128 v[158:161], v134 offset:41504
	ds_read_b128 v[166:169], v135 offset:59936
	v_lshl_add_u64 v[170:171], v[130:131], 0, s[2:3]
	v_lshl_add_u64 v[172:173], v[132:133], 0, s[2:3]
	v_lshl_add_u64 v[174:175], v[170:171], 0, s[22:23]
	global_load_dwordx4 v[64:67], v[174:175], off
	v_lshl_add_u64 v[174:175], v[172:173], 0, s[22:23]
	global_load_dwordx4 v[68:71], v[174:175], off
	v_lshl_add_u64 v[174:175], v[170:171], 0, s[76:77]
	global_load_dwordx4 v[72:75], v[174:175], off
	v_lshl_add_u64 v[174:175], v[172:173], 0, s[76:77]
	global_load_dwordx4 v[76:79], v[174:175], off
	v_lshl_add_u64 v[174:175], v[170:171], 0, s[26:27]
	global_load_dwordx4 v[80:83], v[174:175], off
	v_lshl_add_u64 v[174:175], v[172:173], 0, s[26:27]
	global_load_dwordx4 v[84:87], v[174:175], off
	v_lshl_add_u64 v[174:175], v[170:171], 0, s[70:71]
	global_load_dwordx4 v[88:91], v[174:175], off
	v_lshl_add_u64 v[174:175], v[172:173], 0, s[70:71]
	global_load_dwordx4 v[92:95], v[174:175], off
	s_waitcnt lgkmcnt(4)
	v_mfma_f32_32x32x16_bf16 v[48:63], v[138:141], v[146:149], v[48:63]
	v_mfma_f32_32x32x16_bf16 v[32:47], v[138:141], v[150:153], v[32:47]
	v_mfma_f32_32x32x16_bf16 v[16:31], v[142:145], v[146:149], v[16:31]
	v_mfma_f32_32x32x16_bf16 v[0:15], v[142:145], v[150:153], v[0:15]
	ds_read_b128 v[138:141], v134 offset:36928
	ds_read_b128 v[146:149], v135 offset:55360
	ds_read_b128 v[142:145], v134 offset:41536
	ds_read_b128 v[150:153], v135 offset:59968
	s_waitcnt lgkmcnt(4)
	v_mfma_f32_32x32x16_bf16 v[48:63], v[154:157], v[162:165], v[48:63]
	v_mfma_f32_32x32x16_bf16 v[32:47], v[154:157], v[166:169], v[32:47]
	v_mfma_f32_32x32x16_bf16 v[16:31], v[158:161], v[162:165], v[16:31]
	v_mfma_f32_32x32x16_bf16 v[0:15], v[158:161], v[166:169], v[0:15]
	ds_read_b128 v[154:157], v134 offset:36960
	ds_read_b128 v[162:165], v135 offset:55392
	ds_read_b128 v[158:161], v134 offset:41568
	ds_read_b128 v[166:169], v135 offset:60000
	s_waitcnt lgkmcnt(4)
	v_mfma_f32_32x32x16_bf16 v[48:63], v[138:141], v[146:149], v[48:63]
	s_waitcnt vmcnt(8)
	ds_write_b128 v97, v[98:101]
	ds_write_b128 v97, v[102:105] offset:18432
	v_mfma_f32_32x32x16_bf16 v[32:47], v[138:141], v[150:153], v[32:47]
	ds_write_b128 v97, v[106:109] offset:4608
	ds_write_b128 v97, v[110:113] offset:23040
	v_mfma_f32_32x32x16_bf16 v[16:31], v[142:145], v[146:149], v[16:31]
	ds_write_b128 v97, v[114:117] offset:9216
	ds_write_b128 v97, v[118:121] offset:27648
	v_mfma_f32_32x32x16_bf16 v[0:15], v[142:145], v[150:153], v[0:15]
	ds_write_b128 v97, v[122:125] offset:13824
	ds_write_b128 v97, v[126:129] offset:32256
	s_waitcnt lgkmcnt(8)
	v_mfma_f32_32x32x16_bf16 v[48:63], v[154:157], v[162:165], v[48:63]
	v_mfma_f32_32x32x16_bf16 v[32:47], v[154:157], v[166:169], v[32:47]
	v_mfma_f32_32x32x16_bf16 v[16:31], v[158:161], v[162:165], v[16:31]
	v_mfma_f32_32x32x16_bf16 v[0:15], v[158:161], v[166:169], v[0:15]
	s_waitcnt lgkmcnt(0)
	s_barrier
	s_cbranch_vccnz .LBB0_992
	s_waitcnt vmcnt(0)
	s_movk_i32 s2, 0x1600
	s_nop 5
	v_mul_f32_e32 v64, 0xbfb8aa3b, v48
	v_exp_f32_e32 v64, v64
	v_mov_b32_e32 v66, v244
	v_add_f32_e32 v68, 1.0, v64
	v_div_scale_f32 v69, s[12:13], v68, v68, 1.0
	v_rcp_f32_e32 v70, v69
	v_lshrrev_b32_e32 v67, 3, v66
	v_lshrrev_b32_e32 v65, 1, v66
	v_and_b32_e32 v67, 4, v67
	v_fma_f32 v71, -v69, v70, 1.0
	v_fmac_f32_e32 v70, v71, v70
	v_div_scale_f32 v71, vcc, 1.0, v68, 1.0
	v_mul_f32_e32 v72, v71, v70
	v_fma_f32 v73, -v69, v72, v71
	v_fmac_f32_e32 v72, v73, v70
	v_fma_f32 v69, -v69, v72, v71
	v_div_fmas_f32 v69, v69, v70, v72
	v_div_fixup_f32 v68, v69, v68, 1.0
	v_mul_f32_e32 v48, v48, v68
	v_mul_f32_e32 v68, 0xbfb8aa3b, v49
	v_exp_f32_e32 v68, v68
	v_mul_f32_e32 v32, v32, v48
	v_and_or_b32 v48, v65, s68, v67
	v_lshlrev_b32_e32 v64, 1, v66
	v_add_f32_e32 v67, 1.0, v68
	v_div_scale_f32 v68, s[12:13], v67, v67, 1.0
	v_rcp_f32_e32 v69, v68
	v_and_b32_e32 v64, 62, v64
	v_and_or_b32 v64, v66, 64, v64
	v_cvt_pk_bf16_f32 v32, v32, v32
	v_mad_u64_u32 v[64:65], s[12:13], v48, s85, v[64:65]
	ds_write_b16 v64, v32
	v_fma_f32 v32, -v68, v69, 1.0
	v_fmac_f32_e32 v69, v32, v69
	v_div_scale_f32 v32, vcc, 1.0, v67, 1.0
	v_mul_f32_e32 v48, v32, v69
	v_fma_f32 v65, -v68, v48, v32
	v_fmac_f32_e32 v48, v65, v69
	v_mul_f32_e32 v65, 0xbfb8aa3b, v50
	v_exp_f32_e32 v65, v65
	v_fma_f32 v32, -v68, v48, v32
	v_div_fmas_f32 v32, v32, v69, v48
	v_div_fixup_f32 v32, v32, v67, 1.0
	v_add_f32_e32 v48, 1.0, v65
	v_mul_f32_e32 v32, v49, v32
	v_div_scale_f32 v49, s[12:13], v48, v48, 1.0
	v_rcp_f32_e32 v65, v49
	v_mul_f32_e32 v32, v33, v32
	v_cvt_pk_bf16_f32 v32, v32, v32
	ds_write_b16 v64, v32 offset:144
	v_fma_f32 v32, -v49, v65, 1.0
	v_fmac_f32_e32 v65, v32, v65
	v_div_scale_f32 v32, vcc, 1.0, v48, 1.0
	v_mul_f32_e32 v33, v32, v65
	v_fma_f32 v67, -v49, v33, v32
	v_fmac_f32_e32 v33, v67, v65
	v_fma_f32 v32, -v49, v33, v32
	v_mul_f32_e32 v49, 0xbfb8aa3b, v51
	v_exp_f32_e32 v49, v49
	v_div_fmas_f32 v32, v32, v65, v33
	v_div_fixup_f32 v32, v32, v48, 1.0
	v_mul_f32_e32 v32, v50, v32
	v_add_f32_e32 v33, 1.0, v49
	v_div_scale_f32 v48, s[12:13], v33, v33, 1.0
	v_rcp_f32_e32 v49, v48
	v_mul_f32_e32 v32, v34, v32
	v_cvt_pk_bf16_f32 v32, v32, v32
	ds_write_b16 v64, v32 offset:288
	v_fma_f32 v32, -v48, v49, 1.0
	v_fmac_f32_e32 v49, v32, v49
	v_div_scale_f32 v32, vcc, 1.0, v33, 1.0
	v_mul_f32_e32 v34, v32, v49
	v_fma_f32 v50, -v48, v34, v32
	v_fmac_f32_e32 v34, v50, v49
	v_fma_f32 v32, -v48, v34, v32
	v_mul_f32_e32 v48, 0xbfb8aa3b, v52
	v_exp_f32_e32 v48, v48
	v_div_fmas_f32 v32, v32, v49, v34
	v_div_fixup_f32 v32, v32, v33, 1.0
	v_mul_f32_e32 v32, v51, v32
	v_add_f32_e32 v33, 1.0, v48
	v_div_scale_f32 v34, s[12:13], v33, v33, 1.0
	v_rcp_f32_e32 v48, v34
	v_mul_f32_e32 v32, v35, v32
	v_cvt_pk_bf16_f32 v32, v32, v32
	ds_write_b16 v64, v32 offset:432
	v_fma_f32 v32, -v34, v48, 1.0
	v_fmac_f32_e32 v48, v32, v48
	v_div_scale_f32 v32, vcc, 1.0, v33, 1.0
	v_mul_f32_e32 v35, v32, v48
	v_fma_f32 v49, -v34, v35, v32
	v_fmac_f32_e32 v35, v49, v48
	v_fma_f32 v32, -v34, v35, v32
	v_mul_f32_e32 v34, 0xbfb8aa3b, v53
	v_exp_f32_e32 v34, v34
	v_div_fmas_f32 v32, v32, v48, v35
	v_div_fixup_f32 v32, v32, v33, 1.0
	v_mul_f32_e32 v32, v52, v32
	v_add_f32_e32 v33, 1.0, v34
	v_div_scale_f32 v34, s[12:13], v33, v33, 1.0
	v_rcp_f32_e32 v35, v34
	v_mul_f32_e32 v32, v36, v32
	v_cvt_pk_bf16_f32 v32, v32, v32
	ds_write_b16 v64, v32 offset:1152
	v_fma_f32 v32, -v34, v35, 1.0
	v_fmac_f32_e32 v35, v32, v35
	v_div_scale_f32 v32, vcc, 1.0, v33, 1.0
	v_mul_f32_e32 v36, v32, v35
	v_fma_f32 v48, -v34, v36, v32
	v_fmac_f32_e32 v36, v48, v35
	v_fma_f32 v32, -v34, v36, v32
	v_mul_f32_e32 v34, 0xbfb8aa3b, v54
	v_exp_f32_e32 v34, v34
	v_div_fmas_f32 v32, v32, v35, v36
	v_div_fixup_f32 v32, v32, v33, 1.0
	v_mul_f32_e32 v32, v53, v32
	v_add_f32_e32 v33, 1.0, v34
	v_div_scale_f32 v34, s[12:13], v33, v33, 1.0
	v_rcp_f32_e32 v35, v34
	v_mul_f32_e32 v32, v37, v32
	v_cvt_pk_bf16_f32 v32, v32, v32
	ds_write_b16 v64, v32 offset:1296
	v_fma_f32 v32, -v34, v35, 1.0
	v_fmac_f32_e32 v35, v32, v35
	v_div_scale_f32 v32, vcc, 1.0, v33, 1.0
	v_mul_f32_e32 v36, v32, v35
	v_fma_f32 v37, -v34, v36, v32
	v_fmac_f32_e32 v36, v37, v35
	v_fma_f32 v32, -v34, v36, v32
	v_mul_f32_e32 v34, 0xbfb8aa3b, v55
	v_exp_f32_e32 v34, v34
	v_div_fmas_f32 v32, v32, v35, v36
	v_div_fixup_f32 v32, v32, v33, 1.0
	v_mul_f32_e32 v32, v54, v32
	v_add_f32_e32 v33, 1.0, v34
	v_div_scale_f32 v34, s[12:13], v33, v33, 1.0
	v_rcp_f32_e32 v35, v34
	v_mul_f32_e32 v32, v38, v32
	v_cvt_pk_bf16_f32 v32, v32, v32
	ds_write_b16 v64, v32 offset:1440
	v_fma_f32 v32, -v34, v35, 1.0
	v_fmac_f32_e32 v35, v32, v35
	v_div_scale_f32 v32, vcc, 1.0, v33, 1.0
	v_mul_f32_e32 v36, v32, v35
	v_fma_f32 v37, -v34, v36, v32
	v_fmac_f32_e32 v36, v37, v35
	v_fma_f32 v32, -v34, v36, v32
	v_mul_f32_e32 v34, 0xbfb8aa3b, v56
	v_exp_f32_e32 v34, v34
	v_div_fmas_f32 v32, v32, v35, v36
	v_div_fixup_f32 v32, v32, v33, 1.0
	v_mul_f32_e32 v32, v55, v32
	v_add_f32_e32 v33, 1.0, v34
	v_div_scale_f32 v34, s[12:13], v33, v33, 1.0
	v_rcp_f32_e32 v35, v34
	v_mul_f32_e32 v32, v39, v32
	v_cvt_pk_bf16_f32 v32, v32, v32
	ds_write_b16 v64, v32 offset:1584
	v_fma_f32 v32, -v34, v35, 1.0
	v_fmac_f32_e32 v35, v32, v35
	v_div_scale_f32 v32, vcc, 1.0, v33, 1.0
	v_mul_f32_e32 v36, v32, v35
	v_fma_f32 v37, -v34, v36, v32
	v_fmac_f32_e32 v36, v37, v35
	v_fma_f32 v32, -v34, v36, v32
	v_mul_f32_e32 v34, 0xbfb8aa3b, v57
	v_exp_f32_e32 v34, v34
	v_div_fmas_f32 v32, v32, v35, v36
	v_div_fixup_f32 v32, v32, v33, 1.0
	v_mul_f32_e32 v32, v56, v32
	v_add_f32_e32 v33, 1.0, v34
	v_div_scale_f32 v34, s[12:13], v33, v33, 1.0
	v_rcp_f32_e32 v35, v34
	v_mul_f32_e32 v32, v40, v32
	v_cvt_pk_bf16_f32 v32, v32, v32
	ds_write_b16 v64, v32 offset:2304
	v_fma_f32 v32, -v34, v35, 1.0
	v_fmac_f32_e32 v35, v32, v35
	v_div_scale_f32 v32, vcc, 1.0, v33, 1.0
	v_mul_f32_e32 v36, v32, v35
	v_fma_f32 v37, -v34, v36, v32
	v_fmac_f32_e32 v36, v37, v35
	v_fma_f32 v32, -v34, v36, v32
	v_mul_f32_e32 v34, 0xbfb8aa3b, v58
	v_exp_f32_e32 v34, v34
	v_div_fmas_f32 v32, v32, v35, v36
	v_div_fixup_f32 v32, v32, v33, 1.0
	v_mul_f32_e32 v32, v57, v32
	v_add_f32_e32 v33, 1.0, v34
	v_div_scale_f32 v34, s[12:13], v33, v33, 1.0
	v_rcp_f32_e32 v35, v34
	v_mul_f32_e32 v32, v41, v32
	v_cvt_pk_bf16_f32 v32, v32, v32
	ds_write_b16 v64, v32 offset:2448
	v_fma_f32 v32, -v34, v35, 1.0
	v_fmac_f32_e32 v35, v32, v35
	v_div_scale_f32 v32, vcc, 1.0, v33, 1.0
	v_mul_f32_e32 v36, v32, v35
	v_fma_f32 v37, -v34, v36, v32
	v_fmac_f32_e32 v36, v37, v35
	v_fma_f32 v32, -v34, v36, v32
	v_mul_f32_e32 v34, 0xbfb8aa3b, v59
	v_exp_f32_e32 v34, v34
	v_div_fmas_f32 v32, v32, v35, v36
	v_div_fixup_f32 v32, v32, v33, 1.0
	v_mul_f32_e32 v32, v58, v32
	v_add_f32_e32 v33, 1.0, v34
	v_div_scale_f32 v34, s[12:13], v33, v33, 1.0
	v_rcp_f32_e32 v35, v34
	v_mul_f32_e32 v32, v42, v32
	v_cvt_pk_bf16_f32 v32, v32, v32
	ds_write_b16 v64, v32 offset:2592
	v_fma_f32 v32, -v34, v35, 1.0
	v_fmac_f32_e32 v35, v32, v35
	v_div_scale_f32 v32, vcc, 1.0, v33, 1.0
	v_mul_f32_e32 v36, v32, v35
	v_fma_f32 v37, -v34, v36, v32
	v_fmac_f32_e32 v36, v37, v35
	v_fma_f32 v32, -v34, v36, v32
	v_mul_f32_e32 v34, 0xbfb8aa3b, v60
	v_exp_f32_e32 v34, v34
	v_div_fmas_f32 v32, v32, v35, v36
	v_div_fixup_f32 v32, v32, v33, 1.0
	v_mul_f32_e32 v32, v59, v32
	v_add_f32_e32 v33, 1.0, v34
	v_div_scale_f32 v34, s[12:13], v33, v33, 1.0
	v_rcp_f32_e32 v35, v34
	v_mul_f32_e32 v32, v43, v32
	v_cvt_pk_bf16_f32 v32, v32, v32
	ds_write_b16 v64, v32 offset:2736
	v_fma_f32 v32, -v34, v35, 1.0
	v_fmac_f32_e32 v35, v32, v35
	v_div_scale_f32 v32, vcc, 1.0, v33, 1.0
	v_mul_f32_e32 v36, v32, v35
	v_fma_f32 v37, -v34, v36, v32
	v_fmac_f32_e32 v36, v37, v35
	v_fma_f32 v32, -v34, v36, v32
	v_mul_f32_e32 v34, 0xbfb8aa3b, v61
	v_exp_f32_e32 v34, v34
	v_div_fmas_f32 v32, v32, v35, v36
	v_div_fixup_f32 v32, v32, v33, 1.0
	v_mul_f32_e32 v32, v60, v32
	v_add_f32_e32 v33, 1.0, v34
	v_div_scale_f32 v34, s[12:13], v33, v33, 1.0
	v_rcp_f32_e32 v35, v34
	v_mul_f32_e32 v32, v44, v32
	v_cvt_pk_bf16_f32 v32, v32, v32
	ds_write_b16 v64, v32 offset:3456
	v_fma_f32 v32, -v34, v35, 1.0
	v_fmac_f32_e32 v35, v32, v35
	v_div_scale_f32 v32, vcc, 1.0, v33, 1.0
	v_mul_f32_e32 v36, v32, v35
	v_fma_f32 v37, -v34, v36, v32
	v_fmac_f32_e32 v36, v37, v35
	v_fma_f32 v32, -v34, v36, v32
	v_mul_f32_e32 v34, 0xbfb8aa3b, v62
	v_exp_f32_e32 v34, v34
	v_div_fmas_f32 v32, v32, v35, v36
	v_div_fixup_f32 v32, v32, v33, 1.0
	v_mul_f32_e32 v32, v61, v32
	v_add_f32_e32 v33, 1.0, v34
	v_div_scale_f32 v34, s[12:13], v33, v33, 1.0
	v_rcp_f32_e32 v35, v34
	v_mul_f32_e32 v32, v45, v32
	v_cvt_pk_bf16_f32 v32, v32, v32
	ds_write_b16 v64, v32 offset:3600
	v_fma_f32 v32, -v34, v35, 1.0
	v_fmac_f32_e32 v35, v32, v35
	v_div_scale_f32 v32, vcc, 1.0, v33, 1.0
	v_mul_f32_e32 v36, v32, v35
	v_fma_f32 v37, -v34, v36, v32
	v_fmac_f32_e32 v36, v37, v35
	v_fma_f32 v32, -v34, v36, v32
	v_mul_f32_e32 v34, 0xbfb8aa3b, v63
	v_exp_f32_e32 v34, v34
	v_div_fmas_f32 v32, v32, v35, v36
	v_div_fixup_f32 v32, v32, v33, 1.0
	v_mul_f32_e32 v32, v62, v32
	v_add_f32_e32 v33, 1.0, v34
	v_div_scale_f32 v34, s[12:13], v33, v33, 1.0
	v_rcp_f32_e32 v35, v34
	v_mul_f32_e32 v32, v46, v32
	v_cvt_pk_bf16_f32 v32, v32, v32
	ds_write_b16 v64, v32 offset:3744
	v_fma_f32 v32, -v34, v35, 1.0
	v_fmac_f32_e32 v35, v32, v35
	v_div_scale_f32 v32, vcc, 1.0, v33, 1.0
	v_mul_f32_e32 v36, v32, v35
	v_fma_f32 v37, -v34, v36, v32
	v_fmac_f32_e32 v36, v37, v35
	v_fma_f32 v32, -v34, v36, v32
	v_mul_f32_e32 v34, 0xbfb8aa3b, v16
	v_exp_f32_e32 v34, v34
	v_div_fmas_f32 v32, v32, v35, v36
	v_div_fixup_f32 v32, v32, v33, 1.0
	v_mul_f32_e32 v32, v63, v32
	v_add_f32_e32 v33, 1.0, v34
	v_div_scale_f32 v34, s[12:13], v33, v33, 1.0
	v_rcp_f32_e32 v35, v34
	v_mul_f32_e32 v32, v47, v32
	v_cvt_pk_bf16_f32 v32, v32, v32
	ds_write_b16 v64, v32 offset:3888
	v_fma_f32 v32, -v34, v35, 1.0
	v_fmac_f32_e32 v35, v32, v35
	v_div_scale_f32 v32, vcc, 1.0, v33, 1.0
	v_mul_f32_e32 v36, v32, v35
	v_fma_f32 v37, -v34, v36, v32
	v_fmac_f32_e32 v36, v37, v35
	v_fma_f32 v32, -v34, v36, v32
	v_mul_f32_e32 v34, 0xbfb8aa3b, v17
	v_exp_f32_e32 v34, v34
	v_div_fmas_f32 v32, v32, v35, v36
	v_div_fixup_f32 v32, v32, v33, 1.0
	v_mul_f32_e32 v16, v16, v32
	v_add_f32_e32 v32, 1.0, v34
	v_div_scale_f32 v33, s[12:13], v32, v32, 1.0
	v_rcp_f32_e32 v34, v33
	v_mul_f32_e32 v0, v0, v16
	v_cvt_pk_bf16_f32 v0, v0, v0
	ds_write_b16 v64, v0 offset:4608
	v_fma_f32 v0, -v33, v34, 1.0
	v_fmac_f32_e32 v34, v0, v34
	v_div_scale_f32 v0, vcc, 1.0, v32, 1.0
	v_mul_f32_e32 v16, v0, v34
	v_fma_f32 v35, -v33, v16, v0
	v_fmac_f32_e32 v16, v35, v34
	v_fma_f32 v0, -v33, v16, v0
	v_mul_f32_e32 v33, 0xbfb8aa3b, v18
	v_exp_f32_e32 v33, v33
	v_div_fmas_f32 v0, v0, v34, v16
	v_div_fixup_f32 v0, v0, v32, 1.0
	v_mul_f32_e32 v0, v17, v0
	v_add_f32_e32 v16, 1.0, v33
	v_div_scale_f32 v17, s[12:13], v16, v16, 1.0
	v_rcp_f32_e32 v32, v17
	v_mul_f32_e32 v0, v1, v0
	v_cvt_pk_bf16_f32 v0, v0, v0
	ds_write_b16 v64, v0 offset:4752
	v_fma_f32 v0, -v17, v32, 1.0
	v_fmac_f32_e32 v32, v0, v32
	v_div_scale_f32 v0, vcc, 1.0, v16, 1.0
	v_mul_f32_e32 v1, v0, v32
	v_fma_f32 v33, -v17, v1, v0
	v_fmac_f32_e32 v1, v33, v32
	v_fma_f32 v0, -v17, v1, v0
	v_mul_f32_e32 v17, 0xbfb8aa3b, v19
	v_exp_f32_e32 v17, v17
	v_div_fmas_f32 v0, v0, v32, v1
	v_div_fixup_f32 v0, v0, v16, 1.0
	v_mul_f32_e32 v0, v18, v0
	v_add_f32_e32 v1, 1.0, v17
	v_div_scale_f32 v16, s[12:13], v1, v1, 1.0
	v_rcp_f32_e32 v17, v16
	v_mul_f32_e32 v0, v2, v0
	v_cvt_pk_bf16_f32 v0, v0, v0
	ds_write_b16 v64, v0 offset:4896
	v_fma_f32 v0, -v16, v17, 1.0
	v_fmac_f32_e32 v17, v0, v17
	v_div_scale_f32 v0, vcc, 1.0, v1, 1.0
	v_mul_f32_e32 v2, v0, v17
	v_fma_f32 v18, -v16, v2, v0
	v_fmac_f32_e32 v2, v18, v17
	v_fma_f32 v0, -v16, v2, v0
	v_mul_f32_e32 v16, 0xbfb8aa3b, v20
	v_exp_f32_e32 v16, v16
	v_div_fmas_f32 v0, v0, v17, v2
	v_div_fixup_f32 v0, v0, v1, 1.0
	v_mul_f32_e32 v0, v19, v0
	v_add_f32_e32 v1, 1.0, v16
	v_div_scale_f32 v2, s[12:13], v1, v1, 1.0
	v_rcp_f32_e32 v16, v2
	v_mul_f32_e32 v0, v3, v0
	v_cvt_pk_bf16_f32 v0, v0, v0
	ds_write_b16 v64, v0 offset:5040
	v_fma_f32 v0, -v2, v16, 1.0
	v_fmac_f32_e32 v16, v0, v16
	v_div_scale_f32 v0, vcc, 1.0, v1, 1.0
	v_mul_f32_e32 v3, v0, v16
	v_fma_f32 v17, -v2, v3, v0
	v_fmac_f32_e32 v3, v17, v16
	v_fma_f32 v0, -v2, v3, v0
	v_mul_f32_e32 v2, 0xbfb8aa3b, v21
	v_exp_f32_e32 v2, v2
	v_div_fmas_f32 v0, v0, v16, v3
	v_div_fixup_f32 v0, v0, v1, 1.0
	v_mul_f32_e32 v0, v20, v0
	v_add_f32_e32 v1, 1.0, v2
	v_div_scale_f32 v2, s[12:13], v1, v1, 1.0
	v_rcp_f32_e32 v3, v2
	v_mul_f32_e32 v0, v4, v0
	v_cvt_pk_bf16_f32 v0, v0, v0
	ds_write_b16 v64, v0 offset:5760
	v_fma_f32 v0, -v2, v3, 1.0
	v_fmac_f32_e32 v3, v0, v3
	v_div_scale_f32 v0, vcc, 1.0, v1, 1.0
	v_mul_f32_e32 v4, v0, v3
	v_fma_f32 v16, -v2, v4, v0
	v_fmac_f32_e32 v4, v16, v3
	v_fma_f32 v0, -v2, v4, v0
	v_mul_f32_e32 v2, 0xbfb8aa3b, v22
	v_exp_f32_e32 v2, v2
	v_div_fmas_f32 v0, v0, v3, v4
	v_div_fixup_f32 v0, v0, v1, 1.0
	v_mul_f32_e32 v0, v21, v0
	v_add_f32_e32 v1, 1.0, v2
	v_div_scale_f32 v2, s[12:13], v1, v1, 1.0
	v_rcp_f32_e32 v3, v2
	v_mul_f32_e32 v0, v5, v0
	v_cvt_pk_bf16_f32 v0, v0, v0
	ds_write_b16 v64, v0 offset:5904
	v_fma_f32 v0, -v2, v3, 1.0
	v_fmac_f32_e32 v3, v0, v3
	v_div_scale_f32 v0, vcc, 1.0, v1, 1.0
	v_mul_f32_e32 v4, v0, v3
	v_fma_f32 v5, -v2, v4, v0
	v_fmac_f32_e32 v4, v5, v3
	v_fma_f32 v0, -v2, v4, v0
	v_mul_f32_e32 v2, 0xbfb8aa3b, v23
	v_exp_f32_e32 v2, v2
	v_div_fmas_f32 v0, v0, v3, v4
	v_div_fixup_f32 v0, v0, v1, 1.0
	v_mul_f32_e32 v0, v22, v0
	v_add_f32_e32 v1, 1.0, v2
	v_div_scale_f32 v2, s[12:13], v1, v1, 1.0
	v_rcp_f32_e32 v3, v2
	v_mul_f32_e32 v0, v6, v0
	v_cvt_pk_bf16_f32 v0, v0, v0
	ds_write_b16 v64, v0 offset:6048
	v_fma_f32 v0, -v2, v3, 1.0
	v_fmac_f32_e32 v3, v0, v3
	v_div_scale_f32 v0, vcc, 1.0, v1, 1.0
	v_mul_f32_e32 v4, v0, v3
	v_fma_f32 v5, -v2, v4, v0
	v_fmac_f32_e32 v4, v5, v3
	v_fma_f32 v0, -v2, v4, v0
	v_mul_f32_e32 v2, 0xbfb8aa3b, v24
	v_exp_f32_e32 v2, v2
	v_div_fmas_f32 v0, v0, v3, v4
	v_div_fixup_f32 v0, v0, v1, 1.0
	v_mul_f32_e32 v0, v23, v0
	v_add_f32_e32 v1, 1.0, v2
	v_div_scale_f32 v2, s[12:13], v1, v1, 1.0
	v_rcp_f32_e32 v3, v2
	v_mul_f32_e32 v0, v7, v0
	v_cvt_pk_bf16_f32 v0, v0, v0
	ds_write_b16 v64, v0 offset:6192
	v_fma_f32 v0, -v2, v3, 1.0
	v_fmac_f32_e32 v3, v0, v3
	v_div_scale_f32 v0, vcc, 1.0, v1, 1.0
	v_mul_f32_e32 v4, v0, v3
	v_fma_f32 v5, -v2, v4, v0
	v_fmac_f32_e32 v4, v5, v3
	v_fma_f32 v0, -v2, v4, v0
	v_mul_f32_e32 v2, 0xbfb8aa3b, v25
	v_exp_f32_e32 v2, v2
	v_div_fmas_f32 v0, v0, v3, v4
	v_div_fixup_f32 v0, v0, v1, 1.0
	v_mul_f32_e32 v0, v24, v0
	v_add_f32_e32 v1, 1.0, v2
	v_div_scale_f32 v2, s[12:13], v1, v1, 1.0
	v_rcp_f32_e32 v3, v2
	v_mul_f32_e32 v0, v8, v0
	v_cvt_pk_bf16_f32 v0, v0, v0
	ds_write_b16 v64, v0 offset:6912
	v_fma_f32 v0, -v2, v3, 1.0
	v_fmac_f32_e32 v3, v0, v3
	v_div_scale_f32 v0, vcc, 1.0, v1, 1.0
	v_mul_f32_e32 v4, v0, v3
	v_fma_f32 v5, -v2, v4, v0
	v_fmac_f32_e32 v4, v5, v3
	v_fma_f32 v0, -v2, v4, v0
	v_mul_f32_e32 v2, 0xbfb8aa3b, v26
	v_exp_f32_e32 v2, v2
	v_div_fmas_f32 v0, v0, v3, v4
	v_div_fixup_f32 v0, v0, v1, 1.0
	v_mul_f32_e32 v0, v25, v0
	v_add_f32_e32 v1, 1.0, v2
	v_div_scale_f32 v2, s[12:13], v1, v1, 1.0
	v_rcp_f32_e32 v3, v2
	v_mul_f32_e32 v0, v9, v0
	v_cvt_pk_bf16_f32 v0, v0, v0
	ds_write_b16 v64, v0 offset:7056
	v_fma_f32 v0, -v2, v3, 1.0
	v_fmac_f32_e32 v3, v0, v3
	v_div_scale_f32 v0, vcc, 1.0, v1, 1.0
	v_mul_f32_e32 v4, v0, v3
	v_fma_f32 v5, -v2, v4, v0
	v_fmac_f32_e32 v4, v5, v3
	v_fma_f32 v0, -v2, v4, v0
	v_mul_f32_e32 v2, 0xbfb8aa3b, v27
	v_exp_f32_e32 v2, v2
	v_div_fmas_f32 v0, v0, v3, v4
	v_div_fixup_f32 v0, v0, v1, 1.0
	v_mul_f32_e32 v0, v26, v0
	v_add_f32_e32 v1, 1.0, v2
	v_div_scale_f32 v2, s[12:13], v1, v1, 1.0
	v_rcp_f32_e32 v3, v2
	v_mul_f32_e32 v0, v10, v0
	v_cvt_pk_bf16_f32 v0, v0, v0
	ds_write_b16 v64, v0 offset:7200
	v_fma_f32 v0, -v2, v3, 1.0
	v_fmac_f32_e32 v3, v0, v3
	v_div_scale_f32 v0, vcc, 1.0, v1, 1.0
	v_mul_f32_e32 v4, v0, v3
	v_fma_f32 v5, -v2, v4, v0
	v_fmac_f32_e32 v4, v5, v3
	v_fma_f32 v0, -v2, v4, v0
	v_mul_f32_e32 v2, 0xbfb8aa3b, v28
	v_exp_f32_e32 v2, v2
	v_div_fmas_f32 v0, v0, v3, v4
	v_div_fixup_f32 v0, v0, v1, 1.0
	v_mul_f32_e32 v0, v27, v0
	v_add_f32_e32 v1, 1.0, v2
	v_div_scale_f32 v2, s[12:13], v1, v1, 1.0
	v_rcp_f32_e32 v3, v2
	v_mul_f32_e32 v0, v11, v0
	v_cvt_pk_bf16_f32 v0, v0, v0
	ds_write_b16 v64, v0 offset:7344
	v_fma_f32 v0, -v2, v3, 1.0
	v_fmac_f32_e32 v3, v0, v3
	v_div_scale_f32 v0, vcc, 1.0, v1, 1.0
	v_mul_f32_e32 v4, v0, v3
	v_fma_f32 v5, -v2, v4, v0
	v_fmac_f32_e32 v4, v5, v3
	v_fma_f32 v0, -v2, v4, v0
	v_mul_f32_e32 v2, 0xbfb8aa3b, v29
	v_exp_f32_e32 v2, v2
	v_div_fmas_f32 v0, v0, v3, v4
	v_div_fixup_f32 v0, v0, v1, 1.0
	v_mul_f32_e32 v0, v28, v0
	v_add_f32_e32 v1, 1.0, v2
	v_div_scale_f32 v2, s[12:13], v1, v1, 1.0
	v_rcp_f32_e32 v3, v2
	v_mul_f32_e32 v0, v12, v0
	v_cvt_pk_bf16_f32 v0, v0, v0
	ds_write_b16 v64, v0 offset:8064
	v_fma_f32 v0, -v2, v3, 1.0
	v_fmac_f32_e32 v3, v0, v3
	v_div_scale_f32 v0, vcc, 1.0, v1, 1.0
	v_mul_f32_e32 v4, v0, v3
	v_fma_f32 v5, -v2, v4, v0
	v_fmac_f32_e32 v4, v5, v3
	v_fma_f32 v0, -v2, v4, v0
	v_mul_f32_e32 v2, 0xbfb8aa3b, v30
	v_exp_f32_e32 v2, v2
	v_div_fmas_f32 v0, v0, v3, v4
	v_div_fixup_f32 v0, v0, v1, 1.0
	v_mul_f32_e32 v0, v29, v0
	v_add_f32_e32 v1, 1.0, v2
	v_div_scale_f32 v2, s[12:13], v1, v1, 1.0
	v_rcp_f32_e32 v3, v2
	v_mul_f32_e32 v0, v13, v0
	v_cvt_pk_bf16_f32 v0, v0, v0
	ds_write_b16 v64, v0 offset:8208
	v_fma_f32 v0, -v2, v3, 1.0
	v_fmac_f32_e32 v3, v0, v3
	v_div_scale_f32 v0, vcc, 1.0, v1, 1.0
	v_mul_f32_e32 v4, v0, v3
	v_fma_f32 v5, -v2, v4, v0
	v_fmac_f32_e32 v4, v5, v3
	v_fma_f32 v0, -v2, v4, v0
	v_mul_f32_e32 v2, 0xbfb8aa3b, v31
	v_exp_f32_e32 v2, v2
	v_div_fmas_f32 v0, v0, v3, v4
	v_div_fixup_f32 v0, v0, v1, 1.0
	v_mul_f32_e32 v0, v30, v0
	v_add_f32_e32 v1, 1.0, v2
	v_div_scale_f32 v2, s[12:13], v1, v1, 1.0
	v_rcp_f32_e32 v3, v2
	v_mul_f32_e32 v0, v14, v0
	v_cvt_pk_bf16_f32 v0, v0, v0
	ds_write_b16 v64, v0 offset:8352
	v_fma_f32 v0, -v2, v3, 1.0
	v_fmac_f32_e32 v3, v0, v3
	v_div_scale_f32 v0, vcc, 1.0, v1, 1.0
	v_mul_f32_e32 v4, v0, v3
	v_fma_f32 v5, -v2, v4, v0
	v_fmac_f32_e32 v4, v5, v3
	v_fma_f32 v0, -v2, v4, v0
	v_div_fmas_f32 v0, v0, v3, v4
	v_div_fixup_f32 v0, v0, v1, 1.0
	v_mul_f32_e32 v0, v31, v0
	s_lshl_b32 s12, s11, 6
	v_mul_f32_e32 v0, v15, v0
	s_ashr_i32 s13, s12, 31
	v_cvt_pk_bf16_f32 v0, v0, v0
	s_lshl_b64 s[12:13], s[12:13], 1
	ds_write_b16 v64, v0 offset:8496
	v_lshlrev_b32_e32 v0, 4, v66
	s_add_u32 s12, s9, s12
	v_ashrrev_i32_e32 v4, 3, v66
	v_and_b32_e32 v0, 0x70, v0
	s_addc_u32 s13, s10, s13
	v_mov_b32_e32 v1, v96
	v_lshl_add_u64 v[8:9], s[12:13], 0, v[0:1]
	v_mad_u64_u32 v[10:11], s[12:13], v4, s85, v[0:1]
	s_waitcnt lgkmcnt(0)
	s_barrier
	ds_read_b128 v[0:3], v10
	v_add_u32_e32 v11, s0, v4
	ds_read_b128 v[4:7], v10 offset:4608
	v_mad_i64_i32 v[12:13], s[0:1], v11, s2, v[8:9]
	s_waitcnt lgkmcnt(0)
	global_store_dwordx4 v[12:13], v[0:3], off
	s_nop 1
	v_add_u32_e32 v0, 32, v11
	v_mad_i64_i32 v[0:1], s[0:1], v0, s2, v[8:9]
	global_store_dwordx4 v[0:1], v[4:7], off
	ds_read_b128 v[0:3], v10 offset:9216
	s_nop 0
	v_add_u32_e32 v4, 64, v11
	v_mad_i64_i32 v[12:13], s[0:1], v4, s2, v[8:9]
	ds_read_b128 v[4:7], v10 offset:13824
	s_waitcnt lgkmcnt(0)
	global_store_dwordx4 v[12:13], v[0:3], off
	s_nop 1
	v_add_u32_e32 v0, 0x60, v11
	v_mad_i64_i32 v[0:1], s[0:1], v0, s2, v[8:9]
	v_readlane_b32 s0, v255, 9
	s_add_i32 s4, s4, s0
	s_cmpk_lt_i32 s4, 0x1080
	global_store_dwordx4 v[0:1], v[4:7], off
	s_waitcnt vmcnt(63) expcnt(7) lgkmcnt(15)
	s_barrier
	s_cbranch_scc1 .LBB0_991

.LBB0_1050:
	s_add_i32 s8, s9, 2
	s_cmp_lt_u32 s9, 42
	s_cselect_b64 s[10:11], -1, 0
	s_and_b64 vcc, s[10:11], exec
	s_cselect_b32 s2, s7, 0xac0
	s_lshl_b64 s[10:11], s[2:3], 1
	v_lshl_add_u64 v[158:159], v[180:181], 0, s[10:11]
	global_load_dwordx4 v[138:141], v[158:159], off
	v_lshl_add_u64 v[146:147], v[158:159], 0, s[72:73]
	global_load_dwordx4 v[142:145], v[146:147], off
	v_lshl_add_u64 v[150:151], v[158:159], 0, s[88:89]
	global_load_dwordx4 v[146:149], v[150:151], off
	v_lshl_add_u64 v[154:155], v[158:159], 0, s[34:35]
	global_load_dwordx4 v[150:153], v[154:155], off
	v_lshl_add_u64 v[160:161], v[158:159], 0, s[36:37]
	global_load_dwordx4 v[154:157], v[160:161], off
	v_lshl_add_u64 v[162:163], v[158:159], 0, s[12:13]
	global_load_dwordx4 v[158:161], v[162:163], off
	v_lshl_add_u64 v[174:175], v[182:183], 0, s[10:11]
	global_load_dwordx4 v[162:165], v[174:175], off
	v_lshl_add_u64 v[170:171], v[174:175], 0, s[72:73]
	global_load_dwordx4 v[166:169], v[170:171], off
	v_lshl_add_u64 v[176:177], v[174:175], 0, s[88:89]
	global_load_dwordx4 v[170:173], v[176:177], off
	v_lshl_add_u64 v[186:187], v[174:175], 0, s[34:35]
	global_load_dwordx4 v[174:177], v[186:187], off
	s_min_u32 s2, s9, 40
	s_lshl_b32 s2, s2, 7
	s_mov_b64 s[10:11], 0xb0180
	s_addk_i32 s7, 0x80
	s_mov_b32 s9, s8
	ds_read_b128 v[186:189], v179
	ds_read_b128 v[190:193], v184 offset:27648
	ds_read_b128 v[194:197], v179 offset:4608
	ds_read_b128 v[198:201], v184 offset:32256
	ds_read_b128 v[202:205], v179 offset:9216
	ds_read_b128 v[206:209], v179 offset:32
	ds_read_b128 v[210:213], v184 offset:27680
	ds_read_b128 v[214:217], v179 offset:4640
	ds_read_b128 v[218:221], v184 offset:32288
	ds_read_b128 v[222:225], v179 offset:9248
	s_waitcnt lgkmcnt(5)
	v_mfma_f32_32x32x16_bf16 v[80:95], v[186:189], v[190:193], v[80:95]
	v_mfma_f32_32x32x16_bf16 v[32:47], v[186:189], v[198:201], v[32:47]
	v_mfma_f32_32x32x16_bf16 v[64:79], v[194:197], v[190:193], v[64:79]
	v_mfma_f32_32x32x16_bf16 v[16:31], v[194:197], v[198:201], v[16:31]
	v_mfma_f32_32x32x16_bf16 v[48:63], v[202:205], v[190:193], v[48:63]
	v_mfma_f32_32x32x16_bf16 v[0:15], v[202:205], v[198:201], v[0:15]
	ds_read_b128 v[186:189], v179 offset:64
	ds_read_b128 v[190:193], v184 offset:27712
	ds_read_b128 v[194:197], v179 offset:4672
	ds_read_b128 v[198:201], v184 offset:32320
	ds_read_b128 v[202:205], v179 offset:9280
	s_waitcnt lgkmcnt(5)
	v_mfma_f32_32x32x16_bf16 v[80:95], v[206:209], v[210:213], v[80:95]
	v_mfma_f32_32x32x16_bf16 v[32:47], v[206:209], v[218:221], v[32:47]
	v_mfma_f32_32x32x16_bf16 v[64:79], v[214:217], v[210:213], v[64:79]
	v_mfma_f32_32x32x16_bf16 v[16:31], v[214:217], v[218:221], v[16:31]
	v_mfma_f32_32x32x16_bf16 v[48:63], v[222:225], v[210:213], v[48:63]
	v_mfma_f32_32x32x16_bf16 v[0:15], v[222:225], v[218:221], v[0:15]
	ds_read_b128 v[206:209], v179 offset:96
	ds_read_b128 v[210:213], v184 offset:27744
	ds_read_b128 v[214:217], v179 offset:4704
	ds_read_b128 v[218:221], v184 offset:32352
	ds_read_b128 v[222:225], v179 offset:9312
	s_waitcnt lgkmcnt(0)
	s_waitcnt vmcnt(10)
	s_barrier
	v_mfma_f32_32x32x16_bf16 v[80:95], v[186:189], v[190:193], v[80:95]
	ds_write_b128 v97, v[98:101]
	ds_write_b128 v97, v[102:105] offset:4608
	v_mfma_f32_32x32x16_bf16 v[32:47], v[186:189], v[198:201], v[32:47]
	ds_write_b128 v97, v[106:109] offset:9216
	ds_write_b128 v97, v[110:113] offset:13824
	v_mfma_f32_32x32x16_bf16 v[64:79], v[194:197], v[190:193], v[64:79]
	ds_write_b128 v97, v[114:117] offset:18432
	ds_write_b128 v97, v[118:121] offset:23040
	v_mfma_f32_32x32x16_bf16 v[16:31], v[194:197], v[198:201], v[16:31]
	ds_write_b128 v97, v[122:125] offset:27648
	ds_write_b128 v97, v[126:129] offset:32256
	v_mfma_f32_32x32x16_bf16 v[48:63], v[202:205], v[190:193], v[48:63]
	ds_write_b128 v97, v[130:133] offset:36864
	ds_write_b128 v97, v[134:137] offset:41472
	v_mfma_f32_32x32x16_bf16 v[0:15], v[202:205], v[198:201], v[0:15]
	v_lshl_add_u64 v[118:119], v[180:181], 0, s[2:3]
	v_mfma_f32_32x32x16_bf16 v[80:95], v[206:209], v[210:213], v[80:95]
	v_mfma_f32_32x32x16_bf16 v[32:47], v[206:209], v[218:221], v[32:47]
	v_mfma_f32_32x32x16_bf16 v[64:79], v[214:217], v[210:213], v[64:79]
	v_mfma_f32_32x32x16_bf16 v[16:31], v[214:217], v[218:221], v[16:31]
	v_mfma_f32_32x32x16_bf16 v[48:63], v[222:225], v[210:213], v[48:63]
	v_mfma_f32_32x32x16_bf16 v[0:15], v[222:225], v[218:221], v[0:15]
	s_waitcnt lgkmcnt(0)
	s_barrier
	v_lshl_add_u64 v[102:103], v[118:119], 0, s[22:23]
	global_load_dwordx4 v[98:101], v[102:103], off
	v_lshl_add_u64 v[106:107], v[118:119], 0, s[14:15]
	global_load_dwordx4 v[102:105], v[106:107], off
	v_lshl_add_u64 v[110:111], v[118:119], 0, s[16:17]
	global_load_dwordx4 v[106:109], v[110:111], off
	v_lshl_add_u64 v[114:115], v[118:119], 0, s[20:21]
	global_load_dwordx4 v[110:113], v[114:115], off
	v_lshl_add_u64 v[120:121], v[118:119], 0, s[10:11]
	global_load_dwordx4 v[114:117], v[120:121], off
	s_mov_b64 s[10:11], 0xdc180
	v_lshl_add_u64 v[122:123], v[118:119], 0, s[10:11]
	global_load_dwordx4 v[118:121], v[122:123], off
	v_lshl_add_u64 v[134:135], v[182:183], 0, s[2:3]
	v_lshl_add_u64 v[126:127], v[134:135], 0, s[22:23]
	global_load_dwordx4 v[122:125], v[126:127], off
	v_lshl_add_u64 v[130:131], v[134:135], 0, s[14:15]
	global_load_dwordx4 v[126:129], v[130:131], off
	v_lshl_add_u64 v[136:137], v[134:135], 0, s[16:17]
	global_load_dwordx4 v[130:133], v[136:137], off
	v_lshl_add_u64 v[186:187], v[134:135], 0, s[20:21]
	global_load_dwordx4 v[134:137], v[186:187], off
	ds_read_b128 v[186:189], v179
	ds_read_b128 v[190:193], v184 offset:27648
	ds_read_b128 v[194:197], v179 offset:4608
	ds_read_b128 v[198:201], v184 offset:32256
	ds_read_b128 v[202:205], v179 offset:9216
	ds_read_b128 v[206:209], v179 offset:32
	ds_read_b128 v[210:213], v184 offset:27680
	ds_read_b128 v[214:217], v179 offset:4640
	ds_read_b128 v[218:221], v184 offset:32288
	ds_read_b128 v[222:225], v179 offset:9248
	s_waitcnt lgkmcnt(5)
	v_mfma_f32_32x32x16_bf16 v[80:95], v[186:189], v[190:193], v[80:95]
	v_mfma_f32_32x32x16_bf16 v[32:47], v[186:189], v[198:201], v[32:47]
	v_mfma_f32_32x32x16_bf16 v[64:79], v[194:197], v[190:193], v[64:79]
	v_mfma_f32_32x32x16_bf16 v[16:31], v[194:197], v[198:201], v[16:31]
	v_mfma_f32_32x32x16_bf16 v[48:63], v[202:205], v[190:193], v[48:63]
	v_mfma_f32_32x32x16_bf16 v[0:15], v[202:205], v[198:201], v[0:15]
	ds_read_b128 v[186:189], v179 offset:64
	ds_read_b128 v[190:193], v184 offset:27712
	ds_read_b128 v[194:197], v179 offset:4672
	ds_read_b128 v[198:201], v184 offset:32320
	ds_read_b128 v[202:205], v179 offset:9280
	s_waitcnt lgkmcnt(5)
	v_mfma_f32_32x32x16_bf16 v[80:95], v[206:209], v[210:213], v[80:95]
	v_mfma_f32_32x32x16_bf16 v[32:47], v[206:209], v[218:221], v[32:47]
	v_mfma_f32_32x32x16_bf16 v[64:79], v[214:217], v[210:213], v[64:79]
	v_mfma_f32_32x32x16_bf16 v[16:31], v[214:217], v[218:221], v[16:31]
	v_mfma_f32_32x32x16_bf16 v[48:63], v[222:225], v[210:213], v[48:63]
	v_mfma_f32_32x32x16_bf16 v[0:15], v[222:225], v[218:221], v[0:15]
	ds_read_b128 v[206:209], v179 offset:96
	ds_read_b128 v[210:213], v184 offset:27744
	ds_read_b128 v[214:217], v179 offset:4704
	ds_read_b128 v[218:221], v184 offset:32352
	ds_read_b128 v[222:225], v179 offset:9312
	s_waitcnt lgkmcnt(0)
	s_waitcnt vmcnt(10)
	s_barrier
	v_mfma_f32_32x32x16_bf16 v[80:95], v[186:189], v[190:193], v[80:95]
	ds_write_b128 v97, v[138:141]
	ds_write_b128 v97, v[142:145] offset:4608
	v_mfma_f32_32x32x16_bf16 v[32:47], v[186:189], v[198:201], v[32:47]
	ds_write_b128 v97, v[146:149] offset:9216
	ds_write_b128 v97, v[150:153] offset:13824
	v_mfma_f32_32x32x16_bf16 v[64:79], v[194:197], v[190:193], v[64:79]
	ds_write_b128 v97, v[154:157] offset:18432
	ds_write_b128 v97, v[158:161] offset:23040
	v_mfma_f32_32x32x16_bf16 v[16:31], v[194:197], v[198:201], v[16:31]
	ds_write_b128 v97, v[162:165] offset:27648
	ds_write_b128 v97, v[166:169] offset:32256
	v_mfma_f32_32x32x16_bf16 v[48:63], v[202:205], v[190:193], v[48:63]
	ds_write_b128 v97, v[170:173] offset:36864
	ds_write_b128 v97, v[174:177] offset:41472
	v_mfma_f32_32x32x16_bf16 v[0:15], v[202:205], v[198:201], v[0:15]
	v_mfma_f32_32x32x16_bf16 v[80:95], v[206:209], v[210:213], v[80:95]
	v_mfma_f32_32x32x16_bf16 v[32:47], v[206:209], v[218:221], v[32:47]
	v_mfma_f32_32x32x16_bf16 v[64:79], v[214:217], v[210:213], v[64:79]
	v_mfma_f32_32x32x16_bf16 v[16:31], v[214:217], v[218:221], v[16:31]
	v_mfma_f32_32x32x16_bf16 v[48:63], v[222:225], v[210:213], v[48:63]
	v_mfma_f32_32x32x16_bf16 v[0:15], v[222:225], v[218:221], v[0:15]
	s_waitcnt lgkmcnt(0)
	s_barrier
	s_cbranch_vccnz .LBB0_1050
	s_waitcnt vmcnt(0)
	s_lshl_b64 s[8:9], s[0:1], 12
	s_lshl_b64 s[10:11], s[4:5], 2
	s_add_u32 s8, s8, s10
	s_addc_u32 s9, s9, s11
	s_add_i32 s1, s0, 0xfffff000
	s_lshr_b32 s1, s1, 10
	s_add_i32 s1, s1, 1
	s_cmp_gt_i32 s6, 21
	s_cselect_b32 s1, s1, 0
	s_add_i32 s2, s0, 0xfffff0bf
	s_lshr_b32 s2, s2, 10
	s_add_i32 s2, s2, 1
	s_cmp_gt_i32 s6, 20
	s_cselect_b32 s6, s2, 0
	s_and_b32 s0, s0, 0x3c0
	s_sub_i32 s0, 0x400, s0
	s_cmp_lg_u32 s1, s6
	s_cselect_b32 s2, s0, 0xc0
	v_readlane_b32 s4, v255, 24
	v_readlane_b32 s5, v255, 25
	v_and_b32_e32 v179, 0x5f, v244
	v_ashrrev_i32_e32 v98, 7, v244
	s_add_u32 s4, s4, s10
	s_addc_u32 s5, s5, s11
	s_mul_i32 s0, s1, 0x6000
	s_mul_i32 s7, s6, 0x6000
	s_add_u32 s0, s4, s0
	s_addc_u32 s1, s5, 0
	s_add_u32 s6, s4, s7
	s_addc_u32 s7, s5, 0
	v_mul_u32_u24_e32 v98, 0x60, v98
	v_lshrrev_b32_e32 v97, 3, v244
	v_and_or_b32 v216, v97, 4, v98
	v_lshlrev_b32_e32 v97, 2, v179
	v_lshl_or_b32 v99, v216, 10, v179
	v_lshlrev_b32_e32 v99, 2, v99
	v_sub_u32_e32 v217, s2, v216
	global_load_dword v214, v97, s[0:1]
	global_load_dword v215, v97, s[6:7]
	global_load_dword v218, v97, s[0:1] offset:128
	global_load_dword v219, v97, s[6:7] offset:128
	v_readlane_b32 s4, v255, 20
	v_readlane_b32 s5, v255, 21
	v_readlane_b32 s10, v255, 22
	v_readlane_b32 s11, v255, 23
	s_add_u32 s4, s4, s8
	s_addc_u32 s5, s5, s9
	s_add_u32 s10, s10, s8
	s_addc_u32 s11, s11, s9
	s_mov_b64 s[0:1], s[4:5]
	global_load_dword v100, v99, s[0:1]
	s_add_u32 s0, s0, 0x1000
	s_addc_u32 s1, s1, 0
	global_load_dword v101, v99, s[0:1]
	s_add_u32 s0, s0, 0x1000
	s_addc_u32 s1, s1, 0
	global_load_dword v102, v99, s[0:1]
	s_add_u32 s0, s0, 0x1000
	s_addc_u32 s1, s1, 0
	global_load_dword v103, v99, s[0:1]
	s_add_u32 s0, s0, 0x5000
	s_addc_u32 s1, s1, 0
	global_load_dword v104, v99, s[0:1]
	s_add_u32 s0, s0, 0x1000
	s_addc_u32 s1, s1, 0
	global_load_dword v105, v99, s[0:1]
	s_add_u32 s0, s0, 0x1000
	s_addc_u32 s1, s1, 0
	global_load_dword v106, v99, s[0:1]
	s_add_u32 s0, s0, 0x1000
	s_addc_u32 s1, s1, 0
	global_load_dword v107, v99, s[0:1]
	s_add_u32 s0, s0, 0x5000
	s_addc_u32 s1, s1, 0
	global_load_dword v108, v99, s[0:1]
	s_add_u32 s0, s0, 0x1000
	s_addc_u32 s1, s1, 0
	global_load_dword v109, v99, s[0:1]
	s_add_u32 s0, s0, 0x1000
	s_addc_u32 s1, s1, 0
	global_load_dword v110, v99, s[0:1]
	s_add_u32 s0, s0, 0x1000
	s_addc_u32 s1, s1, 0
	global_load_dword v111, v99, s[0:1]
	s_add_u32 s0, s0, 0x5000
	s_addc_u32 s1, s1, 0
	global_load_dword v112, v99, s[0:1]
	s_add_u32 s0, s0, 0x1000
	s_addc_u32 s1, s1, 0
	global_load_dword v113, v99, s[0:1]
	s_add_u32 s0, s0, 0x1000
	s_addc_u32 s1, s1, 0
	global_load_dword v114, v99, s[0:1]
	s_add_u32 s0, s0, 0x1000
	s_addc_u32 s1, s1, 0
	global_load_dword v115, v99, s[0:1]
	s_add_u32 s0, s0, 0x5000
	s_addc_u32 s1, s1, 0
	global_load_dword v116, v99, s[0:1]
	s_add_u32 s0, s0, 0x1000
	s_addc_u32 s1, s1, 0
	global_load_dword v117, v99, s[0:1]
	s_add_u32 s0, s0, 0x1000
	s_addc_u32 s1, s1, 0
	global_load_dword v118, v99, s[0:1]
	s_add_u32 s0, s0, 0x1000
	s_addc_u32 s1, s1, 0
	global_load_dword v119, v99, s[0:1]
	s_add_u32 s0, s0, 0x5000
	s_addc_u32 s1, s1, 0
	global_load_dword v120, v99, s[0:1]
	s_add_u32 s0, s0, 0x1000
	s_addc_u32 s1, s1, 0
	global_load_dword v121, v99, s[0:1]
	s_add_u32 s0, s0, 0x1000
	s_addc_u32 s1, s1, 0
	global_load_dword v122, v99, s[0:1]
	s_add_u32 s0, s0, 0x1000
	s_addc_u32 s1, s1, 0
	global_load_dword v123, v99, s[0:1]
	s_add_u32 s0, s0, 0x5000
	s_addc_u32 s1, s1, 0
	global_load_dword v124, v99, s[0:1]
	s_add_u32 s0, s0, 0x1000
	s_addc_u32 s1, s1, 0
	global_load_dword v125, v99, s[0:1]
	s_add_u32 s0, s0, 0x1000
	s_addc_u32 s1, s1, 0
	global_load_dword v126, v99, s[0:1]
	s_add_u32 s0, s0, 0x1000
	s_addc_u32 s1, s1, 0
	global_load_dword v127, v99, s[0:1]
	s_add_u32 s0, s0, 0x5000
	s_addc_u32 s1, s1, 0
	global_load_dword v128, v99, s[0:1]
	s_add_u32 s0, s0, 0x1000
	s_addc_u32 s1, s1, 0
	global_load_dword v129, v99, s[0:1]
	s_add_u32 s0, s0, 0x1000
	s_addc_u32 s1, s1, 0
	global_load_dword v130, v99, s[0:1]
	s_add_u32 s0, s0, 0x1000
	s_addc_u32 s1, s1, 0
	global_load_dword v131, v99, s[0:1]
	s_add_u32 s0, s0, 0x5000
	s_addc_u32 s1, s1, 0
	global_load_dword v132, v99, s[0:1]
	s_add_u32 s0, s0, 0x1000
	s_addc_u32 s1, s1, 0
	global_load_dword v133, v99, s[0:1]
	s_add_u32 s0, s0, 0x1000
	s_addc_u32 s1, s1, 0
	global_load_dword v134, v99, s[0:1]
	s_add_u32 s0, s0, 0x1000
	s_addc_u32 s1, s1, 0
	global_load_dword v135, v99, s[0:1]
	s_add_u32 s0, s0, 0x5000
	s_addc_u32 s1, s1, 0
	global_load_dword v136, v99, s[0:1]
	s_add_u32 s0, s0, 0x1000
	s_addc_u32 s1, s1, 0
	global_load_dword v137, v99, s[0:1]
	s_add_u32 s0, s0, 0x1000
	s_addc_u32 s1, s1, 0
	global_load_dword v138, v99, s[0:1]
	s_add_u32 s0, s0, 0x1000
	s_addc_u32 s1, s1, 0
	global_load_dword v139, v99, s[0:1]
	s_add_u32 s0, s0, 0x5000
	s_addc_u32 s1, s1, 0
	global_load_dword v140, v99, s[0:1]
	s_add_u32 s0, s0, 0x1000
	s_addc_u32 s1, s1, 0
	global_load_dword v141, v99, s[0:1]
	s_add_u32 s0, s0, 0x1000
	s_addc_u32 s1, s1, 0
	global_load_dword v142, v99, s[0:1]
	s_add_u32 s0, s0, 0x1000
	s_addc_u32 s1, s1, 0
	global_load_dword v143, v99, s[0:1]
	s_add_u32 s0, s0, 0x5000
	s_addc_u32 s1, s1, 0
	global_load_dword v144, v99, s[0:1]
	s_add_u32 s0, s0, 0x1000
	s_addc_u32 s1, s1, 0
	global_load_dword v145, v99, s[0:1]
	s_add_u32 s0, s0, 0x1000
	s_addc_u32 s1, s1, 0
	global_load_dword v146, v99, s[0:1]
	s_add_u32 s0, s0, 0x1000
	s_addc_u32 s1, s1, 0
	global_load_dword v147, v99, s[0:1]
	s_waitcnt vmcnt(0)
	v_cmp_lt_i32_e32 vcc, 0, v217
	v_mul_f32_e32 v100, 0x3fd744fd, v100
	s_nop 0
	v_cndmask_b32_e32 v97, v215, v214, vcc
	v_fmac_f32_e32 v100, v80, v97
	v_cmp_lt_i32_e32 vcc, 1, v217
	v_mul_f32_e32 v101, 0x3fd744fd, v101
	s_nop 0
	v_cndmask_b32_e32 v97, v215, v214, vcc
	v_fmac_f32_e32 v101, v81, v97
	v_cmp_lt_i32_e32 vcc, 2, v217
	v_mul_f32_e32 v102, 0x3fd744fd, v102
	s_nop 0
	v_cndmask_b32_e32 v97, v215, v214, vcc
	v_fmac_f32_e32 v102, v82, v97
	v_cmp_lt_i32_e32 vcc, 3, v217
	v_mul_f32_e32 v103, 0x3fd744fd, v103
	s_nop 0
	v_cndmask_b32_e32 v97, v215, v214, vcc
	v_fmac_f32_e32 v103, v83, v97
	v_cmp_lt_i32_e32 vcc, 8, v217
	v_mul_f32_e32 v104, 0x3fd744fd, v104
	s_nop 0
	v_cndmask_b32_e32 v97, v215, v214, vcc
	v_fmac_f32_e32 v104, v84, v97
	v_cmp_lt_i32_e32 vcc, 9, v217
	v_mul_f32_e32 v105, 0x3fd744fd, v105
	s_nop 0
	v_cndmask_b32_e32 v97, v215, v214, vcc
	v_fmac_f32_e32 v105, v85, v97
	v_cmp_lt_i32_e32 vcc, 10, v217
	v_mul_f32_e32 v106, 0x3fd744fd, v106
	s_nop 0
	v_cndmask_b32_e32 v97, v215, v214, vcc
	v_fmac_f32_e32 v106, v86, v97
	v_cmp_lt_i32_e32 vcc, 11, v217
	v_mul_f32_e32 v107, 0x3fd744fd, v107
	s_nop 0
	v_cndmask_b32_e32 v97, v215, v214, vcc
	v_fmac_f32_e32 v107, v87, v97
	v_cmp_lt_i32_e32 vcc, 16, v217
	v_mul_f32_e32 v108, 0x3fd744fd, v108
	s_nop 0
	v_cndmask_b32_e32 v97, v215, v214, vcc
	v_fmac_f32_e32 v108, v88, v97
	v_cmp_lt_i32_e32 vcc, 17, v217
	v_mul_f32_e32 v109, 0x3fd744fd, v109
	s_nop 0
	v_cndmask_b32_e32 v97, v215, v214, vcc
	v_fmac_f32_e32 v109, v89, v97
	v_cmp_lt_i32_e32 vcc, 18, v217
	v_mul_f32_e32 v110, 0x3fd744fd, v110
	s_nop 0
	v_cndmask_b32_e32 v97, v215, v214, vcc
	v_fmac_f32_e32 v110, v90, v97
	v_cmp_lt_i32_e32 vcc, 19, v217
	v_mul_f32_e32 v111, 0x3fd744fd, v111
	s_nop 0
	v_cndmask_b32_e32 v97, v215, v214, vcc
	v_fmac_f32_e32 v111, v91, v97
	v_cmp_lt_i32_e32 vcc, 24, v217
	v_mul_f32_e32 v112, 0x3fd744fd, v112
	s_nop 0
	v_cndmask_b32_e32 v97, v215, v214, vcc
	v_fmac_f32_e32 v112, v92, v97
	v_cmp_lt_i32_e32 vcc, 25, v217
	v_mul_f32_e32 v113, 0x3fd744fd, v113
	s_nop 0
	v_cndmask_b32_e32 v97, v215, v214, vcc
	v_fmac_f32_e32 v113, v93, v97
	v_cmp_lt_i32_e32 vcc, 26, v217
	v_mul_f32_e32 v114, 0x3fd744fd, v114
	s_nop 0
	v_cndmask_b32_e32 v97, v215, v214, vcc
	v_fmac_f32_e32 v114, v94, v97
	v_cmp_lt_i32_e32 vcc, 27, v217
	v_mul_f32_e32 v115, 0x3fd744fd, v115
	s_nop 0
	v_cndmask_b32_e32 v97, v215, v214, vcc
	v_fmac_f32_e32 v115, v95, v97
	v_cmp_lt_i32_e32 vcc, 32, v217
	v_mul_f32_e32 v116, 0x3fd744fd, v116
	s_nop 0
	v_cndmask_b32_e32 v97, v215, v214, vcc
	v_fmac_f32_e32 v116, v64, v97
	v_cmp_lt_i32_e32 vcc, 33, v217
	v_mul_f32_e32 v117, 0x3fd744fd, v117
	s_nop 0
	v_cndmask_b32_e32 v97, v215, v214, vcc
	v_fmac_f32_e32 v117, v65, v97
	v_cmp_lt_i32_e32 vcc, 34, v217
	v_mul_f32_e32 v118, 0x3fd744fd, v118
	s_nop 0
	v_cndmask_b32_e32 v97, v215, v214, vcc
	v_fmac_f32_e32 v118, v66, v97
	v_cmp_lt_i32_e32 vcc, 35, v217
	v_mul_f32_e32 v119, 0x3fd744fd, v119
	s_nop 0
	v_cndmask_b32_e32 v97, v215, v214, vcc
	v_fmac_f32_e32 v119, v67, v97
	v_cmp_lt_i32_e32 vcc, 40, v217
	v_mul_f32_e32 v120, 0x3fd744fd, v120
	s_nop 0
	v_cndmask_b32_e32 v97, v215, v214, vcc
	v_fmac_f32_e32 v120, v68, v97
	v_cmp_lt_i32_e32 vcc, 41, v217
	v_mul_f32_e32 v121, 0x3fd744fd, v121
	s_nop 0
	v_cndmask_b32_e32 v97, v215, v214, vcc
	v_fmac_f32_e32 v121, v69, v97
	v_cmp_lt_i32_e32 vcc, 42, v217
	v_mul_f32_e32 v122, 0x3fd744fd, v122
	s_nop 0
	v_cndmask_b32_e32 v97, v215, v214, vcc
	v_fmac_f32_e32 v122, v70, v97
	v_cmp_lt_i32_e32 vcc, 43, v217
	v_mul_f32_e32 v123, 0x3fd744fd, v123
	s_nop 0
	v_cndmask_b32_e32 v97, v215, v214, vcc
	v_fmac_f32_e32 v123, v71, v97
	v_cmp_lt_i32_e32 vcc, 48, v217
	v_mul_f32_e32 v124, 0x3fd744fd, v124
	s_nop 0
	v_cndmask_b32_e32 v97, v215, v214, vcc
	v_fmac_f32_e32 v124, v72, v97
	v_cmp_lt_i32_e32 vcc, 49, v217
	v_mul_f32_e32 v125, 0x3fd744fd, v125
	s_nop 0
	v_cndmask_b32_e32 v97, v215, v214, vcc
	v_fmac_f32_e32 v125, v73, v97
	v_cmp_lt_i32_e32 vcc, 50, v217
	v_mul_f32_e32 v126, 0x3fd744fd, v126
	s_nop 0
	v_cndmask_b32_e32 v97, v215, v214, vcc
	v_fmac_f32_e32 v126, v74, v97
	v_cmp_lt_i32_e32 vcc, 51, v217
	v_mul_f32_e32 v127, 0x3fd744fd, v127
	s_nop 0
	v_cndmask_b32_e32 v97, v215, v214, vcc
	v_fmac_f32_e32 v127, v75, v97
	v_cmp_lt_i32_e32 vcc, 56, v217
	v_mul_f32_e32 v128, 0x3fd744fd, v128
	s_nop 0
	v_cndmask_b32_e32 v97, v215, v214, vcc
	v_fmac_f32_e32 v128, v76, v97
	v_cmp_lt_i32_e32 vcc, 57, v217
	v_mul_f32_e32 v129, 0x3fd744fd, v129
	s_nop 0
	v_cndmask_b32_e32 v97, v215, v214, vcc
	v_fmac_f32_e32 v129, v77, v97
	v_cmp_lt_i32_e32 vcc, 58, v217
	v_mul_f32_e32 v130, 0x3fd744fd, v130
	s_nop 0
	v_cndmask_b32_e32 v97, v215, v214, vcc
	v_fmac_f32_e32 v130, v78, v97
	v_cmp_lt_i32_e32 vcc, 59, v217
	v_mul_f32_e32 v131, 0x3fd744fd, v131
	s_nop 0
	v_cndmask_b32_e32 v97, v215, v214, vcc
	v_fmac_f32_e32 v131, v79, v97
	v_cmp_lt_i32_e32 vcc, 64, v217
	v_mul_f32_e32 v132, 0x3fd744fd, v132
	s_nop 0
	v_cndmask_b32_e32 v97, v215, v214, vcc
	v_fmac_f32_e32 v132, v48, v97
	v_cmp_lt_i32_e32 vcc, 0x41, v217
	v_mul_f32_e32 v133, 0x3fd744fd, v133
	s_nop 0
	v_cndmask_b32_e32 v97, v215, v214, vcc
	v_fmac_f32_e32 v133, v49, v97
	v_cmp_lt_i32_e32 vcc, 0x42, v217
	v_mul_f32_e32 v134, 0x3fd744fd, v134
	s_nop 0
	v_cndmask_b32_e32 v97, v215, v214, vcc
	v_fmac_f32_e32 v134, v50, v97
	v_cmp_lt_i32_e32 vcc, 0x43, v217
	v_mul_f32_e32 v135, 0x3fd744fd, v135
	s_nop 0
	v_cndmask_b32_e32 v97, v215, v214, vcc
	v_fmac_f32_e32 v135, v51, v97
	v_cmp_lt_i32_e32 vcc, 0x48, v217
	v_mul_f32_e32 v136, 0x3fd744fd, v136
	s_nop 0
	v_cndmask_b32_e32 v97, v215, v214, vcc
	v_fmac_f32_e32 v136, v52, v97
	v_cmp_lt_i32_e32 vcc, 0x49, v217
	v_mul_f32_e32 v137, 0x3fd744fd, v137
	s_nop 0
	v_cndmask_b32_e32 v97, v215, v214, vcc
	v_fmac_f32_e32 v137, v53, v97
	v_cmp_lt_i32_e32 vcc, 0x4a, v217
	v_mul_f32_e32 v138, 0x3fd744fd, v138
	s_nop 0
	v_cndmask_b32_e32 v97, v215, v214, vcc
	v_fmac_f32_e32 v138, v54, v97
	v_cmp_lt_i32_e32 vcc, 0x4b, v217
	v_mul_f32_e32 v139, 0x3fd744fd, v139
	s_nop 0
	v_cndmask_b32_e32 v97, v215, v214, vcc
	v_fmac_f32_e32 v139, v55, v97
	v_cmp_lt_i32_e32 vcc, 0x50, v217
	v_mul_f32_e32 v140, 0x3fd744fd, v140
	s_nop 0
	v_cndmask_b32_e32 v97, v215, v214, vcc
	v_fmac_f32_e32 v140, v56, v97
	v_cmp_lt_i32_e32 vcc, 0x51, v217
	v_mul_f32_e32 v141, 0x3fd744fd, v141
	s_nop 0
	v_cndmask_b32_e32 v97, v215, v214, vcc
	v_fmac_f32_e32 v141, v57, v97
	v_cmp_lt_i32_e32 vcc, 0x52, v217
	v_mul_f32_e32 v142, 0x3fd744fd, v142
	s_nop 0
	v_cndmask_b32_e32 v97, v215, v214, vcc
	v_fmac_f32_e32 v142, v58, v97
	v_cmp_lt_i32_e32 vcc, 0x53, v217
	v_mul_f32_e32 v143, 0x3fd744fd, v143
	s_nop 0
	v_cndmask_b32_e32 v97, v215, v214, vcc
	v_fmac_f32_e32 v143, v59, v97
	v_cmp_lt_i32_e32 vcc, 0x58, v217
	v_mul_f32_e32 v144, 0x3fd744fd, v144
	s_nop 0
	v_cndmask_b32_e32 v97, v215, v214, vcc
	v_fmac_f32_e32 v144, v60, v97
	v_cmp_lt_i32_e32 vcc, 0x59, v217
	v_mul_f32_e32 v145, 0x3fd744fd, v145
	s_nop 0
	v_cndmask_b32_e32 v97, v215, v214, vcc
	v_fmac_f32_e32 v145, v61, v97
	v_cmp_lt_i32_e32 vcc, 0x5a, v217
	v_mul_f32_e32 v146, 0x3fd744fd, v146
	s_nop 0
	v_cndmask_b32_e32 v97, v215, v214, vcc
	v_fmac_f32_e32 v146, v62, v97
	v_cmp_lt_i32_e32 vcc, 0x5b, v217
	v_mul_f32_e32 v147, 0x3fd744fd, v147
	s_nop 0
	v_cndmask_b32_e32 v97, v215, v214, vcc
	v_fmac_f32_e32 v147, v63, v97
	s_mov_b64 s[0:1], s[10:11]
	global_store_dword v99, v100, s[0:1]
	s_add_u32 s0, s0, 0x1000
	s_addc_u32 s1, s1, 0
	global_store_dword v99, v101, s[0:1]
	s_add_u32 s0, s0, 0x1000
	s_addc_u32 s1, s1, 0
	global_store_dword v99, v102, s[0:1]
	s_add_u32 s0, s0, 0x1000
	s_addc_u32 s1, s1, 0
	global_store_dword v99, v103, s[0:1]
	s_add_u32 s0, s0, 0x5000
	s_addc_u32 s1, s1, 0
	global_store_dword v99, v104, s[0:1]
	s_add_u32 s0, s0, 0x1000
	s_addc_u32 s1, s1, 0
	global_store_dword v99, v105, s[0:1]
	s_add_u32 s0, s0, 0x1000
	s_addc_u32 s1, s1, 0
	global_store_dword v99, v106, s[0:1]
	s_add_u32 s0, s0, 0x1000
	s_addc_u32 s1, s1, 0
	global_store_dword v99, v107, s[0:1]
	s_add_u32 s0, s0, 0x5000
	s_addc_u32 s1, s1, 0
	global_store_dword v99, v108, s[0:1]
	s_add_u32 s0, s0, 0x1000
	s_addc_u32 s1, s1, 0
	global_store_dword v99, v109, s[0:1]
	s_add_u32 s0, s0, 0x1000
	s_addc_u32 s1, s1, 0
	global_store_dword v99, v110, s[0:1]
	s_add_u32 s0, s0, 0x1000
	s_addc_u32 s1, s1, 0
	global_store_dword v99, v111, s[0:1]
	s_add_u32 s0, s0, 0x5000
	s_addc_u32 s1, s1, 0
	global_store_dword v99, v112, s[0:1]
	s_add_u32 s0, s0, 0x1000
	s_addc_u32 s1, s1, 0
	global_store_dword v99, v113, s[0:1]
	s_add_u32 s0, s0, 0x1000
	s_addc_u32 s1, s1, 0
	global_store_dword v99, v114, s[0:1]
	s_add_u32 s0, s0, 0x1000
	s_addc_u32 s1, s1, 0
	global_store_dword v99, v115, s[0:1]
	s_add_u32 s0, s0, 0x5000
	s_addc_u32 s1, s1, 0
	global_store_dword v99, v116, s[0:1]
	s_add_u32 s0, s0, 0x1000
	s_addc_u32 s1, s1, 0
	global_store_dword v99, v117, s[0:1]
	s_add_u32 s0, s0, 0x1000
	s_addc_u32 s1, s1, 0
	global_store_dword v99, v118, s[0:1]
	s_add_u32 s0, s0, 0x1000
	s_addc_u32 s1, s1, 0
	global_store_dword v99, v119, s[0:1]
	s_add_u32 s0, s0, 0x5000
	s_addc_u32 s1, s1, 0
	global_store_dword v99, v120, s[0:1]
	s_add_u32 s0, s0, 0x1000
	s_addc_u32 s1, s1, 0
	global_store_dword v99, v121, s[0:1]
	s_add_u32 s0, s0, 0x1000
	s_addc_u32 s1, s1, 0
	global_store_dword v99, v122, s[0:1]
	s_add_u32 s0, s0, 0x1000
	s_addc_u32 s1, s1, 0
	global_store_dword v99, v123, s[0:1]
	s_add_u32 s0, s0, 0x5000
	s_addc_u32 s1, s1, 0
	global_store_dword v99, v124, s[0:1]
	s_add_u32 s0, s0, 0x1000
	s_addc_u32 s1, s1, 0
	global_store_dword v99, v125, s[0:1]
	s_add_u32 s0, s0, 0x1000
	s_addc_u32 s1, s1, 0
	global_store_dword v99, v126, s[0:1]
	s_add_u32 s0, s0, 0x1000
	s_addc_u32 s1, s1, 0
	global_store_dword v99, v127, s[0:1]
	s_add_u32 s0, s0, 0x5000
	s_addc_u32 s1, s1, 0
	global_store_dword v99, v128, s[0:1]
	s_add_u32 s0, s0, 0x1000
	s_addc_u32 s1, s1, 0
	global_store_dword v99, v129, s[0:1]
	s_add_u32 s0, s0, 0x1000
	s_addc_u32 s1, s1, 0
	global_store_dword v99, v130, s[0:1]
	s_add_u32 s0, s0, 0x1000
	s_addc_u32 s1, s1, 0
	global_store_dword v99, v131, s[0:1]
	s_add_u32 s0, s0, 0x5000
	s_addc_u32 s1, s1, 0
	global_store_dword v99, v132, s[0:1]
	s_add_u32 s0, s0, 0x1000
	s_addc_u32 s1, s1, 0
	global_store_dword v99, v133, s[0:1]
	s_add_u32 s0, s0, 0x1000
	s_addc_u32 s1, s1, 0
	global_store_dword v99, v134, s[0:1]
	s_add_u32 s0, s0, 0x1000
	s_addc_u32 s1, s1, 0
	global_store_dword v99, v135, s[0:1]
	s_add_u32 s0, s0, 0x5000
	s_addc_u32 s1, s1, 0
	global_store_dword v99, v136, s[0:1]
	s_add_u32 s0, s0, 0x1000
	s_addc_u32 s1, s1, 0
	global_store_dword v99, v137, s[0:1]
	s_add_u32 s0, s0, 0x1000
	s_addc_u32 s1, s1, 0
	global_store_dword v99, v138, s[0:1]
	s_add_u32 s0, s0, 0x1000
	s_addc_u32 s1, s1, 0
	global_store_dword v99, v139, s[0:1]
	s_add_u32 s0, s0, 0x5000
	s_addc_u32 s1, s1, 0
	global_store_dword v99, v140, s[0:1]
	s_add_u32 s0, s0, 0x1000
	s_addc_u32 s1, s1, 0
	global_store_dword v99, v141, s[0:1]
	s_add_u32 s0, s0, 0x1000
	s_addc_u32 s1, s1, 0
	global_store_dword v99, v142, s[0:1]
	s_add_u32 s0, s0, 0x1000
	s_addc_u32 s1, s1, 0
	global_store_dword v99, v143, s[0:1]
	s_add_u32 s0, s0, 0x5000
	s_addc_u32 s1, s1, 0
	global_store_dword v99, v144, s[0:1]
	s_add_u32 s0, s0, 0x1000
	s_addc_u32 s1, s1, 0
	global_store_dword v99, v145, s[0:1]
	s_add_u32 s0, s0, 0x1000
	s_addc_u32 s1, s1, 0
	global_store_dword v99, v146, s[0:1]
	s_add_u32 s0, s0, 0x1000
	s_addc_u32 s1, s1, 0
	global_store_dword v99, v147, s[0:1]
	s_mov_b64 s[0:1], s[4:5]
	global_load_dword v100, v99, s[0:1] offset:128
	s_add_u32 s0, s0, 0x1000
	s_addc_u32 s1, s1, 0
	global_load_dword v101, v99, s[0:1] offset:128
	s_add_u32 s0, s0, 0x1000
	s_addc_u32 s1, s1, 0
	global_load_dword v102, v99, s[0:1] offset:128
	s_add_u32 s0, s0, 0x1000
	s_addc_u32 s1, s1, 0
	global_load_dword v103, v99, s[0:1] offset:128
	s_add_u32 s0, s0, 0x5000
	s_addc_u32 s1, s1, 0
	global_load_dword v104, v99, s[0:1] offset:128
	s_add_u32 s0, s0, 0x1000
	s_addc_u32 s1, s1, 0
	global_load_dword v105, v99, s[0:1] offset:128
	s_add_u32 s0, s0, 0x1000
	s_addc_u32 s1, s1, 0
	global_load_dword v106, v99, s[0:1] offset:128
	s_add_u32 s0, s0, 0x1000
	s_addc_u32 s1, s1, 0
	global_load_dword v107, v99, s[0:1] offset:128
	s_add_u32 s0, s0, 0x5000
	s_addc_u32 s1, s1, 0
	global_load_dword v108, v99, s[0:1] offset:128
	s_add_u32 s0, s0, 0x1000
	s_addc_u32 s1, s1, 0
	global_load_dword v109, v99, s[0:1] offset:128
	s_add_u32 s0, s0, 0x1000
	s_addc_u32 s1, s1, 0
	global_load_dword v110, v99, s[0:1] offset:128
	s_add_u32 s0, s0, 0x1000
	s_addc_u32 s1, s1, 0
	global_load_dword v111, v99, s[0:1] offset:128
	s_add_u32 s0, s0, 0x5000
	s_addc_u32 s1, s1, 0
	global_load_dword v112, v99, s[0:1] offset:128
	s_add_u32 s0, s0, 0x1000
	s_addc_u32 s1, s1, 0
	global_load_dword v113, v99, s[0:1] offset:128
	s_add_u32 s0, s0, 0x1000
	s_addc_u32 s1, s1, 0
	global_load_dword v114, v99, s[0:1] offset:128
	s_add_u32 s0, s0, 0x1000
	s_addc_u32 s1, s1, 0
	global_load_dword v115, v99, s[0:1] offset:128
	s_add_u32 s0, s0, 0x5000
	s_addc_u32 s1, s1, 0
	global_load_dword v116, v99, s[0:1] offset:128
	s_add_u32 s0, s0, 0x1000
	s_addc_u32 s1, s1, 0
	global_load_dword v117, v99, s[0:1] offset:128
	s_add_u32 s0, s0, 0x1000
	s_addc_u32 s1, s1, 0
	global_load_dword v118, v99, s[0:1] offset:128
	s_add_u32 s0, s0, 0x1000
	s_addc_u32 s1, s1, 0
	global_load_dword v119, v99, s[0:1] offset:128
	s_add_u32 s0, s0, 0x5000
	s_addc_u32 s1, s1, 0
	global_load_dword v120, v99, s[0:1] offset:128
	s_add_u32 s0, s0, 0x1000
	s_addc_u32 s1, s1, 0
	global_load_dword v121, v99, s[0:1] offset:128
	s_add_u32 s0, s0, 0x1000
	s_addc_u32 s1, s1, 0
	global_load_dword v122, v99, s[0:1] offset:128
	s_add_u32 s0, s0, 0x1000
	s_addc_u32 s1, s1, 0
	global_load_dword v123, v99, s[0:1] offset:128
	s_add_u32 s0, s0, 0x5000
	s_addc_u32 s1, s1, 0
	global_load_dword v124, v99, s[0:1] offset:128
	s_add_u32 s0, s0, 0x1000
	s_addc_u32 s1, s1, 0
	global_load_dword v125, v99, s[0:1] offset:128
	s_add_u32 s0, s0, 0x1000
	s_addc_u32 s1, s1, 0
	global_load_dword v126, v99, s[0:1] offset:128
	s_add_u32 s0, s0, 0x1000
	s_addc_u32 s1, s1, 0
	global_load_dword v127, v99, s[0:1] offset:128
	s_add_u32 s0, s0, 0x5000
	s_addc_u32 s1, s1, 0
	global_load_dword v128, v99, s[0:1] offset:128
	s_add_u32 s0, s0, 0x1000
	s_addc_u32 s1, s1, 0
	global_load_dword v129, v99, s[0:1] offset:128
	s_add_u32 s0, s0, 0x1000
	s_addc_u32 s1, s1, 0
	global_load_dword v130, v99, s[0:1] offset:128
	s_add_u32 s0, s0, 0x1000
	s_addc_u32 s1, s1, 0
	global_load_dword v131, v99, s[0:1] offset:128
	s_add_u32 s0, s0, 0x5000
	s_addc_u32 s1, s1, 0
	global_load_dword v132, v99, s[0:1] offset:128
	s_add_u32 s0, s0, 0x1000
	s_addc_u32 s1, s1, 0
	global_load_dword v133, v99, s[0:1] offset:128
	s_add_u32 s0, s0, 0x1000
	s_addc_u32 s1, s1, 0
	global_load_dword v134, v99, s[0:1] offset:128
	s_add_u32 s0, s0, 0x1000
	s_addc_u32 s1, s1, 0
	global_load_dword v135, v99, s[0:1] offset:128
	s_add_u32 s0, s0, 0x5000
	s_addc_u32 s1, s1, 0
	global_load_dword v136, v99, s[0:1] offset:128
	s_add_u32 s0, s0, 0x1000
	s_addc_u32 s1, s1, 0
	global_load_dword v137, v99, s[0:1] offset:128
	s_add_u32 s0, s0, 0x1000
	s_addc_u32 s1, s1, 0
	global_load_dword v138, v99, s[0:1] offset:128
	s_add_u32 s0, s0, 0x1000
	s_addc_u32 s1, s1, 0
	global_load_dword v139, v99, s[0:1] offset:128
	s_add_u32 s0, s0, 0x5000
	s_addc_u32 s1, s1, 0
	global_load_dword v140, v99, s[0:1] offset:128
	s_add_u32 s0, s0, 0x1000
	s_addc_u32 s1, s1, 0
	global_load_dword v141, v99, s[0:1] offset:128
	s_add_u32 s0, s0, 0x1000
	s_addc_u32 s1, s1, 0
	global_load_dword v142, v99, s[0:1] offset:128
	s_add_u32 s0, s0, 0x1000
	s_addc_u32 s1, s1, 0
	global_load_dword v143, v99, s[0:1] offset:128
	s_add_u32 s0, s0, 0x5000
	s_addc_u32 s1, s1, 0
	global_load_dword v144, v99, s[0:1] offset:128
	s_add_u32 s0, s0, 0x1000
	s_addc_u32 s1, s1, 0
	global_load_dword v145, v99, s[0:1] offset:128
	s_add_u32 s0, s0, 0x1000
	s_addc_u32 s1, s1, 0
	global_load_dword v146, v99, s[0:1] offset:128
	s_add_u32 s0, s0, 0x1000
	s_addc_u32 s1, s1, 0
	global_load_dword v147, v99, s[0:1] offset:128
	s_waitcnt vmcnt(0)
	v_cmp_lt_i32_e32 vcc, 0, v217
	v_mul_f32_e32 v100, 0x3fd744fd, v100
	s_nop 0
	v_cndmask_b32_e32 v97, v219, v218, vcc
	v_fmac_f32_e32 v100, v32, v97
	v_cmp_lt_i32_e32 vcc, 1, v217
	v_mul_f32_e32 v101, 0x3fd744fd, v101
	s_nop 0
	v_cndmask_b32_e32 v97, v219, v218, vcc
	v_fmac_f32_e32 v101, v33, v97
	v_cmp_lt_i32_e32 vcc, 2, v217
	v_mul_f32_e32 v102, 0x3fd744fd, v102
	s_nop 0
	v_cndmask_b32_e32 v97, v219, v218, vcc
	v_fmac_f32_e32 v102, v34, v97
	v_cmp_lt_i32_e32 vcc, 3, v217
	v_mul_f32_e32 v103, 0x3fd744fd, v103
	s_nop 0
	v_cndmask_b32_e32 v97, v219, v218, vcc
	v_fmac_f32_e32 v103, v35, v97
	v_cmp_lt_i32_e32 vcc, 8, v217
	v_mul_f32_e32 v104, 0x3fd744fd, v104
	s_nop 0
	v_cndmask_b32_e32 v97, v219, v218, vcc
	v_fmac_f32_e32 v104, v36, v97
	v_cmp_lt_i32_e32 vcc, 9, v217
	v_mul_f32_e32 v105, 0x3fd744fd, v105
	s_nop 0
	v_cndmask_b32_e32 v97, v219, v218, vcc
	v_fmac_f32_e32 v105, v37, v97
	v_cmp_lt_i32_e32 vcc, 10, v217
	v_mul_f32_e32 v106, 0x3fd744fd, v106
	s_nop 0
	v_cndmask_b32_e32 v97, v219, v218, vcc
	v_fmac_f32_e32 v106, v38, v97
	v_cmp_lt_i32_e32 vcc, 11, v217
	v_mul_f32_e32 v107, 0x3fd744fd, v107
	s_nop 0
	v_cndmask_b32_e32 v97, v219, v218, vcc
	v_fmac_f32_e32 v107, v39, v97
	v_cmp_lt_i32_e32 vcc, 16, v217
	v_mul_f32_e32 v108, 0x3fd744fd, v108
	s_nop 0
	v_cndmask_b32_e32 v97, v219, v218, vcc
	v_fmac_f32_e32 v108, v40, v97
	v_cmp_lt_i32_e32 vcc, 17, v217
	v_mul_f32_e32 v109, 0x3fd744fd, v109
	s_nop 0
	v_cndmask_b32_e32 v97, v219, v218, vcc
	v_fmac_f32_e32 v109, v41, v97
	v_cmp_lt_i32_e32 vcc, 18, v217
	v_mul_f32_e32 v110, 0x3fd744fd, v110
	s_nop 0
	v_cndmask_b32_e32 v97, v219, v218, vcc
	v_fmac_f32_e32 v110, v42, v97
	v_cmp_lt_i32_e32 vcc, 19, v217
	v_mul_f32_e32 v111, 0x3fd744fd, v111
	s_nop 0
	v_cndmask_b32_e32 v97, v219, v218, vcc
	v_fmac_f32_e32 v111, v43, v97
	v_cmp_lt_i32_e32 vcc, 24, v217
	v_mul_f32_e32 v112, 0x3fd744fd, v112
	s_nop 0
	v_cndmask_b32_e32 v97, v219, v218, vcc
	v_fmac_f32_e32 v112, v44, v97
	v_cmp_lt_i32_e32 vcc, 25, v217
	v_mul_f32_e32 v113, 0x3fd744fd, v113
	s_nop 0
	v_cndmask_b32_e32 v97, v219, v218, vcc
	v_fmac_f32_e32 v113, v45, v97
	v_cmp_lt_i32_e32 vcc, 26, v217
	v_mul_f32_e32 v114, 0x3fd744fd, v114
	s_nop 0
	v_cndmask_b32_e32 v97, v219, v218, vcc
	v_fmac_f32_e32 v114, v46, v97
	v_cmp_lt_i32_e32 vcc, 27, v217
	v_mul_f32_e32 v115, 0x3fd744fd, v115
	s_nop 0
	v_cndmask_b32_e32 v97, v219, v218, vcc
	v_fmac_f32_e32 v115, v47, v97
	v_cmp_lt_i32_e32 vcc, 32, v217
	v_mul_f32_e32 v116, 0x3fd744fd, v116
	s_nop 0
	v_cndmask_b32_e32 v97, v219, v218, vcc
	v_fmac_f32_e32 v116, v16, v97
	v_cmp_lt_i32_e32 vcc, 33, v217
	v_mul_f32_e32 v117, 0x3fd744fd, v117
	s_nop 0
	v_cndmask_b32_e32 v97, v219, v218, vcc
	v_fmac_f32_e32 v117, v17, v97
	v_cmp_lt_i32_e32 vcc, 34, v217
	v_mul_f32_e32 v118, 0x3fd744fd, v118
	s_nop 0
	v_cndmask_b32_e32 v97, v219, v218, vcc
	v_fmac_f32_e32 v118, v18, v97
	v_cmp_lt_i32_e32 vcc, 35, v217
	v_mul_f32_e32 v119, 0x3fd744fd, v119
	s_nop 0
	v_cndmask_b32_e32 v97, v219, v218, vcc
	v_fmac_f32_e32 v119, v19, v97
	v_cmp_lt_i32_e32 vcc, 40, v217
	v_mul_f32_e32 v120, 0x3fd744fd, v120
	s_nop 0
	v_cndmask_b32_e32 v97, v219, v218, vcc
	v_fmac_f32_e32 v120, v20, v97
	v_cmp_lt_i32_e32 vcc, 41, v217
	v_mul_f32_e32 v121, 0x3fd744fd, v121
	s_nop 0
	v_cndmask_b32_e32 v97, v219, v218, vcc
	v_fmac_f32_e32 v121, v21, v97
	v_cmp_lt_i32_e32 vcc, 42, v217
	v_mul_f32_e32 v122, 0x3fd744fd, v122
	s_nop 0
	v_cndmask_b32_e32 v97, v219, v218, vcc
	v_fmac_f32_e32 v122, v22, v97
	v_cmp_lt_i32_e32 vcc, 43, v217
	v_mul_f32_e32 v123, 0x3fd744fd, v123
	s_nop 0
	v_cndmask_b32_e32 v97, v219, v218, vcc
	v_fmac_f32_e32 v123, v23, v97
	v_cmp_lt_i32_e32 vcc, 48, v217
	v_mul_f32_e32 v124, 0x3fd744fd, v124
	s_nop 0
	v_cndmask_b32_e32 v97, v219, v218, vcc
	v_fmac_f32_e32 v124, v24, v97
	v_cmp_lt_i32_e32 vcc, 49, v217
	v_mul_f32_e32 v125, 0x3fd744fd, v125
	s_nop 0
	v_cndmask_b32_e32 v97, v219, v218, vcc
	v_fmac_f32_e32 v125, v25, v97
	v_cmp_lt_i32_e32 vcc, 50, v217
	v_mul_f32_e32 v126, 0x3fd744fd, v126
	s_nop 0
	v_cndmask_b32_e32 v97, v219, v218, vcc
	v_fmac_f32_e32 v126, v26, v97
	v_cmp_lt_i32_e32 vcc, 51, v217
	v_mul_f32_e32 v127, 0x3fd744fd, v127
	s_nop 0
	v_cndmask_b32_e32 v97, v219, v218, vcc
	v_fmac_f32_e32 v127, v27, v97
	v_cmp_lt_i32_e32 vcc, 56, v217
	v_mul_f32_e32 v128, 0x3fd744fd, v128
	s_nop 0
	v_cndmask_b32_e32 v97, v219, v218, vcc
	v_fmac_f32_e32 v128, v28, v97
	v_cmp_lt_i32_e32 vcc, 57, v217
	v_mul_f32_e32 v129, 0x3fd744fd, v129
	s_nop 0
	v_cndmask_b32_e32 v97, v219, v218, vcc
	v_fmac_f32_e32 v129, v29, v97
	v_cmp_lt_i32_e32 vcc, 58, v217
	v_mul_f32_e32 v130, 0x3fd744fd, v130
	s_nop 0
	v_cndmask_b32_e32 v97, v219, v218, vcc
	v_fmac_f32_e32 v130, v30, v97
	v_cmp_lt_i32_e32 vcc, 59, v217
	v_mul_f32_e32 v131, 0x3fd744fd, v131
	s_nop 0
	v_cndmask_b32_e32 v97, v219, v218, vcc
	v_fmac_f32_e32 v131, v31, v97
	v_cmp_lt_i32_e32 vcc, 64, v217
	v_mul_f32_e32 v132, 0x3fd744fd, v132
	s_nop 0
	v_cndmask_b32_e32 v97, v219, v218, vcc
	v_fmac_f32_e32 v132, v0, v97
	v_cmp_lt_i32_e32 vcc, 0x41, v217
	v_mul_f32_e32 v133, 0x3fd744fd, v133
	s_nop 0
	v_cndmask_b32_e32 v97, v219, v218, vcc
	v_fmac_f32_e32 v133, v1, v97
	v_cmp_lt_i32_e32 vcc, 0x42, v217
	v_mul_f32_e32 v134, 0x3fd744fd, v134
	s_nop 0
	v_cndmask_b32_e32 v97, v219, v218, vcc
	v_fmac_f32_e32 v134, v2, v97
	v_cmp_lt_i32_e32 vcc, 0x43, v217
	v_mul_f32_e32 v135, 0x3fd744fd, v135
	s_nop 0
	v_cndmask_b32_e32 v97, v219, v218, vcc
	v_fmac_f32_e32 v135, v3, v97
	v_cmp_lt_i32_e32 vcc, 0x48, v217
	v_mul_f32_e32 v136, 0x3fd744fd, v136
	s_nop 0
	v_cndmask_b32_e32 v97, v219, v218, vcc
	v_fmac_f32_e32 v136, v4, v97
	v_cmp_lt_i32_e32 vcc, 0x49, v217
	v_mul_f32_e32 v137, 0x3fd744fd, v137
	s_nop 0
	v_cndmask_b32_e32 v97, v219, v218, vcc
	v_fmac_f32_e32 v137, v5, v97
	v_cmp_lt_i32_e32 vcc, 0x4a, v217
	v_mul_f32_e32 v138, 0x3fd744fd, v138
	s_nop 0
	v_cndmask_b32_e32 v97, v219, v218, vcc
	v_fmac_f32_e32 v138, v6, v97
	v_cmp_lt_i32_e32 vcc, 0x4b, v217
	v_mul_f32_e32 v139, 0x3fd744fd, v139
	s_nop 0
	v_cndmask_b32_e32 v97, v219, v218, vcc
	v_fmac_f32_e32 v139, v7, v97
	v_cmp_lt_i32_e32 vcc, 0x50, v217
	v_mul_f32_e32 v140, 0x3fd744fd, v140
	s_nop 0
	v_cndmask_b32_e32 v97, v219, v218, vcc
	v_fmac_f32_e32 v140, v8, v97
	v_cmp_lt_i32_e32 vcc, 0x51, v217
	v_mul_f32_e32 v141, 0x3fd744fd, v141
	s_nop 0
	v_cndmask_b32_e32 v97, v219, v218, vcc
	v_fmac_f32_e32 v141, v9, v97
	v_cmp_lt_i32_e32 vcc, 0x52, v217
	v_mul_f32_e32 v142, 0x3fd744fd, v142
	s_nop 0
	v_cndmask_b32_e32 v97, v219, v218, vcc
	v_fmac_f32_e32 v142, v10, v97
	v_cmp_lt_i32_e32 vcc, 0x53, v217
	v_mul_f32_e32 v143, 0x3fd744fd, v143
	s_nop 0
	v_cndmask_b32_e32 v97, v219, v218, vcc
	v_fmac_f32_e32 v143, v11, v97
	v_cmp_lt_i32_e32 vcc, 0x58, v217
	v_mul_f32_e32 v144, 0x3fd744fd, v144
	s_nop 0
	v_cndmask_b32_e32 v97, v219, v218, vcc
	v_fmac_f32_e32 v144, v12, v97
	v_cmp_lt_i32_e32 vcc, 0x59, v217
	v_mul_f32_e32 v145, 0x3fd744fd, v145
	s_nop 0
	v_cndmask_b32_e32 v97, v219, v218, vcc
	v_fmac_f32_e32 v145, v13, v97
	v_cmp_lt_i32_e32 vcc, 0x5a, v217
	v_mul_f32_e32 v146, 0x3fd744fd, v146
	s_nop 0
	v_cndmask_b32_e32 v97, v219, v218, vcc
	v_fmac_f32_e32 v146, v14, v97
	v_cmp_lt_i32_e32 vcc, 0x5b, v217
	v_mul_f32_e32 v147, 0x3fd744fd, v147
	s_nop 0
	v_cndmask_b32_e32 v97, v219, v218, vcc
	v_fmac_f32_e32 v147, v15, v97
	s_mov_b64 s[0:1], s[10:11]
	global_store_dword v99, v100, s[0:1] offset:128
	s_add_u32 s0, s0, 0x1000
	s_addc_u32 s1, s1, 0
	global_store_dword v99, v101, s[0:1] offset:128
	s_add_u32 s0, s0, 0x1000
	s_addc_u32 s1, s1, 0
	global_store_dword v99, v102, s[0:1] offset:128
	s_add_u32 s0, s0, 0x1000
	s_addc_u32 s1, s1, 0
	global_store_dword v99, v103, s[0:1] offset:128
	s_add_u32 s0, s0, 0x5000
	s_addc_u32 s1, s1, 0
	global_store_dword v99, v104, s[0:1] offset:128
	s_add_u32 s0, s0, 0x1000
	s_addc_u32 s1, s1, 0
	global_store_dword v99, v105, s[0:1] offset:128
	s_add_u32 s0, s0, 0x1000
	s_addc_u32 s1, s1, 0
	global_store_dword v99, v106, s[0:1] offset:128
	s_add_u32 s0, s0, 0x1000
	s_addc_u32 s1, s1, 0
	global_store_dword v99, v107, s[0:1] offset:128
	s_add_u32 s0, s0, 0x5000
	s_addc_u32 s1, s1, 0
	global_store_dword v99, v108, s[0:1] offset:128
	s_add_u32 s0, s0, 0x1000
	s_addc_u32 s1, s1, 0
	global_store_dword v99, v109, s[0:1] offset:128
	s_add_u32 s0, s0, 0x1000
	s_addc_u32 s1, s1, 0
	global_store_dword v99, v110, s[0:1] offset:128
	s_add_u32 s0, s0, 0x1000
	s_addc_u32 s1, s1, 0
	global_store_dword v99, v111, s[0:1] offset:128
	s_add_u32 s0, s0, 0x5000
	s_addc_u32 s1, s1, 0
	global_store_dword v99, v112, s[0:1] offset:128
	s_add_u32 s0, s0, 0x1000
	s_addc_u32 s1, s1, 0
	global_store_dword v99, v113, s[0:1] offset:128
	s_add_u32 s0, s0, 0x1000
	s_addc_u32 s1, s1, 0
	global_store_dword v99, v114, s[0:1] offset:128
	s_add_u32 s0, s0, 0x1000
	s_addc_u32 s1, s1, 0
	global_store_dword v99, v115, s[0:1] offset:128
	s_add_u32 s0, s0, 0x5000
	s_addc_u32 s1, s1, 0
	global_store_dword v99, v116, s[0:1] offset:128
	s_add_u32 s0, s0, 0x1000
	s_addc_u32 s1, s1, 0
	global_store_dword v99, v117, s[0:1] offset:128
	s_add_u32 s0, s0, 0x1000
	s_addc_u32 s1, s1, 0
	global_store_dword v99, v118, s[0:1] offset:128
	s_add_u32 s0, s0, 0x1000
	s_addc_u32 s1, s1, 0
	global_store_dword v99, v119, s[0:1] offset:128
	s_add_u32 s0, s0, 0x5000
	s_addc_u32 s1, s1, 0
	global_store_dword v99, v120, s[0:1] offset:128
	s_add_u32 s0, s0, 0x1000
	s_addc_u32 s1, s1, 0
	global_store_dword v99, v121, s[0:1] offset:128
	s_add_u32 s0, s0, 0x1000
	s_addc_u32 s1, s1, 0
	global_store_dword v99, v122, s[0:1] offset:128
	s_add_u32 s0, s0, 0x1000
	s_addc_u32 s1, s1, 0
	global_store_dword v99, v123, s[0:1] offset:128
	s_add_u32 s0, s0, 0x5000
	s_addc_u32 s1, s1, 0
	global_store_dword v99, v124, s[0:1] offset:128
	s_add_u32 s0, s0, 0x1000
	s_addc_u32 s1, s1, 0
	global_store_dword v99, v125, s[0:1] offset:128
	s_add_u32 s0, s0, 0x1000
	s_addc_u32 s1, s1, 0
	global_store_dword v99, v126, s[0:1] offset:128
	s_add_u32 s0, s0, 0x1000
	s_addc_u32 s1, s1, 0
	global_store_dword v99, v127, s[0:1] offset:128
	s_add_u32 s0, s0, 0x5000
	s_addc_u32 s1, s1, 0
	global_store_dword v99, v128, s[0:1] offset:128
	s_add_u32 s0, s0, 0x1000
	s_addc_u32 s1, s1, 0
	global_store_dword v99, v129, s[0:1] offset:128
	s_add_u32 s0, s0, 0x1000
	s_addc_u32 s1, s1, 0
	global_store_dword v99, v130, s[0:1] offset:128
	s_add_u32 s0, s0, 0x1000
	s_addc_u32 s1, s1, 0
	global_store_dword v99, v131, s[0:1] offset:128
	s_add_u32 s0, s0, 0x5000
	s_addc_u32 s1, s1, 0
	global_store_dword v99, v132, s[0:1] offset:128
	s_add_u32 s0, s0, 0x1000
	s_addc_u32 s1, s1, 0
	global_store_dword v99, v133, s[0:1] offset:128
	s_add_u32 s0, s0, 0x1000
	s_addc_u32 s1, s1, 0
	global_store_dword v99, v134, s[0:1] offset:128
	s_add_u32 s0, s0, 0x1000
	s_addc_u32 s1, s1, 0
	global_store_dword v99, v135, s[0:1] offset:128
	s_add_u32 s0, s0, 0x5000
	s_addc_u32 s1, s1, 0
	global_store_dword v99, v136, s[0:1] offset:128
	s_add_u32 s0, s0, 0x1000
	s_addc_u32 s1, s1, 0
	global_store_dword v99, v137, s[0:1] offset:128
	s_add_u32 s0, s0, 0x1000
	s_addc_u32 s1, s1, 0
	global_store_dword v99, v138, s[0:1] offset:128
	s_add_u32 s0, s0, 0x1000
	s_addc_u32 s1, s1, 0
	global_store_dword v99, v139, s[0:1] offset:128
	s_add_u32 s0, s0, 0x5000
	s_addc_u32 s1, s1, 0
	global_store_dword v99, v140, s[0:1] offset:128
	s_add_u32 s0, s0, 0x1000
	s_addc_u32 s1, s1, 0
	global_store_dword v99, v141, s[0:1] offset:128
	s_add_u32 s0, s0, 0x1000
	s_addc_u32 s1, s1, 0
	global_store_dword v99, v142, s[0:1] offset:128
	s_add_u32 s0, s0, 0x1000
	s_addc_u32 s1, s1, 0
	global_store_dword v99, v143, s[0:1] offset:128
	s_add_u32 s0, s0, 0x5000
	s_addc_u32 s1, s1, 0
	global_store_dword v99, v144, s[0:1] offset:128
	s_add_u32 s0, s0, 0x1000
	s_addc_u32 s1, s1, 0
	global_store_dword v99, v145, s[0:1] offset:128
	s_add_u32 s0, s0, 0x1000
	s_addc_u32 s1, s1, 0
	global_store_dword v99, v146, s[0:1] offset:128
	s_add_u32 s0, s0, 0x1000
	s_addc_u32 s1, s1, 0
	global_store_dword v99, v147, s[0:1] offset:128
	s_mov_b64 s[34:35], 0x84000
	s_mov_b64 s[36:37], 0xb0000
	s_movk_i32 s45, 0x60
	s_mov_b64 s[72:73], 0x2c000
	v_readlane_b32 s0, v255, 9
	s_add_i32 s33, s33, s0
	s_cmpk_lt_i32 s33, 0x200
	s_mov_b64 s[94:95], 0x80
	s_mov_b64 s[88:89], 0x58000
	s_movk_i32 s85, 0x90
	s_cbranch_scc1 .LBB0_1049
	v_readlane_b32 s86, v255, 3
	v_readlane_b32 s90, v255, 5
	v_readlane_b32 s62, v255, 44
	v_readlane_b32 s84, v255, 2
	v_readlane_b32 s87, v255, 4
	v_readlane_b32 s91, v255, 6
	s_mov_b64 s[92:93], 0x30000
	s_mov_b64 s[96:97], 0x10080
	s_mov_b64 s[64:65], 0x20080
	s_mov_b64 s[66:67], 0x30080
	s_mov_b32 s68, 0xfffffc0
	s_mov_b64 s[76:77], 0x10180
	s_mov_b64 s[70:71], 0x30180
	s_mov_b32 s69, 0xbfb8aa3b
	s_movk_i32 s60, 0xc4
	s_movk_i32 s56, 0xcc
	s_movk_i32 s57, 0xd4
	s_movk_i32 s58, 0xdc
	s_movk_i32 s59, 0xe4
	s_mov_b64 s[82:83], 0x4000
	s_mov_b64 s[78:79], 0x8000
	s_mov_b64 s[74:75], 0x8180
	s_movk_i32 s61, 0xfff
	s_mov_b32 s54, 0x800000
	s_movk_i32 s55, 0x2fff
	v_readlane_b32 s46, v255, 8
	s_mov_b64 s[50:51], 0x50000
	v_readlane_b32 s47, v255, 14
	v_readlane_b32 s63, v255, 45
	v_mov_b32_e32 v238, v245
	v_mov_b32_e32 v242, 0x2000
	v_mov_b32_e32 v243, 0x7f800000
	v_mov_b32_e32 v245, 0x7fc00000
	v_mov_b32_e32 v246, 0xff800000
